# mixer_b gate/output tile staged through LDS (coalesced), mixer_a reworked (8 consecutive tokens per lane, shared c*x products), mixer_c LN+swish tail as compact 2-row loop
# speedup vs baseline: 1.0228x; 1.0041x over previous
.LBB0_471:
	s_ashr_i32 s87, s86, 31
	v_mov_b32_e32 v176, v192
	s_cmpk_gt_i32 s18, 0xff
	s_cbranch_scc0 .LBB0_483
	s_cmpk_gt_u32 s18, 0x1ff
	s_cbranch_scc0 .LBB0_484
	s_cmpk_gt_u32 s18, 0x27f
	s_mov_b64 s[2:3], -1
	s_cbranch_scc0 .LBB0_477
	v_writelane_b32 v255, s8, 40
	v_writelane_b32 v255, s9, 41
	v_writelane_b32 v255, s10, 42
	v_writelane_b32 v255, s11, 43
	s_lshl_b32 s0, s18, 7
	s_add_i32 s0, s0, 0xfffec000
	s_and_b32 s2, s0, 0xfff
	s_mul_i32 s5, s0, 0x1800
	s_add_u32 s10, s66, s5
	s_addc_u32 s11, s67, 0
	s_sub_u32 s8, s10, 0x3000
	s_subb_u32 s9, s11, 0
	s_add_u32 s10, s10, 0x1000
	s_addc_u32 s11, s11, 0
	v_lshrrev_b32_e32 v25, 5, v176
	v_and_b32_e32 v26, 31, v176
	v_mul_u32_u24_e32 v24, 0xc000, v25
	v_lshl_add_u32 v24, v26, 4, v24
	v_lshlrev_b32_e32 v27, 5, v26
	global_load_dwordx4 v[0:3], v27, s[38:39]
	global_load_dwordx4 v[4:7], v27, s[38:39] offset:16
	global_load_dwordx4 v[8:11], v27, s[38:39] offset:1024
	global_load_dwordx4 v[12:15], v27, s[38:39] offset:1040
	global_load_dwordx4 v[16:19], v27, s[38:39] offset:2048
	global_load_dwordx4 v[20:23], v27, s[38:39] offset:2064
	global_load_dwordx4 v[28:31], v24, s[8:9] offset:512
	global_load_dwordx4 v[32:35], v24, s[8:9] offset:1024
	s_add_u32 s8, s8, 0x1800
	s_addc_u32 s9, s9, 0
	global_load_dwordx4 v[36:39], v24, s[8:9] offset:512
	global_load_dwordx4 v[40:43], v24, s[8:9] offset:1024
	s_add_u32 s8, s8, 0x1800
	s_addc_u32 s9, s9, 0
	global_load_dwordx4 v[44:47], v24, s[8:9] offset:512
	global_load_dwordx4 v[48:51], v24, s[8:9] offset:1024
	global_load_dwordx4 v[108:111], v24, s[8:9]
	s_add_u32 s8, s8, 0x1800
	s_addc_u32 s9, s9, 0
	global_load_dwordx4 v[52:55], v24, s[8:9] offset:512
	global_load_dwordx4 v[56:59], v24, s[8:9] offset:1024
	global_load_dwordx4 v[112:115], v24, s[8:9]
	s_add_u32 s8, s8, 0x1800
	s_addc_u32 s9, s9, 0
	global_load_dwordx4 v[60:63], v24, s[8:9] offset:512
	global_load_dwordx4 v[64:67], v24, s[8:9] offset:1024
	global_load_dwordx4 v[116:119], v24, s[8:9]
	s_add_u32 s8, s8, 0x1800
	s_addc_u32 s9, s9, 0
	global_load_dwordx4 v[68:71], v24, s[8:9] offset:512
	global_load_dwordx4 v[72:75], v24, s[8:9] offset:1024
	global_load_dwordx4 v[120:123], v24, s[8:9]
	s_add_u32 s8, s8, 0x1800
	s_addc_u32 s9, s9, 0
	global_load_dwordx4 v[76:79], v24, s[8:9] offset:512
	global_load_dwordx4 v[80:83], v24, s[8:9] offset:1024
	global_load_dwordx4 v[124:127], v24, s[8:9]
	s_add_u32 s8, s8, 0x1800
	s_addc_u32 s9, s9, 0
	global_load_dwordx4 v[84:87], v24, s[8:9] offset:512
	global_load_dwordx4 v[88:91], v24, s[8:9] offset:1024
	global_load_dwordx4 v[128:131], v24, s[8:9]
	s_add_u32 s8, s8, 0x1800
	s_addc_u32 s9, s9, 0
	global_load_dwordx4 v[92:95], v24, s[8:9] offset:512
	global_load_dwordx4 v[96:99], v24, s[8:9] offset:1024
	global_load_dwordx4 v[132:135], v24, s[8:9]
	s_add_u32 s8, s8, 0x1800
	s_addc_u32 s9, s9, 0
	global_load_dwordx4 v[100:103], v24, s[8:9] offset:512
	global_load_dwordx4 v[104:107], v24, s[8:9] offset:1024
	global_load_dwordx4 v[136:139], v24, s[8:9]
	s_cmp_eq_u32 s2, 0
	s_cselect_b64 s[36:37], -1, 0
	v_cmp_eq_u32_e32 vcc, 0, v25
	s_and_b64 vcc, vcc, s[36:37]
	s_waitcnt vmcnt(21)
	s_nop 1
	v_cndmask_b32_e32 v28, v28, v145, vcc
	v_cndmask_b32_e32 v29, v29, v145, vcc
	v_cndmask_b32_e32 v30, v30, v145, vcc
	v_cndmask_b32_e32 v31, v31, v145, vcc
	v_cndmask_b32_e32 v36, v36, v145, vcc
	v_cndmask_b32_e32 v37, v37, v145, vcc
	v_cndmask_b32_e32 v38, v38, v145, vcc
	v_cndmask_b32_e32 v39, v39, v145, vcc
	v_lshlrev_b32_e32 v156, 16, v28
	v_and_b32_e32 v157, 0xffff0000, v28
	v_lshlrev_b32_e32 v158, 16, v29
	v_and_b32_e32 v159, 0xffff0000, v29
	v_lshlrev_b32_e32 v160, 16, v30
	v_and_b32_e32 v161, 0xffff0000, v30
	v_lshlrev_b32_e32 v162, 16, v31
	v_and_b32_e32 v163, 0xffff0000, v31
	v_lshlrev_b32_e32 v164, 16, v32
	v_and_b32_e32 v165, 0xffff0000, v32
	v_lshlrev_b32_e32 v166, 16, v33
	v_and_b32_e32 v167, 0xffff0000, v33
	v_lshlrev_b32_e32 v168, 16, v34
	v_and_b32_e32 v169, 0xffff0000, v34
	v_lshlrev_b32_e32 v170, 16, v35
	v_and_b32_e32 v171, 0xffff0000, v35
	v_pk_mul_f32 v[28:29], v[156:157], v[164:165]
	v_pk_mul_f32 v[30:31], v[158:159], v[166:167]
	v_pk_mul_f32 v[32:33], v[160:161], v[168:169]
	v_pk_mul_f32 v[34:35], v[162:163], v[170:171]
	v_lshlrev_b32_e32 v156, 16, v36
	v_and_b32_e32 v157, 0xffff0000, v36
	v_lshlrev_b32_e32 v158, 16, v37
	v_and_b32_e32 v159, 0xffff0000, v37
	v_lshlrev_b32_e32 v160, 16, v38
	v_and_b32_e32 v161, 0xffff0000, v38
	v_lshlrev_b32_e32 v162, 16, v39
	v_and_b32_e32 v163, 0xffff0000, v39
	v_lshlrev_b32_e32 v164, 16, v40
	v_and_b32_e32 v165, 0xffff0000, v40
	v_lshlrev_b32_e32 v166, 16, v41
	v_and_b32_e32 v167, 0xffff0000, v41
	v_lshlrev_b32_e32 v168, 16, v42
	v_and_b32_e32 v169, 0xffff0000, v42
	v_lshlrev_b32_e32 v170, 16, v43
	v_and_b32_e32 v171, 0xffff0000, v43
	v_pk_mul_f32 v[36:37], v[156:157], v[164:165]
	v_pk_mul_f32 v[38:39], v[158:159], v[166:167]
	v_pk_mul_f32 v[40:41], v[160:161], v[168:169]
	v_pk_mul_f32 v[42:43], v[162:163], v[170:171]
	v_lshlrev_b32_e32 v156, 16, v44
	v_and_b32_e32 v157, 0xffff0000, v44
	v_lshlrev_b32_e32 v158, 16, v45
	v_and_b32_e32 v159, 0xffff0000, v45
	v_lshlrev_b32_e32 v160, 16, v46
	v_and_b32_e32 v161, 0xffff0000, v46
	v_lshlrev_b32_e32 v162, 16, v47
	v_and_b32_e32 v163, 0xffff0000, v47
	v_lshlrev_b32_e32 v164, 16, v48
	v_and_b32_e32 v165, 0xffff0000, v48
	v_lshlrev_b32_e32 v166, 16, v49
	v_and_b32_e32 v167, 0xffff0000, v49
	v_lshlrev_b32_e32 v168, 16, v50
	v_and_b32_e32 v169, 0xffff0000, v50
	v_lshlrev_b32_e32 v170, 16, v51
	v_and_b32_e32 v171, 0xffff0000, v51
	v_pk_mul_f32 v[44:45], v[156:157], v[164:165]
	v_pk_mul_f32 v[46:47], v[158:159], v[166:167]
	v_pk_mul_f32 v[48:49], v[160:161], v[168:169]
	v_pk_mul_f32 v[50:51], v[162:163], v[170:171]
	v_pk_mul_f32 v[140:141], v[0:1], v[28:29]
	v_pk_mul_f32 v[142:143], v[2:3], v[30:31]
	v_pk_mul_f32 v[172:173], v[4:5], v[32:33]
	v_pk_mul_f32 v[174:175], v[6:7], v[34:35]
	v_pk_fma_f32 v[140:141], v[8:9], v[36:37], v[140:141]
	v_pk_fma_f32 v[142:143], v[10:11], v[38:39], v[142:143]
	v_pk_fma_f32 v[172:173], v[12:13], v[40:41], v[172:173]
	v_pk_fma_f32 v[174:175], v[14:15], v[42:43], v[174:175]
	v_pk_fma_f32 v[140:141], v[16:17], v[44:45], v[140:141]
	v_pk_fma_f32 v[142:143], v[18:19], v[46:47], v[142:143]
	v_pk_fma_f32 v[172:173], v[20:21], v[48:49], v[172:173]
	v_pk_fma_f32 v[174:175], v[22:23], v[50:51], v[174:175]
	v_lshlrev_b32_e32 v156, 16, v108
	v_and_b32_e32 v157, 0xffff0000, v108
	v_lshlrev_b32_e32 v158, 16, v109
	v_and_b32_e32 v159, 0xffff0000, v109
	v_lshlrev_b32_e32 v160, 16, v110
	v_and_b32_e32 v161, 0xffff0000, v110
	v_lshlrev_b32_e32 v162, 16, v111
	v_and_b32_e32 v163, 0xffff0000, v111
	v_pk_mul_f32 v[140:141], v[140:141], v[156:157]
	v_pk_mul_f32 v[142:143], v[142:143], v[158:159]
	v_pk_mul_f32 v[172:173], v[172:173], v[160:161]
	v_pk_mul_f32 v[174:175], v[174:175], v[162:163]
	v_cvt_pk_bf16_f32 v108, v140, v141
	v_cvt_pk_bf16_f32 v109, v142, v143
	v_cvt_pk_bf16_f32 v110, v172, v173
	v_cvt_pk_bf16_f32 v111, v174, v175
	global_store_dwordx4 v24, v[108:111], s[10:11]
	s_add_u32 s10, s10, 0x1800
	s_addc_u32 s11, s11, 0
	s_waitcnt vmcnt(19)
	v_lshlrev_b32_e32 v156, 16, v52
	v_and_b32_e32 v157, 0xffff0000, v52
	v_lshlrev_b32_e32 v158, 16, v53
	v_and_b32_e32 v159, 0xffff0000, v53
	v_lshlrev_b32_e32 v160, 16, v54
	v_and_b32_e32 v161, 0xffff0000, v54
	v_lshlrev_b32_e32 v162, 16, v55
	v_and_b32_e32 v163, 0xffff0000, v55
	v_lshlrev_b32_e32 v164, 16, v56
	v_and_b32_e32 v165, 0xffff0000, v56
	v_lshlrev_b32_e32 v166, 16, v57
	v_and_b32_e32 v167, 0xffff0000, v57
	v_lshlrev_b32_e32 v168, 16, v58
	v_and_b32_e32 v169, 0xffff0000, v58
	v_lshlrev_b32_e32 v170, 16, v59
	v_and_b32_e32 v171, 0xffff0000, v59
	v_pk_mul_f32 v[52:53], v[156:157], v[164:165]
	v_pk_mul_f32 v[54:55], v[158:159], v[166:167]
	v_pk_mul_f32 v[56:57], v[160:161], v[168:169]
	v_pk_mul_f32 v[58:59], v[162:163], v[170:171]
	v_pk_mul_f32 v[140:141], v[0:1], v[36:37]
	v_pk_mul_f32 v[142:143], v[2:3], v[38:39]
	v_pk_mul_f32 v[172:173], v[4:5], v[40:41]
	v_pk_mul_f32 v[174:175], v[6:7], v[42:43]
	v_pk_fma_f32 v[140:141], v[8:9], v[44:45], v[140:141]
	v_pk_fma_f32 v[142:143], v[10:11], v[46:47], v[142:143]
	v_pk_fma_f32 v[172:173], v[12:13], v[48:49], v[172:173]
	v_pk_fma_f32 v[174:175], v[14:15], v[50:51], v[174:175]
	v_pk_fma_f32 v[140:141], v[16:17], v[52:53], v[140:141]
	v_pk_fma_f32 v[142:143], v[18:19], v[54:55], v[142:143]
	v_pk_fma_f32 v[172:173], v[20:21], v[56:57], v[172:173]
	v_pk_fma_f32 v[174:175], v[22:23], v[58:59], v[174:175]
	v_lshlrev_b32_e32 v156, 16, v112
	v_and_b32_e32 v157, 0xffff0000, v112
	v_lshlrev_b32_e32 v158, 16, v113
	v_and_b32_e32 v159, 0xffff0000, v113
	v_lshlrev_b32_e32 v160, 16, v114
	v_and_b32_e32 v161, 0xffff0000, v114
	v_lshlrev_b32_e32 v162, 16, v115
	v_and_b32_e32 v163, 0xffff0000, v115
	v_pk_mul_f32 v[140:141], v[140:141], v[156:157]
	v_pk_mul_f32 v[142:143], v[142:143], v[158:159]
	v_pk_mul_f32 v[172:173], v[172:173], v[160:161]
	v_pk_mul_f32 v[174:175], v[174:175], v[162:163]
	v_cvt_pk_bf16_f32 v112, v140, v141
	v_cvt_pk_bf16_f32 v113, v142, v143
	v_cvt_pk_bf16_f32 v114, v172, v173
	v_cvt_pk_bf16_f32 v115, v174, v175
	global_store_dwordx4 v24, v[112:115], s[10:11]
	s_add_u32 s10, s10, 0x1800
	s_addc_u32 s11, s11, 0
	s_waitcnt vmcnt(17)
	v_lshlrev_b32_e32 v156, 16, v60
	v_and_b32_e32 v157, 0xffff0000, v60
	v_lshlrev_b32_e32 v158, 16, v61
	v_and_b32_e32 v159, 0xffff0000, v61
	v_lshlrev_b32_e32 v160, 16, v62
	v_and_b32_e32 v161, 0xffff0000, v62
	v_lshlrev_b32_e32 v162, 16, v63
	v_and_b32_e32 v163, 0xffff0000, v63
	v_lshlrev_b32_e32 v164, 16, v64
	v_and_b32_e32 v165, 0xffff0000, v64
	v_lshlrev_b32_e32 v166, 16, v65
	v_and_b32_e32 v167, 0xffff0000, v65
	v_lshlrev_b32_e32 v168, 16, v66
	v_and_b32_e32 v169, 0xffff0000, v66
	v_lshlrev_b32_e32 v170, 16, v67
	v_and_b32_e32 v171, 0xffff0000, v67
	v_pk_mul_f32 v[60:61], v[156:157], v[164:165]
	v_pk_mul_f32 v[62:63], v[158:159], v[166:167]
	v_pk_mul_f32 v[64:65], v[160:161], v[168:169]
	v_pk_mul_f32 v[66:67], v[162:163], v[170:171]
	v_pk_mul_f32 v[140:141], v[0:1], v[44:45]
	v_pk_mul_f32 v[142:143], v[2:3], v[46:47]
	v_pk_mul_f32 v[172:173], v[4:5], v[48:49]
	v_pk_mul_f32 v[174:175], v[6:7], v[50:51]
	v_pk_fma_f32 v[140:141], v[8:9], v[52:53], v[140:141]
	v_pk_fma_f32 v[142:143], v[10:11], v[54:55], v[142:143]
	v_pk_fma_f32 v[172:173], v[12:13], v[56:57], v[172:173]
	v_pk_fma_f32 v[174:175], v[14:15], v[58:59], v[174:175]
	v_pk_fma_f32 v[140:141], v[16:17], v[60:61], v[140:141]
	v_pk_fma_f32 v[142:143], v[18:19], v[62:63], v[142:143]
	v_pk_fma_f32 v[172:173], v[20:21], v[64:65], v[172:173]
	v_pk_fma_f32 v[174:175], v[22:23], v[66:67], v[174:175]
	v_lshlrev_b32_e32 v156, 16, v116
	v_and_b32_e32 v157, 0xffff0000, v116
	v_lshlrev_b32_e32 v158, 16, v117
	v_and_b32_e32 v159, 0xffff0000, v117
	v_lshlrev_b32_e32 v160, 16, v118
	v_and_b32_e32 v161, 0xffff0000, v118
	v_lshlrev_b32_e32 v162, 16, v119
	v_and_b32_e32 v163, 0xffff0000, v119
	v_pk_mul_f32 v[140:141], v[140:141], v[156:157]
	v_pk_mul_f32 v[142:143], v[142:143], v[158:159]
	v_pk_mul_f32 v[172:173], v[172:173], v[160:161]
	v_pk_mul_f32 v[174:175], v[174:175], v[162:163]
	v_cvt_pk_bf16_f32 v116, v140, v141
	v_cvt_pk_bf16_f32 v117, v142, v143
	v_cvt_pk_bf16_f32 v118, v172, v173
	v_cvt_pk_bf16_f32 v119, v174, v175
	global_store_dwordx4 v24, v[116:119], s[10:11]
	s_add_u32 s10, s10, 0x1800
	s_addc_u32 s11, s11, 0
	s_waitcnt vmcnt(15)
	v_lshlrev_b32_e32 v156, 16, v68
	v_and_b32_e32 v157, 0xffff0000, v68
	v_lshlrev_b32_e32 v158, 16, v69
	v_and_b32_e32 v159, 0xffff0000, v69
	v_lshlrev_b32_e32 v160, 16, v70
	v_and_b32_e32 v161, 0xffff0000, v70
	v_lshlrev_b32_e32 v162, 16, v71
	v_and_b32_e32 v163, 0xffff0000, v71
	v_lshlrev_b32_e32 v164, 16, v72
	v_and_b32_e32 v165, 0xffff0000, v72
	v_lshlrev_b32_e32 v166, 16, v73
	v_and_b32_e32 v167, 0xffff0000, v73
	v_lshlrev_b32_e32 v168, 16, v74
	v_and_b32_e32 v169, 0xffff0000, v74
	v_lshlrev_b32_e32 v170, 16, v75
	v_and_b32_e32 v171, 0xffff0000, v75
	v_pk_mul_f32 v[68:69], v[156:157], v[164:165]
	v_pk_mul_f32 v[70:71], v[158:159], v[166:167]
	v_pk_mul_f32 v[72:73], v[160:161], v[168:169]
	v_pk_mul_f32 v[74:75], v[162:163], v[170:171]
	v_pk_mul_f32 v[140:141], v[0:1], v[52:53]
	v_pk_mul_f32 v[142:143], v[2:3], v[54:55]
	v_pk_mul_f32 v[172:173], v[4:5], v[56:57]
	v_pk_mul_f32 v[174:175], v[6:7], v[58:59]
	v_pk_fma_f32 v[140:141], v[8:9], v[60:61], v[140:141]
	v_pk_fma_f32 v[142:143], v[10:11], v[62:63], v[142:143]
	v_pk_fma_f32 v[172:173], v[12:13], v[64:65], v[172:173]
	v_pk_fma_f32 v[174:175], v[14:15], v[66:67], v[174:175]
	v_pk_fma_f32 v[140:141], v[16:17], v[68:69], v[140:141]
	v_pk_fma_f32 v[142:143], v[18:19], v[70:71], v[142:143]
	v_pk_fma_f32 v[172:173], v[20:21], v[72:73], v[172:173]
	v_pk_fma_f32 v[174:175], v[22:23], v[74:75], v[174:175]
	v_lshlrev_b32_e32 v156, 16, v120
	v_and_b32_e32 v157, 0xffff0000, v120
	v_lshlrev_b32_e32 v158, 16, v121
	v_and_b32_e32 v159, 0xffff0000, v121
	v_lshlrev_b32_e32 v160, 16, v122
	v_and_b32_e32 v161, 0xffff0000, v122
	v_lshlrev_b32_e32 v162, 16, v123
	v_and_b32_e32 v163, 0xffff0000, v123
	v_pk_mul_f32 v[140:141], v[140:141], v[156:157]
	v_pk_mul_f32 v[142:143], v[142:143], v[158:159]
	v_pk_mul_f32 v[172:173], v[172:173], v[160:161]
	v_pk_mul_f32 v[174:175], v[174:175], v[162:163]
	v_cvt_pk_bf16_f32 v120, v140, v141
	v_cvt_pk_bf16_f32 v121, v142, v143
	v_cvt_pk_bf16_f32 v122, v172, v173
	v_cvt_pk_bf16_f32 v123, v174, v175
	global_store_dwordx4 v24, v[120:123], s[10:11]
	s_add_u32 s10, s10, 0x1800
	s_addc_u32 s11, s11, 0
	s_waitcnt vmcnt(13)
	v_lshlrev_b32_e32 v156, 16, v76
	v_and_b32_e32 v157, 0xffff0000, v76
	v_lshlrev_b32_e32 v158, 16, v77
	v_and_b32_e32 v159, 0xffff0000, v77
	v_lshlrev_b32_e32 v160, 16, v78
	v_and_b32_e32 v161, 0xffff0000, v78
	v_lshlrev_b32_e32 v162, 16, v79
	v_and_b32_e32 v163, 0xffff0000, v79
	v_lshlrev_b32_e32 v164, 16, v80
	v_and_b32_e32 v165, 0xffff0000, v80
	v_lshlrev_b32_e32 v166, 16, v81
	v_and_b32_e32 v167, 0xffff0000, v81
	v_lshlrev_b32_e32 v168, 16, v82
	v_and_b32_e32 v169, 0xffff0000, v82
	v_lshlrev_b32_e32 v170, 16, v83
	v_and_b32_e32 v171, 0xffff0000, v83
	v_pk_mul_f32 v[76:77], v[156:157], v[164:165]
	v_pk_mul_f32 v[78:79], v[158:159], v[166:167]
	v_pk_mul_f32 v[80:81], v[160:161], v[168:169]
	v_pk_mul_f32 v[82:83], v[162:163], v[170:171]
	v_pk_mul_f32 v[140:141], v[0:1], v[60:61]
	v_pk_mul_f32 v[142:143], v[2:3], v[62:63]
	v_pk_mul_f32 v[172:173], v[4:5], v[64:65]
	v_pk_mul_f32 v[174:175], v[6:7], v[66:67]
	v_pk_fma_f32 v[140:141], v[8:9], v[68:69], v[140:141]
	v_pk_fma_f32 v[142:143], v[10:11], v[70:71], v[142:143]
	v_pk_fma_f32 v[172:173], v[12:13], v[72:73], v[172:173]
	v_pk_fma_f32 v[174:175], v[14:15], v[74:75], v[174:175]
	v_pk_fma_f32 v[140:141], v[16:17], v[76:77], v[140:141]
	v_pk_fma_f32 v[142:143], v[18:19], v[78:79], v[142:143]
	v_pk_fma_f32 v[172:173], v[20:21], v[80:81], v[172:173]
	v_pk_fma_f32 v[174:175], v[22:23], v[82:83], v[174:175]
	v_lshlrev_b32_e32 v156, 16, v124
	v_and_b32_e32 v157, 0xffff0000, v124
	v_lshlrev_b32_e32 v158, 16, v125
	v_and_b32_e32 v159, 0xffff0000, v125
	v_lshlrev_b32_e32 v160, 16, v126
	v_and_b32_e32 v161, 0xffff0000, v126
	v_lshlrev_b32_e32 v162, 16, v127
	v_and_b32_e32 v163, 0xffff0000, v127
	v_pk_mul_f32 v[140:141], v[140:141], v[156:157]
	v_pk_mul_f32 v[142:143], v[142:143], v[158:159]
	v_pk_mul_f32 v[172:173], v[172:173], v[160:161]
	v_pk_mul_f32 v[174:175], v[174:175], v[162:163]
	v_cvt_pk_bf16_f32 v124, v140, v141
	v_cvt_pk_bf16_f32 v125, v142, v143
	v_cvt_pk_bf16_f32 v126, v172, v173
	v_cvt_pk_bf16_f32 v127, v174, v175
	global_store_dwordx4 v24, v[124:127], s[10:11]
	s_add_u32 s10, s10, 0x1800
	s_addc_u32 s11, s11, 0
	s_waitcnt vmcnt(11)
	v_lshlrev_b32_e32 v156, 16, v84
	v_and_b32_e32 v157, 0xffff0000, v84
	v_lshlrev_b32_e32 v158, 16, v85
	v_and_b32_e32 v159, 0xffff0000, v85
	v_lshlrev_b32_e32 v160, 16, v86
	v_and_b32_e32 v161, 0xffff0000, v86
	v_lshlrev_b32_e32 v162, 16, v87
	v_and_b32_e32 v163, 0xffff0000, v87
	v_lshlrev_b32_e32 v164, 16, v88
	v_and_b32_e32 v165, 0xffff0000, v88
	v_lshlrev_b32_e32 v166, 16, v89
	v_and_b32_e32 v167, 0xffff0000, v89
	v_lshlrev_b32_e32 v168, 16, v90
	v_and_b32_e32 v169, 0xffff0000, v90
	v_lshlrev_b32_e32 v170, 16, v91
	v_and_b32_e32 v171, 0xffff0000, v91
	v_pk_mul_f32 v[84:85], v[156:157], v[164:165]
	v_pk_mul_f32 v[86:87], v[158:159], v[166:167]
	v_pk_mul_f32 v[88:89], v[160:161], v[168:169]
	v_pk_mul_f32 v[90:91], v[162:163], v[170:171]
	v_pk_mul_f32 v[140:141], v[0:1], v[68:69]
	v_pk_mul_f32 v[142:143], v[2:3], v[70:71]
	v_pk_mul_f32 v[172:173], v[4:5], v[72:73]
	v_pk_mul_f32 v[174:175], v[6:7], v[74:75]
	v_pk_fma_f32 v[140:141], v[8:9], v[76:77], v[140:141]
	v_pk_fma_f32 v[142:143], v[10:11], v[78:79], v[142:143]
	v_pk_fma_f32 v[172:173], v[12:13], v[80:81], v[172:173]
	v_pk_fma_f32 v[174:175], v[14:15], v[82:83], v[174:175]
	v_pk_fma_f32 v[140:141], v[16:17], v[84:85], v[140:141]
	v_pk_fma_f32 v[142:143], v[18:19], v[86:87], v[142:143]
	v_pk_fma_f32 v[172:173], v[20:21], v[88:89], v[172:173]
	v_pk_fma_f32 v[174:175], v[22:23], v[90:91], v[174:175]
	v_lshlrev_b32_e32 v156, 16, v128
	v_and_b32_e32 v157, 0xffff0000, v128
	v_lshlrev_b32_e32 v158, 16, v129
	v_and_b32_e32 v159, 0xffff0000, v129
	v_lshlrev_b32_e32 v160, 16, v130
	v_and_b32_e32 v161, 0xffff0000, v130
	v_lshlrev_b32_e32 v162, 16, v131
	v_and_b32_e32 v163, 0xffff0000, v131
	v_pk_mul_f32 v[140:141], v[140:141], v[156:157]
	v_pk_mul_f32 v[142:143], v[142:143], v[158:159]
	v_pk_mul_f32 v[172:173], v[172:173], v[160:161]
	v_pk_mul_f32 v[174:175], v[174:175], v[162:163]
	v_cvt_pk_bf16_f32 v128, v140, v141
	v_cvt_pk_bf16_f32 v129, v142, v143
	v_cvt_pk_bf16_f32 v130, v172, v173
	v_cvt_pk_bf16_f32 v131, v174, v175
	global_store_dwordx4 v24, v[128:131], s[10:11]
	s_add_u32 s10, s10, 0x1800
	s_addc_u32 s11, s11, 0
	s_waitcnt vmcnt(9)
	v_lshlrev_b32_e32 v156, 16, v92
	v_and_b32_e32 v157, 0xffff0000, v92
	v_lshlrev_b32_e32 v158, 16, v93
	v_and_b32_e32 v159, 0xffff0000, v93
	v_lshlrev_b32_e32 v160, 16, v94
	v_and_b32_e32 v161, 0xffff0000, v94
	v_lshlrev_b32_e32 v162, 16, v95
	v_and_b32_e32 v163, 0xffff0000, v95
	v_lshlrev_b32_e32 v164, 16, v96
	v_and_b32_e32 v165, 0xffff0000, v96
	v_lshlrev_b32_e32 v166, 16, v97
	v_and_b32_e32 v167, 0xffff0000, v97
	v_lshlrev_b32_e32 v168, 16, v98
	v_and_b32_e32 v169, 0xffff0000, v98
	v_lshlrev_b32_e32 v170, 16, v99
	v_and_b32_e32 v171, 0xffff0000, v99
	v_pk_mul_f32 v[92:93], v[156:157], v[164:165]
	v_pk_mul_f32 v[94:95], v[158:159], v[166:167]
	v_pk_mul_f32 v[96:97], v[160:161], v[168:169]
	v_pk_mul_f32 v[98:99], v[162:163], v[170:171]
	v_pk_mul_f32 v[140:141], v[0:1], v[76:77]
	v_pk_mul_f32 v[142:143], v[2:3], v[78:79]
	v_pk_mul_f32 v[172:173], v[4:5], v[80:81]
	v_pk_mul_f32 v[174:175], v[6:7], v[82:83]
	v_pk_fma_f32 v[140:141], v[8:9], v[84:85], v[140:141]
	v_pk_fma_f32 v[142:143], v[10:11], v[86:87], v[142:143]
	v_pk_fma_f32 v[172:173], v[12:13], v[88:89], v[172:173]
	v_pk_fma_f32 v[174:175], v[14:15], v[90:91], v[174:175]
	v_pk_fma_f32 v[140:141], v[16:17], v[92:93], v[140:141]
	v_pk_fma_f32 v[142:143], v[18:19], v[94:95], v[142:143]
	v_pk_fma_f32 v[172:173], v[20:21], v[96:97], v[172:173]
	v_pk_fma_f32 v[174:175], v[22:23], v[98:99], v[174:175]
	v_lshlrev_b32_e32 v156, 16, v132
	v_and_b32_e32 v157, 0xffff0000, v132
	v_lshlrev_b32_e32 v158, 16, v133
	v_and_b32_e32 v159, 0xffff0000, v133
	v_lshlrev_b32_e32 v160, 16, v134
	v_and_b32_e32 v161, 0xffff0000, v134
	v_lshlrev_b32_e32 v162, 16, v135
	v_and_b32_e32 v163, 0xffff0000, v135
	v_pk_mul_f32 v[140:141], v[140:141], v[156:157]
	v_pk_mul_f32 v[142:143], v[142:143], v[158:159]
	v_pk_mul_f32 v[172:173], v[172:173], v[160:161]
	v_pk_mul_f32 v[174:175], v[174:175], v[162:163]
	v_cvt_pk_bf16_f32 v132, v140, v141
	v_cvt_pk_bf16_f32 v133, v142, v143
	v_cvt_pk_bf16_f32 v134, v172, v173
	v_cvt_pk_bf16_f32 v135, v174, v175
	global_store_dwordx4 v24, v[132:135], s[10:11]
	s_add_u32 s10, s10, 0x1800
	s_addc_u32 s11, s11, 0
	s_waitcnt vmcnt(7)
	v_lshlrev_b32_e32 v156, 16, v100
	v_and_b32_e32 v157, 0xffff0000, v100
	v_lshlrev_b32_e32 v158, 16, v101
	v_and_b32_e32 v159, 0xffff0000, v101
	v_lshlrev_b32_e32 v160, 16, v102
	v_and_b32_e32 v161, 0xffff0000, v102
	v_lshlrev_b32_e32 v162, 16, v103
	v_and_b32_e32 v163, 0xffff0000, v103
	v_lshlrev_b32_e32 v164, 16, v104
	v_and_b32_e32 v165, 0xffff0000, v104
	v_lshlrev_b32_e32 v166, 16, v105
	v_and_b32_e32 v167, 0xffff0000, v105
	v_lshlrev_b32_e32 v168, 16, v106
	v_and_b32_e32 v169, 0xffff0000, v106
	v_lshlrev_b32_e32 v170, 16, v107
	v_and_b32_e32 v171, 0xffff0000, v107
	v_pk_mul_f32 v[100:101], v[156:157], v[164:165]
	v_pk_mul_f32 v[102:103], v[158:159], v[166:167]
	v_pk_mul_f32 v[104:105], v[160:161], v[168:169]
	v_pk_mul_f32 v[106:107], v[162:163], v[170:171]
	v_pk_mul_f32 v[140:141], v[0:1], v[84:85]
	v_pk_mul_f32 v[142:143], v[2:3], v[86:87]
	v_pk_mul_f32 v[172:173], v[4:5], v[88:89]
	v_pk_mul_f32 v[174:175], v[6:7], v[90:91]
	v_pk_fma_f32 v[140:141], v[8:9], v[92:93], v[140:141]
	v_pk_fma_f32 v[142:143], v[10:11], v[94:95], v[142:143]
	v_pk_fma_f32 v[172:173], v[12:13], v[96:97], v[172:173]
	v_pk_fma_f32 v[174:175], v[14:15], v[98:99], v[174:175]
	v_pk_fma_f32 v[140:141], v[16:17], v[100:101], v[140:141]
	v_pk_fma_f32 v[142:143], v[18:19], v[102:103], v[142:143]
	v_pk_fma_f32 v[172:173], v[20:21], v[104:105], v[172:173]
	v_pk_fma_f32 v[174:175], v[22:23], v[106:107], v[174:175]
	v_lshlrev_b32_e32 v156, 16, v136
	v_and_b32_e32 v157, 0xffff0000, v136
	v_lshlrev_b32_e32 v158, 16, v137
	v_and_b32_e32 v159, 0xffff0000, v137
	v_lshlrev_b32_e32 v160, 16, v138
	v_and_b32_e32 v161, 0xffff0000, v138
	v_lshlrev_b32_e32 v162, 16, v139
	v_and_b32_e32 v163, 0xffff0000, v139
	v_pk_mul_f32 v[140:141], v[140:141], v[156:157]
	v_pk_mul_f32 v[142:143], v[142:143], v[158:159]
	v_pk_mul_f32 v[172:173], v[172:173], v[160:161]
	v_pk_mul_f32 v[174:175], v[174:175], v[162:163]
	v_cvt_pk_bf16_f32 v136, v140, v141
	v_cvt_pk_bf16_f32 v137, v142, v143
	v_cvt_pk_bf16_f32 v138, v172, v173
	v_cvt_pk_bf16_f32 v139, v174, v175
	global_store_dwordx4 v24, v[136:139], s[10:11]
	v_readlane_b32 s8, v255, 40
	v_readlane_b32 s9, v255, 41
	v_readlane_b32 s10, v255, 42
	v_readlane_b32 s11, v255, 43
	s_mov_b64 s[2:3], 0
.LBB0_477:
	s_mov_b64 s[4:5], 0
	s_and_b64 vcc, exec, s[2:3]
	s_mov_b64 s[2:3], 0
	s_cbranch_vccz .LBB0_485
	v_writelane_b32 v255, s8, 40
	v_writelane_b32 v255, s9, 41
	v_writelane_b32 v255, s10, 42
	v_writelane_b32 v255, s11, 43
	v_writelane_b32 v255, s12, 44
	v_writelane_b32 v255, s13, 45
	v_writelane_b32 v255, s14, 46
	v_writelane_b32 v255, s15, 47
	s_lshl_b32 s0, s18, 7
	s_add_i32 s0, s0, 0xffff0000
	v_lshrrev_b32_e32 v9, 6, v176
	v_and_b32_e32 v0, 15, v197
	v_readfirstlane_b32 s2, v9
	v_lshrrev_b32_e32 v1, 4, v197
	v_lshlrev_b32_e32 v2, 3, v197
	v_lshlrev_b32_e32 v9, 4, v197
	s_nop 3
	s_lshr_b32 s3, s2, 1
	s_and_b32 s4, s2, 1
	s_lshl_b32 s5, s2, 4
	s_add_i32 s5, s5, s0
	s_mul_i32 s5, s5, 0x1800
	s_add_u32 s8, s66, s5
	s_addc_u32 s9, s67, 0
	v_lshrrev_b32_e32 v30, 5, v176
	v_and_b32_e32 v31, 31, v176
	v_mul_u32_u24_e32 v28, 0x1800, v30
	v_lshl_add_u32 v28, v31, 4, v28
	v_mul_u32_u24_e32 v144, 0x210, v30
	v_lshl_add_u32 v144, v31, 4, v144
	v_add_u32_e32 v144, 0x11000, v144
	s_mul_i32 s5, s0, 0x1800
	s_add_u32 s10, s66, s5
	s_addc_u32 s11, s67, 0
	global_load_dwordx4 v[128:131], v28, s[10:11] offset:1536
	s_add_u32 s10, s10, 0x18000
	s_addc_u32 s11, s11, 0
	global_load_dwordx4 v[132:135], v28, s[10:11] offset:1536
	s_add_u32 s10, s10, 0x18000
	s_addc_u32 s11, s11, 0
	global_load_dwordx4 v[136:139], v28, s[10:11] offset:1536
	s_add_u32 s10, s10, 0x18000
	s_addc_u32 s11, s11, 0
	global_load_dwordx4 v[140:143], v28, s[10:11] offset:1536
	s_add_u32 s10, s10, 0x18000
	s_addc_u32 s11, s11, 0
	global_load_dwordx4 v[156:159], v28, s[10:11] offset:1536
	s_add_u32 s10, s10, 0x18000
	s_addc_u32 s11, s11, 0
	global_load_dwordx4 v[160:163], v28, s[10:11] offset:1536
	s_add_u32 s10, s10, 0x18000
	s_addc_u32 s11, s11, 0
	global_load_dwordx4 v[164:167], v28, s[10:11] offset:1536
	s_add_u32 s10, s10, 0x18000
	s_addc_u32 s11, s11, 0
	global_load_dwordx4 v[168:171], v28, s[10:11] offset:1536
	s_add_u32 s10, s10, 0x18000
	s_addc_u32 s11, s11, 0
	s_mul_i32 s5, s2, 0x18000
	s_mul_i32 s36, s0, 0x1800
	s_add_i32 s5, s5, s36
	s_add_u32 s8, s66, s5
	s_addc_u32 s9, s67, 0
	global_load_dwordx2 v[32:33], v2, s[8:9] offset:2048
	s_add_u32 s8, s8, 0x1800
	s_addc_u32 s9, s9, 0
	global_load_dwordx2 v[34:35], v2, s[8:9] offset:2048
	s_add_u32 s8, s8, 0x1800
	s_addc_u32 s9, s9, 0
	global_load_dwordx2 v[36:37], v2, s[8:9] offset:2048
	s_add_u32 s8, s8, 0x1800
	s_addc_u32 s9, s9, 0
	global_load_dwordx2 v[38:39], v2, s[8:9] offset:2048
	s_add_u32 s8, s8, 0x1800
	s_addc_u32 s9, s9, 0
	global_load_dwordx2 v[40:41], v2, s[8:9] offset:2048
	s_add_u32 s8, s8, 0x1800
	s_addc_u32 s9, s9, 0
	global_load_dwordx2 v[42:43], v2, s[8:9] offset:2048
	s_add_u32 s8, s8, 0x1800
	s_addc_u32 s9, s9, 0
	global_load_dwordx2 v[44:45], v2, s[8:9] offset:2048
	s_add_u32 s8, s8, 0x1800
	s_addc_u32 s9, s9, 0
	global_load_dwordx2 v[46:47], v2, s[8:9] offset:2048
	s_add_u32 s8, s8, 0x1800
	s_addc_u32 s9, s9, 0
	global_load_dwordx2 v[48:49], v2, s[8:9] offset:2048
	s_add_u32 s8, s8, 0x1800
	s_addc_u32 s9, s9, 0
	global_load_dwordx2 v[50:51], v2, s[8:9] offset:2048
	s_add_u32 s8, s8, 0x1800
	s_addc_u32 s9, s9, 0
	global_load_dwordx2 v[52:53], v2, s[8:9] offset:2048
	s_add_u32 s8, s8, 0x1800
	s_addc_u32 s9, s9, 0
	global_load_dwordx2 v[54:55], v2, s[8:9] offset:2048
	s_add_u32 s8, s8, 0x1800
	s_addc_u32 s9, s9, 0
	global_load_dwordx2 v[56:57], v2, s[8:9] offset:2048
	s_add_u32 s8, s8, 0x1800
	s_addc_u32 s9, s9, 0
	global_load_dwordx2 v[58:59], v2, s[8:9] offset:2048
	s_add_u32 s8, s8, 0x1800
	s_addc_u32 s9, s9, 0
	global_load_dwordx2 v[60:61], v2, s[8:9] offset:2048
	s_add_u32 s8, s8, 0x1800
	s_addc_u32 s9, s9, 0
	global_load_dwordx2 v[62:63], v2, s[8:9] offset:2048
	global_load_dwordx4 v[10:13], v9, s[40:41]
	s_lshl_b32 s5, s3, 7
	s_lshl_b32 s36, s4, 6
	s_add_i32 s5, s5, s36
	s_lshl_b32 s36, s5, 2
	s_add_u32 s14, s44, s36
	s_addc_u32 s15, s45, 0
	s_lshl_b32 s5, s5, 9
	s_add_u32 s10, s42, s5
	s_addc_u32 s11, s43, 0
	v_lshlrev_b32_e32 v3, 9, v0
	v_lshl_add_u32 v3, v1, 5, v3
	global_load_dwordx4 v[64:67], v3, s[10:11]
	global_load_dwordx4 v[68:71], v3, s[10:11] offset:16
	global_load_dwordx4 v[96:99], v3, s[10:11] offset:128
	global_load_dwordx4 v[100:103], v3, s[10:11] offset:144
	s_add_u32 s10, s10, 0x2000
	s_addc_u32 s11, s11, 0
	global_load_dwordx4 v[72:75], v3, s[10:11]
	global_load_dwordx4 v[76:79], v3, s[10:11] offset:16
	global_load_dwordx4 v[104:107], v3, s[10:11] offset:128
	global_load_dwordx4 v[108:111], v3, s[10:11] offset:144
	s_add_u32 s10, s10, 0x2000
	s_addc_u32 s11, s11, 0
	global_load_dwordx4 v[80:83], v3, s[10:11]
	global_load_dwordx4 v[84:87], v3, s[10:11] offset:16
	global_load_dwordx4 v[112:115], v3, s[10:11] offset:128
	global_load_dwordx4 v[116:119], v3, s[10:11] offset:144
	s_add_u32 s10, s10, 0x2000
	s_addc_u32 s11, s11, 0
	global_load_dwordx4 v[88:91], v3, s[10:11]
	global_load_dwordx4 v[92:95], v3, s[10:11] offset:16
	global_load_dwordx4 v[120:123], v3, s[10:11] offset:128
	global_load_dwordx4 v[124:127], v3, s[10:11] offset:144
	s_add_u32 s10, s10, 0x2000
	s_addc_u32 s11, s11, 0
	s_sub_u32 s12, 0, s4
	s_mov_b32 s13, 0xf800000
	v_mul_u32_u24_e32 v4, 0x440, v197
	s_lshl_b32 s5, s2, 5
	v_add_u32_e32 v4, s5, v4
	v_mul_u32_u24_e32 v5, 0x110, v0
	v_lshl_add_u32 v5, v1, 4, v5
	s_mul_i32 s5, s3, 0x4400
	v_add_u32_e32 v5, s5, v5
	v_mul_u32_u24_e32 v6, 0x1800, v0
	v_lshl_add_u32 v6, v1, 3, v6
	v_lshlrev_b32_e32 v7, 2, v0
	v_mov_b32_e32 v8, 0xffff
	v_lshlrev_b32_e32 v174, 3, v1
	v_sub_u32_e32 v172, v0, v174
	v_add_u32_e32 v173, 16, v172
	v_add_u32_e32 v174, 0, v172
	v_add_u32_e32 v175, -1, v174
	v_ashrrev_i32_e32 v174, 31, v174
	v_ashrrev_i32_e32 v175, 31, v175
	v_not_b32_e32 v174, v174
	v_not_b32_e32 v175, v175
	v_bfi_b32 v14, v8, v174, v175
	v_add_u32_e32 v174, -2, v172
	v_add_u32_e32 v175, -1, v174
	v_ashrrev_i32_e32 v174, 31, v174
	v_ashrrev_i32_e32 v175, 31, v175
	v_not_b32_e32 v174, v174
	v_not_b32_e32 v175, v175
	v_bfi_b32 v15, v8, v174, v175
	v_add_u32_e32 v174, -4, v172
	v_add_u32_e32 v175, -1, v174
	v_ashrrev_i32_e32 v174, 31, v174
	v_ashrrev_i32_e32 v175, 31, v175
	v_not_b32_e32 v174, v174
	v_not_b32_e32 v175, v175
	v_bfi_b32 v16, v8, v174, v175
	v_add_u32_e32 v174, -6, v172
	v_add_u32_e32 v175, -1, v174
	v_ashrrev_i32_e32 v174, 31, v174
	v_ashrrev_i32_e32 v175, 31, v175
	v_not_b32_e32 v174, v174
	v_not_b32_e32 v175, v175
	v_bfi_b32 v17, v8, v174, v175
	v_add_u32_e32 v174, 0, v173
	v_add_u32_e32 v175, -1, v174
	v_ashrrev_i32_e32 v174, 31, v174
	v_ashrrev_i32_e32 v175, 31, v175
	v_not_b32_e32 v174, v174
	v_not_b32_e32 v175, v175
	v_bfi_b32 v18, v8, v174, v175
	v_add_u32_e32 v174, -2, v173
	v_add_u32_e32 v175, -1, v174
	v_ashrrev_i32_e32 v174, 31, v174
	v_ashrrev_i32_e32 v175, 31, v175
	v_not_b32_e32 v174, v174
	v_not_b32_e32 v175, v175
	v_bfi_b32 v19, v8, v174, v175
	v_add_u32_e32 v174, -4, v173
	v_add_u32_e32 v175, -1, v174
	v_ashrrev_i32_e32 v174, 31, v174
	v_ashrrev_i32_e32 v175, 31, v175
	v_not_b32_e32 v174, v174
	v_not_b32_e32 v175, v175
	v_bfi_b32 v20, v8, v174, v175
	v_add_u32_e32 v174, -6, v173
	v_add_u32_e32 v175, -1, v174
	v_ashrrev_i32_e32 v174, 31, v174
	v_ashrrev_i32_e32 v175, 31, v175
	v_not_b32_e32 v174, v174
	v_not_b32_e32 v175, v175
	v_bfi_b32 v21, v8, v174, v175
	v_or_b32_e32 v22, s12, v14
	v_or_b32_e32 v23, s12, v15
	v_or_b32_e32 v24, s12, v16
	v_or_b32_e32 v25, s12, v17
	v_or_b32_e32 v26, s12, v18
	v_or_b32_e32 v27, s12, v19
	v_or_b32_e32 v28, s12, v20
	v_or_b32_e32 v29, s12, v21
	s_waitcnt vmcnt(33)
	ds_write_b128 v144, v[128:131]
	ds_write_b128 v144, v[132:135] offset:8448
	ds_write_b128 v144, v[136:139] offset:16896
	ds_write_b128 v144, v[140:143] offset:25344
	ds_write_b128 v144, v[156:159] offset:33792
	ds_write_b128 v144, v[160:163] offset:42240
	ds_write_b128 v144, v[164:167] offset:50688
	ds_write_b128 v144, v[168:171] offset:59136
	s_waitcnt vmcnt(16)
	v_lshlrev_b32_e32 v128, 16, v32
	v_and_b32_e32 v129, 0xffff0000, v32
	v_lshlrev_b32_e32 v130, 16, v33
	v_and_b32_e32 v131, 0xffff0000, v33
	v_lshlrev_b32_e32 v132, 16, v34
	v_and_b32_e32 v133, 0xffff0000, v34
	v_lshlrev_b32_e32 v134, 16, v35
	v_and_b32_e32 v135, 0xffff0000, v35
	v_lshlrev_b32_e32 v136, 16, v36
	v_and_b32_e32 v137, 0xffff0000, v36
	v_lshlrev_b32_e32 v138, 16, v37
	v_and_b32_e32 v139, 0xffff0000, v37
	v_lshlrev_b32_e32 v140, 16, v38
	v_and_b32_e32 v141, 0xffff0000, v38
	v_lshlrev_b32_e32 v142, 16, v39
	v_and_b32_e32 v143, 0xffff0000, v39
	v_add_f32_e32 v156, v128, v129
	v_add_f32_e32 v160, v130, v131
	v_add_f32_e32 v157, v132, v133
	v_add_f32_e32 v161, v134, v135
	v_add_f32_e32 v158, v136, v137
	v_add_f32_e32 v162, v138, v139
	v_add_f32_e32 v159, v140, v141
	v_add_f32_e32 v163, v142, v143
	v_add_f32_e32 v156, v156, v160
	v_add_f32_e32 v157, v157, v161
	v_add_f32_e32 v158, v158, v162
	v_add_f32_e32 v159, v159, v163
	v_add_f32_dpp v156, v156, v156 quad_perm:[1,0,3,2] row_mask:0xf bank_mask:0xf
	v_add_f32_dpp v157, v157, v157 quad_perm:[1,0,3,2] row_mask:0xf bank_mask:0xf
	v_add_f32_dpp v158, v158, v158 quad_perm:[1,0,3,2] row_mask:0xf bank_mask:0xf
	v_add_f32_dpp v159, v159, v159 quad_perm:[1,0,3,2] row_mask:0xf bank_mask:0xf
	v_add_f32_dpp v156, v156, v156 quad_perm:[2,3,0,1] row_mask:0xf bank_mask:0xf
	v_add_f32_dpp v157, v157, v157 quad_perm:[2,3,0,1] row_mask:0xf bank_mask:0xf
	v_add_f32_dpp v158, v158, v158 quad_perm:[2,3,0,1] row_mask:0xf bank_mask:0xf
	v_add_f32_dpp v159, v159, v159 quad_perm:[2,3,0,1] row_mask:0xf bank_mask:0xf
	v_add_f32_dpp v156, v156, v156 row_half_mirror row_mask:0xf bank_mask:0xf
	v_add_f32_dpp v157, v157, v157 row_half_mirror row_mask:0xf bank_mask:0xf
	v_add_f32_dpp v158, v158, v158 row_half_mirror row_mask:0xf bank_mask:0xf
	v_add_f32_dpp v159, v159, v159 row_half_mirror row_mask:0xf bank_mask:0xf
	v_add_f32_dpp v156, v156, v156 row_mirror row_mask:0xf bank_mask:0xf
	v_add_f32_dpp v157, v157, v157 row_mirror row_mask:0xf bank_mask:0xf
	v_add_f32_dpp v158, v158, v158 row_mirror row_mask:0xf bank_mask:0xf
	v_add_f32_dpp v159, v159, v159 row_mirror row_mask:0xf bank_mask:0xf
	v_mov_b32_e32 v160, v156
	v_mov_b32_e32 v161, v157
	v_mov_b32_e32 v162, v158
	v_mov_b32_e32 v163, v159
	v_permlane16_swap_b32_e32 v156, v160
	v_permlane16_swap_b32_e32 v157, v161
	v_permlane16_swap_b32_e32 v158, v162
	v_permlane16_swap_b32_e32 v159, v163
	v_add_f32_e32 v156, v156, v160
	v_add_f32_e32 v157, v157, v161
	v_add_f32_e32 v158, v158, v162
	v_add_f32_e32 v159, v159, v163
	v_mov_b32_e32 v160, v156
	v_mov_b32_e32 v161, v157
	v_mov_b32_e32 v162, v158
	v_mov_b32_e32 v163, v159
	v_permlane32_swap_b32_e32 v156, v160
	v_permlane32_swap_b32_e32 v157, v161
	v_permlane32_swap_b32_e32 v158, v162
	v_permlane32_swap_b32_e32 v159, v163
	v_add_f32_e32 v156, v156, v160
	v_add_f32_e32 v157, v157, v161
	v_add_f32_e32 v158, v158, v162
	v_add_f32_e32 v159, v159, v163
	v_fmac_f32_e32 v129, 0xbb800000, v156
	v_fmac_f32_e32 v131, 0xbb800000, v156
	v_fmac_f32_e32 v130, 0xbb800000, v156
	v_fmac_f32_e32 v128, 0xbb800000, v156
	v_fmac_f32_e32 v133, 0xbb800000, v157
	v_fmac_f32_e32 v135, 0xbb800000, v157
	v_fmac_f32_e32 v134, 0xbb800000, v157
	v_fmac_f32_e32 v132, 0xbb800000, v157
	v_fmac_f32_e32 v137, 0xbb800000, v158
	v_fmac_f32_e32 v139, 0xbb800000, v158
	v_fmac_f32_e32 v138, 0xbb800000, v158
	v_fmac_f32_e32 v136, 0xbb800000, v158
	v_fmac_f32_e32 v141, 0xbb800000, v159
	v_fmac_f32_e32 v143, 0xbb800000, v159
	v_fmac_f32_e32 v142, 0xbb800000, v159
	v_fmac_f32_e32 v140, 0xbb800000, v159
	v_mul_f32_e32 v156, v128, v128
	v_mul_f32_e32 v160, v129, v129
	v_mul_f32_e32 v164, v130, v130
	v_mul_f32_e32 v168, v131, v131
	v_mul_f32_e32 v157, v132, v132
	v_mul_f32_e32 v161, v133, v133
	v_mul_f32_e32 v165, v134, v134
	v_mul_f32_e32 v169, v135, v135
	v_mul_f32_e32 v158, v136, v136
	v_mul_f32_e32 v162, v137, v137
	v_mul_f32_e32 v166, v138, v138
	v_mul_f32_e32 v170, v139, v139
	v_mul_f32_e32 v159, v140, v140
	v_mul_f32_e32 v163, v141, v141
	v_mul_f32_e32 v167, v142, v142
	v_mul_f32_e32 v171, v143, v143
	v_add_f32_e32 v156, v160, v156
	v_add_f32_e32 v164, v164, v168
	v_add_f32_e32 v157, v161, v157
	v_add_f32_e32 v165, v165, v169
	v_add_f32_e32 v158, v162, v158
	v_add_f32_e32 v166, v166, v170
	v_add_f32_e32 v159, v163, v159
	v_add_f32_e32 v167, v167, v171
	v_add_f32_e32 v156, v156, v164
	v_add_f32_e32 v157, v157, v165
	v_add_f32_e32 v158, v158, v166
	v_add_f32_e32 v159, v159, v167
	v_add_f32_dpp v156, v156, v156 quad_perm:[1,0,3,2] row_mask:0xf bank_mask:0xf
	v_add_f32_dpp v157, v157, v157 quad_perm:[1,0,3,2] row_mask:0xf bank_mask:0xf
	v_add_f32_dpp v158, v158, v158 quad_perm:[1,0,3,2] row_mask:0xf bank_mask:0xf
	v_add_f32_dpp v159, v159, v159 quad_perm:[1,0,3,2] row_mask:0xf bank_mask:0xf
	v_add_f32_dpp v156, v156, v156 quad_perm:[2,3,0,1] row_mask:0xf bank_mask:0xf
	v_add_f32_dpp v157, v157, v157 quad_perm:[2,3,0,1] row_mask:0xf bank_mask:0xf
	v_add_f32_dpp v158, v158, v158 quad_perm:[2,3,0,1] row_mask:0xf bank_mask:0xf
	v_add_f32_dpp v159, v159, v159 quad_perm:[2,3,0,1] row_mask:0xf bank_mask:0xf
	v_add_f32_dpp v156, v156, v156 row_half_mirror row_mask:0xf bank_mask:0xf
	v_add_f32_dpp v157, v157, v157 row_half_mirror row_mask:0xf bank_mask:0xf
	v_add_f32_dpp v158, v158, v158 row_half_mirror row_mask:0xf bank_mask:0xf
	v_add_f32_dpp v159, v159, v159 row_half_mirror row_mask:0xf bank_mask:0xf
	v_add_f32_dpp v156, v156, v156 row_mirror row_mask:0xf bank_mask:0xf
	v_add_f32_dpp v157, v157, v157 row_mirror row_mask:0xf bank_mask:0xf
	v_add_f32_dpp v158, v158, v158 row_mirror row_mask:0xf bank_mask:0xf
	v_add_f32_dpp v159, v159, v159 row_mirror row_mask:0xf bank_mask:0xf
	v_mov_b32_e32 v160, v156
	v_mov_b32_e32 v161, v157
	v_mov_b32_e32 v162, v158
	v_mov_b32_e32 v163, v159
	v_permlane16_swap_b32_e32 v156, v160
	v_permlane16_swap_b32_e32 v157, v161
	v_permlane16_swap_b32_e32 v158, v162
	v_permlane16_swap_b32_e32 v159, v163
	v_add_f32_e32 v156, v156, v160
	v_add_f32_e32 v157, v157, v161
	v_add_f32_e32 v158, v158, v162
	v_add_f32_e32 v159, v159, v163
	v_mov_b32_e32 v160, v156
	v_mov_b32_e32 v161, v157
	v_mov_b32_e32 v162, v158
	v_mov_b32_e32 v163, v159
	v_permlane32_swap_b32_e32 v156, v160
	v_permlane32_swap_b32_e32 v157, v161
	v_permlane32_swap_b32_e32 v158, v162
	v_permlane32_swap_b32_e32 v159, v163
	v_add_f32_e32 v156, v156, v160
	v_add_f32_e32 v157, v157, v161
	v_add_f32_e32 v158, v158, v162
	v_add_f32_e32 v159, v159, v163
	v_fmamk_f32 v156, v156, 0x3b800000, v194
	v_fmamk_f32 v157, v157, 0x3b800000, v194
	v_fmamk_f32 v158, v158, 0x3b800000, v194
	v_fmamk_f32 v159, v159, 0x3b800000, v194
	v_cmp_gt_f32_e32 vcc, s13, v156
	v_mul_f32_e32 v164, 0x4f800000, v156
	s_nop 0
	v_cndmask_b32_e32 v156, v156, v164, vcc
	v_sqrt_f32_e32 v164, v156
	s_nop 0
	v_add_u32_e32 v165, -1, v164
	v_fma_f32 v166, -v165, v164, v156
	v_cmp_ge_f32_e64 s[36:37], 0, v166
	v_add_u32_e32 v166, 1, v164
	s_nop 0
	v_cndmask_b32_e64 v165, v164, v165, s[36:37]
	v_fma_f32 v164, -v166, v164, v156
	v_cmp_lt_f32_e64 s[36:37], 0, v164
	s_nop 1
	v_cndmask_b32_e64 v164, v165, v166, s[36:37]
	v_mul_f32_e32 v165, 0x37800000, v164
	v_cndmask_b32_e32 v164, v164, v165, vcc
	v_cmp_class_f32_e32 vcc, v156, v196
	s_nop 1
	v_cndmask_b32_e32 v156, v164, v156, vcc
	v_div_scale_f32 v164, s[36:37], v156, v156, 1.0
	v_rcp_f32_e32 v165, v164
	s_nop 0
	v_fma_f32 v166, -v164, v165, 1.0
	v_fmac_f32_e32 v165, v166, v165
	v_div_scale_f32 v166, vcc, 1.0, v156, 1.0
	v_mul_f32_e32 v167, v166, v165
	v_fma_f32 v168, -v164, v167, v166
	v_fmac_f32_e32 v167, v168, v165
	v_fma_f32 v164, -v164, v167, v166
	v_div_fmas_f32 v164, v164, v165, v167
	v_div_fixup_f32 v156, v164, v156, 1.0
	v_cmp_gt_f32_e32 vcc, s13, v157
	v_mul_f32_e32 v164, 0x4f800000, v157
	s_nop 0
	v_cndmask_b32_e32 v157, v157, v164, vcc
	v_sqrt_f32_e32 v164, v157
	s_nop 0
	v_add_u32_e32 v165, -1, v164
	v_fma_f32 v166, -v165, v164, v157
	v_cmp_ge_f32_e64 s[36:37], 0, v166
	v_add_u32_e32 v166, 1, v164
	s_nop 0
	v_cndmask_b32_e64 v165, v164, v165, s[36:37]
	v_fma_f32 v164, -v166, v164, v157
	v_cmp_lt_f32_e64 s[36:37], 0, v164
	s_nop 1
	v_cndmask_b32_e64 v164, v165, v166, s[36:37]
	v_mul_f32_e32 v165, 0x37800000, v164
	v_cndmask_b32_e32 v164, v164, v165, vcc
	v_cmp_class_f32_e32 vcc, v157, v196
	s_nop 1
	v_cndmask_b32_e32 v157, v164, v157, vcc
	v_div_scale_f32 v164, s[36:37], v157, v157, 1.0
	v_rcp_f32_e32 v165, v164
	s_nop 0
	v_fma_f32 v166, -v164, v165, 1.0
	v_fmac_f32_e32 v165, v166, v165
	v_div_scale_f32 v166, vcc, 1.0, v157, 1.0
	v_mul_f32_e32 v167, v166, v165
	v_fma_f32 v168, -v164, v167, v166
	v_fmac_f32_e32 v167, v168, v165
	v_fma_f32 v164, -v164, v167, v166
	v_div_fmas_f32 v164, v164, v165, v167
	v_div_fixup_f32 v157, v164, v157, 1.0
	v_cmp_gt_f32_e32 vcc, s13, v158
	v_mul_f32_e32 v164, 0x4f800000, v158
	s_nop 0
	v_cndmask_b32_e32 v158, v158, v164, vcc
	v_sqrt_f32_e32 v164, v158
	s_nop 0
	v_add_u32_e32 v165, -1, v164
	v_fma_f32 v166, -v165, v164, v158
	v_cmp_ge_f32_e64 s[36:37], 0, v166
	v_add_u32_e32 v166, 1, v164
	s_nop 0
	v_cndmask_b32_e64 v165, v164, v165, s[36:37]
	v_fma_f32 v164, -v166, v164, v158
	v_cmp_lt_f32_e64 s[36:37], 0, v164
	s_nop 1
	v_cndmask_b32_e64 v164, v165, v166, s[36:37]
	v_mul_f32_e32 v165, 0x37800000, v164
	v_cndmask_b32_e32 v164, v164, v165, vcc
	v_cmp_class_f32_e32 vcc, v158, v196
	s_nop 1
	v_cndmask_b32_e32 v158, v164, v158, vcc
	v_div_scale_f32 v164, s[36:37], v158, v158, 1.0
	v_rcp_f32_e32 v165, v164
	s_nop 0
	v_fma_f32 v166, -v164, v165, 1.0
	v_fmac_f32_e32 v165, v166, v165
	v_div_scale_f32 v166, vcc, 1.0, v158, 1.0
	v_mul_f32_e32 v167, v166, v165
	v_fma_f32 v168, -v164, v167, v166
	v_fmac_f32_e32 v167, v168, v165
	v_fma_f32 v164, -v164, v167, v166
	v_div_fmas_f32 v164, v164, v165, v167
	v_div_fixup_f32 v158, v164, v158, 1.0
	v_cmp_gt_f32_e32 vcc, s13, v159
	v_mul_f32_e32 v164, 0x4f800000, v159
	s_nop 0
	v_cndmask_b32_e32 v159, v159, v164, vcc
	v_sqrt_f32_e32 v164, v159
	s_nop 0
	v_add_u32_e32 v165, -1, v164
	v_fma_f32 v166, -v165, v164, v159
	v_cmp_ge_f32_e64 s[36:37], 0, v166
	v_add_u32_e32 v166, 1, v164
	s_nop 0
	v_cndmask_b32_e64 v165, v164, v165, s[36:37]
	v_fma_f32 v164, -v166, v164, v159
	v_cmp_lt_f32_e64 s[36:37], 0, v164
	s_nop 1
	v_cndmask_b32_e64 v164, v165, v166, s[36:37]
	v_mul_f32_e32 v165, 0x37800000, v164
	v_cndmask_b32_e32 v164, v164, v165, vcc
	v_cmp_class_f32_e32 vcc, v159, v196
	s_nop 1
	v_cndmask_b32_e32 v159, v164, v159, vcc
	v_div_scale_f32 v164, s[36:37], v159, v159, 1.0
	v_rcp_f32_e32 v165, v164
	s_nop 0
	v_fma_f32 v166, -v164, v165, 1.0
	v_fmac_f32_e32 v165, v166, v165
	v_div_scale_f32 v166, vcc, 1.0, v159, 1.0
	v_mul_f32_e32 v167, v166, v165
	v_fma_f32 v168, -v164, v167, v166
	v_fmac_f32_e32 v167, v168, v165
	v_fma_f32 v164, -v164, v167, v166
	v_div_fmas_f32 v164, v164, v165, v167
	v_div_fixup_f32 v159, v164, v159, 1.0
	v_mul_f32_e32 v128, v128, v156
	v_mul_f32_e32 v129, v129, v156
	v_mul_f32_e32 v130, v130, v156
	v_mul_f32_e32 v131, v131, v156
	v_mul_f32_e32 v132, v132, v157
	v_mul_f32_e32 v133, v133, v157
	v_mul_f32_e32 v134, v134, v157
	v_mul_f32_e32 v135, v135, v157
	v_mul_f32_e32 v136, v136, v158
	v_mul_f32_e32 v137, v137, v158
	v_mul_f32_e32 v138, v138, v158
	v_mul_f32_e32 v139, v139, v158
	v_mul_f32_e32 v140, v140, v159
	v_mul_f32_e32 v141, v141, v159
	v_mul_f32_e32 v142, v142, v159
	v_mul_f32_e32 v143, v143, v159
	v_mul_f32_e32 v128, v10, v128
	v_mul_f32_e32 v129, v11, v129
	v_mul_f32_e32 v130, v12, v130
	v_mul_f32_e32 v131, v13, v131
	v_mul_f32_e32 v132, v10, v132
	v_mul_f32_e32 v133, v11, v133
	v_mul_f32_e32 v134, v12, v134
	v_mul_f32_e32 v135, v13, v135
	v_mul_f32_e32 v136, v10, v136
	v_mul_f32_e32 v137, v11, v137
	v_mul_f32_e32 v138, v12, v138
	v_mul_f32_e32 v139, v13, v139
	v_mul_f32_e32 v140, v10, v140
	v_mul_f32_e32 v141, v11, v141
	v_mul_f32_e32 v142, v12, v142
	v_mul_f32_e32 v143, v13, v143
	v_cvt_pk_bf16_f32 v172, v128, v132
	v_cvt_pk_bf16_f32 v173, v136, v140
	v_cvt_pk_bf16_f32 v174, v129, v133
	v_cvt_pk_bf16_f32 v175, v137, v141
	v_cvt_pk_bf16_f32 v146, v130, v134
	v_cvt_pk_bf16_f32 v147, v138, v142
	v_cvt_pk_bf16_f32 v154, v131, v135
	v_cvt_pk_bf16_f32 v155, v139, v143
	ds_write_b64 v4, v[172:173] offset:0
	ds_write_b64 v4, v[174:175] offset:272
	ds_write_b64 v4, v[146:147] offset:544
	ds_write_b64 v4, v[154:155] offset:816
	v_lshlrev_b32_e32 v128, 16, v40
	v_and_b32_e32 v129, 0xffff0000, v40
	v_lshlrev_b32_e32 v130, 16, v41
	v_and_b32_e32 v131, 0xffff0000, v41
	v_lshlrev_b32_e32 v132, 16, v42
	v_and_b32_e32 v133, 0xffff0000, v42
	v_lshlrev_b32_e32 v134, 16, v43
	v_and_b32_e32 v135, 0xffff0000, v43
	v_lshlrev_b32_e32 v136, 16, v44
	v_and_b32_e32 v137, 0xffff0000, v44
	v_lshlrev_b32_e32 v138, 16, v45
	v_and_b32_e32 v139, 0xffff0000, v45
	v_lshlrev_b32_e32 v140, 16, v46
	v_and_b32_e32 v141, 0xffff0000, v46
	v_lshlrev_b32_e32 v142, 16, v47
	v_and_b32_e32 v143, 0xffff0000, v47
	v_add_f32_e32 v156, v128, v129
	v_add_f32_e32 v160, v130, v131
	v_add_f32_e32 v157, v132, v133
	v_add_f32_e32 v161, v134, v135
	v_add_f32_e32 v158, v136, v137
	v_add_f32_e32 v162, v138, v139
	v_add_f32_e32 v159, v140, v141
	v_add_f32_e32 v163, v142, v143
	v_add_f32_e32 v156, v156, v160
	v_add_f32_e32 v157, v157, v161
	v_add_f32_e32 v158, v158, v162
	v_add_f32_e32 v159, v159, v163
	v_add_f32_dpp v156, v156, v156 quad_perm:[1,0,3,2] row_mask:0xf bank_mask:0xf
	v_add_f32_dpp v157, v157, v157 quad_perm:[1,0,3,2] row_mask:0xf bank_mask:0xf
	v_add_f32_dpp v158, v158, v158 quad_perm:[1,0,3,2] row_mask:0xf bank_mask:0xf
	v_add_f32_dpp v159, v159, v159 quad_perm:[1,0,3,2] row_mask:0xf bank_mask:0xf
	v_add_f32_dpp v156, v156, v156 quad_perm:[2,3,0,1] row_mask:0xf bank_mask:0xf
	v_add_f32_dpp v157, v157, v157 quad_perm:[2,3,0,1] row_mask:0xf bank_mask:0xf
	v_add_f32_dpp v158, v158, v158 quad_perm:[2,3,0,1] row_mask:0xf bank_mask:0xf
	v_add_f32_dpp v159, v159, v159 quad_perm:[2,3,0,1] row_mask:0xf bank_mask:0xf
	v_add_f32_dpp v156, v156, v156 row_half_mirror row_mask:0xf bank_mask:0xf
	v_add_f32_dpp v157, v157, v157 row_half_mirror row_mask:0xf bank_mask:0xf
	v_add_f32_dpp v158, v158, v158 row_half_mirror row_mask:0xf bank_mask:0xf
	v_add_f32_dpp v159, v159, v159 row_half_mirror row_mask:0xf bank_mask:0xf
	v_add_f32_dpp v156, v156, v156 row_mirror row_mask:0xf bank_mask:0xf
	v_add_f32_dpp v157, v157, v157 row_mirror row_mask:0xf bank_mask:0xf
	v_add_f32_dpp v158, v158, v158 row_mirror row_mask:0xf bank_mask:0xf
	v_add_f32_dpp v159, v159, v159 row_mirror row_mask:0xf bank_mask:0xf
	v_mov_b32_e32 v160, v156
	v_mov_b32_e32 v161, v157
	v_mov_b32_e32 v162, v158
	v_mov_b32_e32 v163, v159
	v_permlane16_swap_b32_e32 v156, v160
	v_permlane16_swap_b32_e32 v157, v161
	v_permlane16_swap_b32_e32 v158, v162
	v_permlane16_swap_b32_e32 v159, v163
	v_add_f32_e32 v156, v156, v160
	v_add_f32_e32 v157, v157, v161
	v_add_f32_e32 v158, v158, v162
	v_add_f32_e32 v159, v159, v163
	v_mov_b32_e32 v160, v156
	v_mov_b32_e32 v161, v157
	v_mov_b32_e32 v162, v158
	v_mov_b32_e32 v163, v159
	v_permlane32_swap_b32_e32 v156, v160
	v_permlane32_swap_b32_e32 v157, v161
	v_permlane32_swap_b32_e32 v158, v162
	v_permlane32_swap_b32_e32 v159, v163
	v_add_f32_e32 v156, v156, v160
	v_add_f32_e32 v157, v157, v161
	v_add_f32_e32 v158, v158, v162
	v_add_f32_e32 v159, v159, v163
	v_fmac_f32_e32 v129, 0xbb800000, v156
	v_fmac_f32_e32 v131, 0xbb800000, v156
	v_fmac_f32_e32 v130, 0xbb800000, v156
	v_fmac_f32_e32 v128, 0xbb800000, v156
	v_fmac_f32_e32 v133, 0xbb800000, v157
	v_fmac_f32_e32 v135, 0xbb800000, v157
	v_fmac_f32_e32 v134, 0xbb800000, v157
	v_fmac_f32_e32 v132, 0xbb800000, v157
	v_fmac_f32_e32 v137, 0xbb800000, v158
	v_fmac_f32_e32 v139, 0xbb800000, v158
	v_fmac_f32_e32 v138, 0xbb800000, v158
	v_fmac_f32_e32 v136, 0xbb800000, v158
	v_fmac_f32_e32 v141, 0xbb800000, v159
	v_fmac_f32_e32 v143, 0xbb800000, v159
	v_fmac_f32_e32 v142, 0xbb800000, v159
	v_fmac_f32_e32 v140, 0xbb800000, v159
	v_mul_f32_e32 v156, v128, v128
	v_mul_f32_e32 v160, v129, v129
	v_mul_f32_e32 v164, v130, v130
	v_mul_f32_e32 v168, v131, v131
	v_mul_f32_e32 v157, v132, v132
	v_mul_f32_e32 v161, v133, v133
	v_mul_f32_e32 v165, v134, v134
	v_mul_f32_e32 v169, v135, v135
	v_mul_f32_e32 v158, v136, v136
	v_mul_f32_e32 v162, v137, v137
	v_mul_f32_e32 v166, v138, v138
	v_mul_f32_e32 v170, v139, v139
	v_mul_f32_e32 v159, v140, v140
	v_mul_f32_e32 v163, v141, v141
	v_mul_f32_e32 v167, v142, v142
	v_mul_f32_e32 v171, v143, v143
	v_add_f32_e32 v156, v160, v156
	v_add_f32_e32 v164, v164, v168
	v_add_f32_e32 v157, v161, v157
	v_add_f32_e32 v165, v165, v169
	v_add_f32_e32 v158, v162, v158
	v_add_f32_e32 v166, v166, v170
	v_add_f32_e32 v159, v163, v159
	v_add_f32_e32 v167, v167, v171
	v_add_f32_e32 v156, v156, v164
	v_add_f32_e32 v157, v157, v165
	v_add_f32_e32 v158, v158, v166
	v_add_f32_e32 v159, v159, v167
	v_add_f32_dpp v156, v156, v156 quad_perm:[1,0,3,2] row_mask:0xf bank_mask:0xf
	v_add_f32_dpp v157, v157, v157 quad_perm:[1,0,3,2] row_mask:0xf bank_mask:0xf
	v_add_f32_dpp v158, v158, v158 quad_perm:[1,0,3,2] row_mask:0xf bank_mask:0xf
	v_add_f32_dpp v159, v159, v159 quad_perm:[1,0,3,2] row_mask:0xf bank_mask:0xf
	v_add_f32_dpp v156, v156, v156 quad_perm:[2,3,0,1] row_mask:0xf bank_mask:0xf
	v_add_f32_dpp v157, v157, v157 quad_perm:[2,3,0,1] row_mask:0xf bank_mask:0xf
	v_add_f32_dpp v158, v158, v158 quad_perm:[2,3,0,1] row_mask:0xf bank_mask:0xf
	v_add_f32_dpp v159, v159, v159 quad_perm:[2,3,0,1] row_mask:0xf bank_mask:0xf
	v_add_f32_dpp v156, v156, v156 row_half_mirror row_mask:0xf bank_mask:0xf
	v_add_f32_dpp v157, v157, v157 row_half_mirror row_mask:0xf bank_mask:0xf
	v_add_f32_dpp v158, v158, v158 row_half_mirror row_mask:0xf bank_mask:0xf
	v_add_f32_dpp v159, v159, v159 row_half_mirror row_mask:0xf bank_mask:0xf
	v_add_f32_dpp v156, v156, v156 row_mirror row_mask:0xf bank_mask:0xf
	v_add_f32_dpp v157, v157, v157 row_mirror row_mask:0xf bank_mask:0xf
	v_add_f32_dpp v158, v158, v158 row_mirror row_mask:0xf bank_mask:0xf
	v_add_f32_dpp v159, v159, v159 row_mirror row_mask:0xf bank_mask:0xf
	v_mov_b32_e32 v160, v156
	v_mov_b32_e32 v161, v157
	v_mov_b32_e32 v162, v158
	v_mov_b32_e32 v163, v159
	v_permlane16_swap_b32_e32 v156, v160
	v_permlane16_swap_b32_e32 v157, v161
	v_permlane16_swap_b32_e32 v158, v162
	v_permlane16_swap_b32_e32 v159, v163
	v_add_f32_e32 v156, v156, v160
	v_add_f32_e32 v157, v157, v161
	v_add_f32_e32 v158, v158, v162
	v_add_f32_e32 v159, v159, v163
	v_mov_b32_e32 v160, v156
	v_mov_b32_e32 v161, v157
	v_mov_b32_e32 v162, v158
	v_mov_b32_e32 v163, v159
	v_permlane32_swap_b32_e32 v156, v160
	v_permlane32_swap_b32_e32 v157, v161
	v_permlane32_swap_b32_e32 v158, v162
	v_permlane32_swap_b32_e32 v159, v163
	v_add_f32_e32 v156, v156, v160
	v_add_f32_e32 v157, v157, v161
	v_add_f32_e32 v158, v158, v162
	v_add_f32_e32 v159, v159, v163
	v_fmamk_f32 v156, v156, 0x3b800000, v194
	v_fmamk_f32 v157, v157, 0x3b800000, v194
	v_fmamk_f32 v158, v158, 0x3b800000, v194
	v_fmamk_f32 v159, v159, 0x3b800000, v194
	v_cmp_gt_f32_e32 vcc, s13, v156
	v_mul_f32_e32 v164, 0x4f800000, v156
	s_nop 0
	v_cndmask_b32_e32 v156, v156, v164, vcc
	v_sqrt_f32_e32 v164, v156
	s_nop 0
	v_add_u32_e32 v165, -1, v164
	v_fma_f32 v166, -v165, v164, v156
	v_cmp_ge_f32_e64 s[36:37], 0, v166
	v_add_u32_e32 v166, 1, v164
	s_nop 0
	v_cndmask_b32_e64 v165, v164, v165, s[36:37]
	v_fma_f32 v164, -v166, v164, v156
	v_cmp_lt_f32_e64 s[36:37], 0, v164
	s_nop 1
	v_cndmask_b32_e64 v164, v165, v166, s[36:37]
	v_mul_f32_e32 v165, 0x37800000, v164
	v_cndmask_b32_e32 v164, v164, v165, vcc
	v_cmp_class_f32_e32 vcc, v156, v196
	s_nop 1
	v_cndmask_b32_e32 v156, v164, v156, vcc
	v_div_scale_f32 v164, s[36:37], v156, v156, 1.0
	v_rcp_f32_e32 v165, v164
	s_nop 0
	v_fma_f32 v166, -v164, v165, 1.0
	v_fmac_f32_e32 v165, v166, v165
	v_div_scale_f32 v166, vcc, 1.0, v156, 1.0
	v_mul_f32_e32 v167, v166, v165
	v_fma_f32 v168, -v164, v167, v166
	v_fmac_f32_e32 v167, v168, v165
	v_fma_f32 v164, -v164, v167, v166
	v_div_fmas_f32 v164, v164, v165, v167
	v_div_fixup_f32 v156, v164, v156, 1.0
	v_cmp_gt_f32_e32 vcc, s13, v157
	v_mul_f32_e32 v164, 0x4f800000, v157
	s_nop 0
	v_cndmask_b32_e32 v157, v157, v164, vcc
	v_sqrt_f32_e32 v164, v157
	s_nop 0
	v_add_u32_e32 v165, -1, v164
	v_fma_f32 v166, -v165, v164, v157
	v_cmp_ge_f32_e64 s[36:37], 0, v166
	v_add_u32_e32 v166, 1, v164
	s_nop 0
	v_cndmask_b32_e64 v165, v164, v165, s[36:37]
	v_fma_f32 v164, -v166, v164, v157
	v_cmp_lt_f32_e64 s[36:37], 0, v164
	s_nop 1
	v_cndmask_b32_e64 v164, v165, v166, s[36:37]
	v_mul_f32_e32 v165, 0x37800000, v164
	v_cndmask_b32_e32 v164, v164, v165, vcc
	v_cmp_class_f32_e32 vcc, v157, v196
	s_nop 1
	v_cndmask_b32_e32 v157, v164, v157, vcc
	v_div_scale_f32 v164, s[36:37], v157, v157, 1.0
	v_rcp_f32_e32 v165, v164
	s_nop 0
	v_fma_f32 v166, -v164, v165, 1.0
	v_fmac_f32_e32 v165, v166, v165
	v_div_scale_f32 v166, vcc, 1.0, v157, 1.0
	v_mul_f32_e32 v167, v166, v165
	v_fma_f32 v168, -v164, v167, v166
	v_fmac_f32_e32 v167, v168, v165
	v_fma_f32 v164, -v164, v167, v166
	v_div_fmas_f32 v164, v164, v165, v167
	v_div_fixup_f32 v157, v164, v157, 1.0
	v_cmp_gt_f32_e32 vcc, s13, v158
	v_mul_f32_e32 v164, 0x4f800000, v158
	s_nop 0
	v_cndmask_b32_e32 v158, v158, v164, vcc
	v_sqrt_f32_e32 v164, v158
	s_nop 0
	v_add_u32_e32 v165, -1, v164
	v_fma_f32 v166, -v165, v164, v158
	v_cmp_ge_f32_e64 s[36:37], 0, v166
	v_add_u32_e32 v166, 1, v164
	s_nop 0
	v_cndmask_b32_e64 v165, v164, v165, s[36:37]
	v_fma_f32 v164, -v166, v164, v158
	v_cmp_lt_f32_e64 s[36:37], 0, v164
	s_nop 1
	v_cndmask_b32_e64 v164, v165, v166, s[36:37]
	v_mul_f32_e32 v165, 0x37800000, v164
	v_cndmask_b32_e32 v164, v164, v165, vcc
	v_cmp_class_f32_e32 vcc, v158, v196
	s_nop 1
	v_cndmask_b32_e32 v158, v164, v158, vcc
	v_div_scale_f32 v164, s[36:37], v158, v158, 1.0
	v_rcp_f32_e32 v165, v164
	s_nop 0
	v_fma_f32 v166, -v164, v165, 1.0
	v_fmac_f32_e32 v165, v166, v165
	v_div_scale_f32 v166, vcc, 1.0, v158, 1.0
	v_mul_f32_e32 v167, v166, v165
	v_fma_f32 v168, -v164, v167, v166
	v_fmac_f32_e32 v167, v168, v165
	v_fma_f32 v164, -v164, v167, v166
	v_div_fmas_f32 v164, v164, v165, v167
	v_div_fixup_f32 v158, v164, v158, 1.0
	v_cmp_gt_f32_e32 vcc, s13, v159
	v_mul_f32_e32 v164, 0x4f800000, v159
	s_nop 0
	v_cndmask_b32_e32 v159, v159, v164, vcc
	v_sqrt_f32_e32 v164, v159
	s_nop 0
	v_add_u32_e32 v165, -1, v164
	v_fma_f32 v166, -v165, v164, v159
	v_cmp_ge_f32_e64 s[36:37], 0, v166
	v_add_u32_e32 v166, 1, v164
	s_nop 0
	v_cndmask_b32_e64 v165, v164, v165, s[36:37]
	v_fma_f32 v164, -v166, v164, v159
	v_cmp_lt_f32_e64 s[36:37], 0, v164
	s_nop 1
	v_cndmask_b32_e64 v164, v165, v166, s[36:37]
	v_mul_f32_e32 v165, 0x37800000, v164
	v_cndmask_b32_e32 v164, v164, v165, vcc
	v_cmp_class_f32_e32 vcc, v159, v196
	s_nop 1
	v_cndmask_b32_e32 v159, v164, v159, vcc
	v_div_scale_f32 v164, s[36:37], v159, v159, 1.0
	v_rcp_f32_e32 v165, v164
	s_nop 0
	v_fma_f32 v166, -v164, v165, 1.0
	v_fmac_f32_e32 v165, v166, v165
	v_div_scale_f32 v166, vcc, 1.0, v159, 1.0
	v_mul_f32_e32 v167, v166, v165
	v_fma_f32 v168, -v164, v167, v166
	v_fmac_f32_e32 v167, v168, v165
	v_fma_f32 v164, -v164, v167, v166
	v_div_fmas_f32 v164, v164, v165, v167
	v_div_fixup_f32 v159, v164, v159, 1.0
	v_mul_f32_e32 v128, v128, v156
	v_mul_f32_e32 v129, v129, v156
	v_mul_f32_e32 v130, v130, v156
	v_mul_f32_e32 v131, v131, v156
	v_mul_f32_e32 v132, v132, v157
	v_mul_f32_e32 v133, v133, v157
	v_mul_f32_e32 v134, v134, v157
	v_mul_f32_e32 v135, v135, v157
	v_mul_f32_e32 v136, v136, v158
	v_mul_f32_e32 v137, v137, v158
	v_mul_f32_e32 v138, v138, v158
	v_mul_f32_e32 v139, v139, v158
	v_mul_f32_e32 v140, v140, v159
	v_mul_f32_e32 v141, v141, v159
	v_mul_f32_e32 v142, v142, v159
	v_mul_f32_e32 v143, v143, v159
	v_mul_f32_e32 v128, v10, v128
	v_mul_f32_e32 v129, v11, v129
	v_mul_f32_e32 v130, v12, v130
	v_mul_f32_e32 v131, v13, v131
	v_mul_f32_e32 v132, v10, v132
	v_mul_f32_e32 v133, v11, v133
	v_mul_f32_e32 v134, v12, v134
	v_mul_f32_e32 v135, v13, v135
	v_mul_f32_e32 v136, v10, v136
	v_mul_f32_e32 v137, v11, v137
	v_mul_f32_e32 v138, v12, v138
	v_mul_f32_e32 v139, v13, v139
	v_mul_f32_e32 v140, v10, v140
	v_mul_f32_e32 v141, v11, v141
	v_mul_f32_e32 v142, v12, v142
	v_mul_f32_e32 v143, v13, v143
	v_cvt_pk_bf16_f32 v172, v128, v132
	v_cvt_pk_bf16_f32 v173, v136, v140
	v_cvt_pk_bf16_f32 v174, v129, v133
	v_cvt_pk_bf16_f32 v175, v137, v141
	v_cvt_pk_bf16_f32 v146, v130, v134
	v_cvt_pk_bf16_f32 v147, v138, v142
	v_cvt_pk_bf16_f32 v154, v131, v135
	v_cvt_pk_bf16_f32 v155, v139, v143
	ds_write_b64 v4, v[172:173] offset:8
	ds_write_b64 v4, v[174:175] offset:280
	ds_write_b64 v4, v[146:147] offset:552
	ds_write_b64 v4, v[154:155] offset:824
	v_lshlrev_b32_e32 v128, 16, v48
	v_and_b32_e32 v129, 0xffff0000, v48
	v_lshlrev_b32_e32 v130, 16, v49
	v_and_b32_e32 v131, 0xffff0000, v49
	v_lshlrev_b32_e32 v132, 16, v50
	v_and_b32_e32 v133, 0xffff0000, v50
	v_lshlrev_b32_e32 v134, 16, v51
	v_and_b32_e32 v135, 0xffff0000, v51
	v_lshlrev_b32_e32 v136, 16, v52
	v_and_b32_e32 v137, 0xffff0000, v52
	v_lshlrev_b32_e32 v138, 16, v53
	v_and_b32_e32 v139, 0xffff0000, v53
	v_lshlrev_b32_e32 v140, 16, v54
	v_and_b32_e32 v141, 0xffff0000, v54
	v_lshlrev_b32_e32 v142, 16, v55
	v_and_b32_e32 v143, 0xffff0000, v55
	v_add_f32_e32 v156, v128, v129
	v_add_f32_e32 v160, v130, v131
	v_add_f32_e32 v157, v132, v133
	v_add_f32_e32 v161, v134, v135
	v_add_f32_e32 v158, v136, v137
	v_add_f32_e32 v162, v138, v139
	v_add_f32_e32 v159, v140, v141
	v_add_f32_e32 v163, v142, v143
	v_add_f32_e32 v156, v156, v160
	v_add_f32_e32 v157, v157, v161
	v_add_f32_e32 v158, v158, v162
	v_add_f32_e32 v159, v159, v163
	v_add_f32_dpp v156, v156, v156 quad_perm:[1,0,3,2] row_mask:0xf bank_mask:0xf
	v_add_f32_dpp v157, v157, v157 quad_perm:[1,0,3,2] row_mask:0xf bank_mask:0xf
	v_add_f32_dpp v158, v158, v158 quad_perm:[1,0,3,2] row_mask:0xf bank_mask:0xf
	v_add_f32_dpp v159, v159, v159 quad_perm:[1,0,3,2] row_mask:0xf bank_mask:0xf
	v_add_f32_dpp v156, v156, v156 quad_perm:[2,3,0,1] row_mask:0xf bank_mask:0xf
	v_add_f32_dpp v157, v157, v157 quad_perm:[2,3,0,1] row_mask:0xf bank_mask:0xf
	v_add_f32_dpp v158, v158, v158 quad_perm:[2,3,0,1] row_mask:0xf bank_mask:0xf
	v_add_f32_dpp v159, v159, v159 quad_perm:[2,3,0,1] row_mask:0xf bank_mask:0xf
	v_add_f32_dpp v156, v156, v156 row_half_mirror row_mask:0xf bank_mask:0xf
	v_add_f32_dpp v157, v157, v157 row_half_mirror row_mask:0xf bank_mask:0xf
	v_add_f32_dpp v158, v158, v158 row_half_mirror row_mask:0xf bank_mask:0xf
	v_add_f32_dpp v159, v159, v159 row_half_mirror row_mask:0xf bank_mask:0xf
	v_add_f32_dpp v156, v156, v156 row_mirror row_mask:0xf bank_mask:0xf
	v_add_f32_dpp v157, v157, v157 row_mirror row_mask:0xf bank_mask:0xf
	v_add_f32_dpp v158, v158, v158 row_mirror row_mask:0xf bank_mask:0xf
	v_add_f32_dpp v159, v159, v159 row_mirror row_mask:0xf bank_mask:0xf
	v_mov_b32_e32 v160, v156
	v_mov_b32_e32 v161, v157
	v_mov_b32_e32 v162, v158
	v_mov_b32_e32 v163, v159
	v_permlane16_swap_b32_e32 v156, v160
	v_permlane16_swap_b32_e32 v157, v161
	v_permlane16_swap_b32_e32 v158, v162
	v_permlane16_swap_b32_e32 v159, v163
	v_add_f32_e32 v156, v156, v160
	v_add_f32_e32 v157, v157, v161
	v_add_f32_e32 v158, v158, v162
	v_add_f32_e32 v159, v159, v163
	v_mov_b32_e32 v160, v156
	v_mov_b32_e32 v161, v157
	v_mov_b32_e32 v162, v158
	v_mov_b32_e32 v163, v159
	v_permlane32_swap_b32_e32 v156, v160
	v_permlane32_swap_b32_e32 v157, v161
	v_permlane32_swap_b32_e32 v158, v162
	v_permlane32_swap_b32_e32 v159, v163
	v_add_f32_e32 v156, v156, v160
	v_add_f32_e32 v157, v157, v161
	v_add_f32_e32 v158, v158, v162
	v_add_f32_e32 v159, v159, v163
	v_fmac_f32_e32 v129, 0xbb800000, v156
	v_fmac_f32_e32 v131, 0xbb800000, v156
	v_fmac_f32_e32 v130, 0xbb800000, v156
	v_fmac_f32_e32 v128, 0xbb800000, v156
	v_fmac_f32_e32 v133, 0xbb800000, v157
	v_fmac_f32_e32 v135, 0xbb800000, v157
	v_fmac_f32_e32 v134, 0xbb800000, v157
	v_fmac_f32_e32 v132, 0xbb800000, v157
	v_fmac_f32_e32 v137, 0xbb800000, v158
	v_fmac_f32_e32 v139, 0xbb800000, v158
	v_fmac_f32_e32 v138, 0xbb800000, v158
	v_fmac_f32_e32 v136, 0xbb800000, v158
	v_fmac_f32_e32 v141, 0xbb800000, v159
	v_fmac_f32_e32 v143, 0xbb800000, v159
	v_fmac_f32_e32 v142, 0xbb800000, v159
	v_fmac_f32_e32 v140, 0xbb800000, v159
	v_mul_f32_e32 v156, v128, v128
	v_mul_f32_e32 v160, v129, v129
	v_mul_f32_e32 v164, v130, v130
	v_mul_f32_e32 v168, v131, v131
	v_mul_f32_e32 v157, v132, v132
	v_mul_f32_e32 v161, v133, v133
	v_mul_f32_e32 v165, v134, v134
	v_mul_f32_e32 v169, v135, v135
	v_mul_f32_e32 v158, v136, v136
	v_mul_f32_e32 v162, v137, v137
	v_mul_f32_e32 v166, v138, v138
	v_mul_f32_e32 v170, v139, v139
	v_mul_f32_e32 v159, v140, v140
	v_mul_f32_e32 v163, v141, v141
	v_mul_f32_e32 v167, v142, v142
	v_mul_f32_e32 v171, v143, v143
	v_add_f32_e32 v156, v160, v156
	v_add_f32_e32 v164, v164, v168
	v_add_f32_e32 v157, v161, v157
	v_add_f32_e32 v165, v165, v169
	v_add_f32_e32 v158, v162, v158
	v_add_f32_e32 v166, v166, v170
	v_add_f32_e32 v159, v163, v159
	v_add_f32_e32 v167, v167, v171
	v_add_f32_e32 v156, v156, v164
	v_add_f32_e32 v157, v157, v165
	v_add_f32_e32 v158, v158, v166
	v_add_f32_e32 v159, v159, v167
	v_add_f32_dpp v156, v156, v156 quad_perm:[1,0,3,2] row_mask:0xf bank_mask:0xf
	v_add_f32_dpp v157, v157, v157 quad_perm:[1,0,3,2] row_mask:0xf bank_mask:0xf
	v_add_f32_dpp v158, v158, v158 quad_perm:[1,0,3,2] row_mask:0xf bank_mask:0xf
	v_add_f32_dpp v159, v159, v159 quad_perm:[1,0,3,2] row_mask:0xf bank_mask:0xf
	v_add_f32_dpp v156, v156, v156 quad_perm:[2,3,0,1] row_mask:0xf bank_mask:0xf
	v_add_f32_dpp v157, v157, v157 quad_perm:[2,3,0,1] row_mask:0xf bank_mask:0xf
	v_add_f32_dpp v158, v158, v158 quad_perm:[2,3,0,1] row_mask:0xf bank_mask:0xf
	v_add_f32_dpp v159, v159, v159 quad_perm:[2,3,0,1] row_mask:0xf bank_mask:0xf
	v_add_f32_dpp v156, v156, v156 row_half_mirror row_mask:0xf bank_mask:0xf
	v_add_f32_dpp v157, v157, v157 row_half_mirror row_mask:0xf bank_mask:0xf
	v_add_f32_dpp v158, v158, v158 row_half_mirror row_mask:0xf bank_mask:0xf
	v_add_f32_dpp v159, v159, v159 row_half_mirror row_mask:0xf bank_mask:0xf
	v_add_f32_dpp v156, v156, v156 row_mirror row_mask:0xf bank_mask:0xf
	v_add_f32_dpp v157, v157, v157 row_mirror row_mask:0xf bank_mask:0xf
	v_add_f32_dpp v158, v158, v158 row_mirror row_mask:0xf bank_mask:0xf
	v_add_f32_dpp v159, v159, v159 row_mirror row_mask:0xf bank_mask:0xf
	v_mov_b32_e32 v160, v156
	v_mov_b32_e32 v161, v157
	v_mov_b32_e32 v162, v158
	v_mov_b32_e32 v163, v159
	v_permlane16_swap_b32_e32 v156, v160
	v_permlane16_swap_b32_e32 v157, v161
	v_permlane16_swap_b32_e32 v158, v162
	v_permlane16_swap_b32_e32 v159, v163
	v_add_f32_e32 v156, v156, v160
	v_add_f32_e32 v157, v157, v161
	v_add_f32_e32 v158, v158, v162
	v_add_f32_e32 v159, v159, v163
	v_mov_b32_e32 v160, v156
	v_mov_b32_e32 v161, v157
	v_mov_b32_e32 v162, v158
	v_mov_b32_e32 v163, v159
	v_permlane32_swap_b32_e32 v156, v160
	v_permlane32_swap_b32_e32 v157, v161
	v_permlane32_swap_b32_e32 v158, v162
	v_permlane32_swap_b32_e32 v159, v163
	v_add_f32_e32 v156, v156, v160
	v_add_f32_e32 v157, v157, v161
	v_add_f32_e32 v158, v158, v162
	v_add_f32_e32 v159, v159, v163
	v_fmamk_f32 v156, v156, 0x3b800000, v194
	v_fmamk_f32 v157, v157, 0x3b800000, v194
	v_fmamk_f32 v158, v158, 0x3b800000, v194
	v_fmamk_f32 v159, v159, 0x3b800000, v194
	v_cmp_gt_f32_e32 vcc, s13, v156
	v_mul_f32_e32 v164, 0x4f800000, v156
	s_nop 0
	v_cndmask_b32_e32 v156, v156, v164, vcc
	v_sqrt_f32_e32 v164, v156
	s_nop 0
	v_add_u32_e32 v165, -1, v164
	v_fma_f32 v166, -v165, v164, v156
	v_cmp_ge_f32_e64 s[36:37], 0, v166
	v_add_u32_e32 v166, 1, v164
	s_nop 0
	v_cndmask_b32_e64 v165, v164, v165, s[36:37]
	v_fma_f32 v164, -v166, v164, v156
	v_cmp_lt_f32_e64 s[36:37], 0, v164
	s_nop 1
	v_cndmask_b32_e64 v164, v165, v166, s[36:37]
	v_mul_f32_e32 v165, 0x37800000, v164
	v_cndmask_b32_e32 v164, v164, v165, vcc
	v_cmp_class_f32_e32 vcc, v156, v196
	s_nop 1
	v_cndmask_b32_e32 v156, v164, v156, vcc
	v_div_scale_f32 v164, s[36:37], v156, v156, 1.0
	v_rcp_f32_e32 v165, v164
	s_nop 0
	v_fma_f32 v166, -v164, v165, 1.0
	v_fmac_f32_e32 v165, v166, v165
	v_div_scale_f32 v166, vcc, 1.0, v156, 1.0
	v_mul_f32_e32 v167, v166, v165
	v_fma_f32 v168, -v164, v167, v166
	v_fmac_f32_e32 v167, v168, v165
	v_fma_f32 v164, -v164, v167, v166
	v_div_fmas_f32 v164, v164, v165, v167
	v_div_fixup_f32 v156, v164, v156, 1.0
	v_cmp_gt_f32_e32 vcc, s13, v157
	v_mul_f32_e32 v164, 0x4f800000, v157
	s_nop 0
	v_cndmask_b32_e32 v157, v157, v164, vcc
	v_sqrt_f32_e32 v164, v157
	s_nop 0
	v_add_u32_e32 v165, -1, v164
	v_fma_f32 v166, -v165, v164, v157
	v_cmp_ge_f32_e64 s[36:37], 0, v166
	v_add_u32_e32 v166, 1, v164
	s_nop 0
	v_cndmask_b32_e64 v165, v164, v165, s[36:37]
	v_fma_f32 v164, -v166, v164, v157
	v_cmp_lt_f32_e64 s[36:37], 0, v164
	s_nop 1
	v_cndmask_b32_e64 v164, v165, v166, s[36:37]
	v_mul_f32_e32 v165, 0x37800000, v164
	v_cndmask_b32_e32 v164, v164, v165, vcc
	v_cmp_class_f32_e32 vcc, v157, v196
	s_nop 1
	v_cndmask_b32_e32 v157, v164, v157, vcc
	v_div_scale_f32 v164, s[36:37], v157, v157, 1.0
	v_rcp_f32_e32 v165, v164
	s_nop 0
	v_fma_f32 v166, -v164, v165, 1.0
	v_fmac_f32_e32 v165, v166, v165
	v_div_scale_f32 v166, vcc, 1.0, v157, 1.0
	v_mul_f32_e32 v167, v166, v165
	v_fma_f32 v168, -v164, v167, v166
	v_fmac_f32_e32 v167, v168, v165
	v_fma_f32 v164, -v164, v167, v166
	v_div_fmas_f32 v164, v164, v165, v167
	v_div_fixup_f32 v157, v164, v157, 1.0
	v_cmp_gt_f32_e32 vcc, s13, v158
	v_mul_f32_e32 v164, 0x4f800000, v158
	s_nop 0
	v_cndmask_b32_e32 v158, v158, v164, vcc
	v_sqrt_f32_e32 v164, v158
	s_nop 0
	v_add_u32_e32 v165, -1, v164
	v_fma_f32 v166, -v165, v164, v158
	v_cmp_ge_f32_e64 s[36:37], 0, v166
	v_add_u32_e32 v166, 1, v164
	s_nop 0
	v_cndmask_b32_e64 v165, v164, v165, s[36:37]
	v_fma_f32 v164, -v166, v164, v158
	v_cmp_lt_f32_e64 s[36:37], 0, v164
	s_nop 1
	v_cndmask_b32_e64 v164, v165, v166, s[36:37]
	v_mul_f32_e32 v165, 0x37800000, v164
	v_cndmask_b32_e32 v164, v164, v165, vcc
	v_cmp_class_f32_e32 vcc, v158, v196
	s_nop 1
	v_cndmask_b32_e32 v158, v164, v158, vcc
	v_div_scale_f32 v164, s[36:37], v158, v158, 1.0
	v_rcp_f32_e32 v165, v164
	s_nop 0
	v_fma_f32 v166, -v164, v165, 1.0
	v_fmac_f32_e32 v165, v166, v165
	v_div_scale_f32 v166, vcc, 1.0, v158, 1.0
	v_mul_f32_e32 v167, v166, v165
	v_fma_f32 v168, -v164, v167, v166
	v_fmac_f32_e32 v167, v168, v165
	v_fma_f32 v164, -v164, v167, v166
	v_div_fmas_f32 v164, v164, v165, v167
	v_div_fixup_f32 v158, v164, v158, 1.0
	v_cmp_gt_f32_e32 vcc, s13, v159
	v_mul_f32_e32 v164, 0x4f800000, v159
	s_nop 0
	v_cndmask_b32_e32 v159, v159, v164, vcc
	v_sqrt_f32_e32 v164, v159
	s_nop 0
	v_add_u32_e32 v165, -1, v164
	v_fma_f32 v166, -v165, v164, v159
	v_cmp_ge_f32_e64 s[36:37], 0, v166
	v_add_u32_e32 v166, 1, v164
	s_nop 0
	v_cndmask_b32_e64 v165, v164, v165, s[36:37]
	v_fma_f32 v164, -v166, v164, v159
	v_cmp_lt_f32_e64 s[36:37], 0, v164
	s_nop 1
	v_cndmask_b32_e64 v164, v165, v166, s[36:37]
	v_mul_f32_e32 v165, 0x37800000, v164
	v_cndmask_b32_e32 v164, v164, v165, vcc
	v_cmp_class_f32_e32 vcc, v159, v196
	s_nop 1
	v_cndmask_b32_e32 v159, v164, v159, vcc
	v_div_scale_f32 v164, s[36:37], v159, v159, 1.0
	v_rcp_f32_e32 v165, v164
	s_nop 0
	v_fma_f32 v166, -v164, v165, 1.0
	v_fmac_f32_e32 v165, v166, v165
	v_div_scale_f32 v166, vcc, 1.0, v159, 1.0
	v_mul_f32_e32 v167, v166, v165
	v_fma_f32 v168, -v164, v167, v166
	v_fmac_f32_e32 v167, v168, v165
	v_fma_f32 v164, -v164, v167, v166
	v_div_fmas_f32 v164, v164, v165, v167
	v_div_fixup_f32 v159, v164, v159, 1.0
	v_mul_f32_e32 v128, v128, v156
	v_mul_f32_e32 v129, v129, v156
	v_mul_f32_e32 v130, v130, v156
	v_mul_f32_e32 v131, v131, v156
	v_mul_f32_e32 v132, v132, v157
	v_mul_f32_e32 v133, v133, v157
	v_mul_f32_e32 v134, v134, v157
	v_mul_f32_e32 v135, v135, v157
	v_mul_f32_e32 v136, v136, v158
	v_mul_f32_e32 v137, v137, v158
	v_mul_f32_e32 v138, v138, v158
	v_mul_f32_e32 v139, v139, v158
	v_mul_f32_e32 v140, v140, v159
	v_mul_f32_e32 v141, v141, v159
	v_mul_f32_e32 v142, v142, v159
	v_mul_f32_e32 v143, v143, v159
	v_mul_f32_e32 v128, v10, v128
	v_mul_f32_e32 v129, v11, v129
	v_mul_f32_e32 v130, v12, v130
	v_mul_f32_e32 v131, v13, v131
	v_mul_f32_e32 v132, v10, v132
	v_mul_f32_e32 v133, v11, v133
	v_mul_f32_e32 v134, v12, v134
	v_mul_f32_e32 v135, v13, v135
	v_mul_f32_e32 v136, v10, v136
	v_mul_f32_e32 v137, v11, v137
	v_mul_f32_e32 v138, v12, v138
	v_mul_f32_e32 v139, v13, v139
	v_mul_f32_e32 v140, v10, v140
	v_mul_f32_e32 v141, v11, v141
	v_mul_f32_e32 v142, v12, v142
	v_mul_f32_e32 v143, v13, v143
	v_cvt_pk_bf16_f32 v172, v128, v132
	v_cvt_pk_bf16_f32 v173, v136, v140
	v_cvt_pk_bf16_f32 v174, v129, v133
	v_cvt_pk_bf16_f32 v175, v137, v141
	v_cvt_pk_bf16_f32 v146, v130, v134
	v_cvt_pk_bf16_f32 v147, v138, v142
	v_cvt_pk_bf16_f32 v154, v131, v135
	v_cvt_pk_bf16_f32 v155, v139, v143
	ds_write_b64 v4, v[172:173] offset:16
	ds_write_b64 v4, v[174:175] offset:288
	ds_write_b64 v4, v[146:147] offset:560
	ds_write_b64 v4, v[154:155] offset:832
	v_lshlrev_b32_e32 v128, 16, v56
	v_and_b32_e32 v129, 0xffff0000, v56
	v_lshlrev_b32_e32 v130, 16, v57
	v_and_b32_e32 v131, 0xffff0000, v57
	v_lshlrev_b32_e32 v132, 16, v58
	v_and_b32_e32 v133, 0xffff0000, v58
	v_lshlrev_b32_e32 v134, 16, v59
	v_and_b32_e32 v135, 0xffff0000, v59
	v_lshlrev_b32_e32 v136, 16, v60
	v_and_b32_e32 v137, 0xffff0000, v60
	v_lshlrev_b32_e32 v138, 16, v61
	v_and_b32_e32 v139, 0xffff0000, v61
	v_lshlrev_b32_e32 v140, 16, v62
	v_and_b32_e32 v141, 0xffff0000, v62
	v_lshlrev_b32_e32 v142, 16, v63
	v_and_b32_e32 v143, 0xffff0000, v63
	v_add_f32_e32 v156, v128, v129
	v_add_f32_e32 v160, v130, v131
	v_add_f32_e32 v157, v132, v133
	v_add_f32_e32 v161, v134, v135
	v_add_f32_e32 v158, v136, v137
	v_add_f32_e32 v162, v138, v139
	v_add_f32_e32 v159, v140, v141
	v_add_f32_e32 v163, v142, v143
	v_add_f32_e32 v156, v156, v160
	v_add_f32_e32 v157, v157, v161
	v_add_f32_e32 v158, v158, v162
	v_add_f32_e32 v159, v159, v163
	v_add_f32_dpp v156, v156, v156 quad_perm:[1,0,3,2] row_mask:0xf bank_mask:0xf
	v_add_f32_dpp v157, v157, v157 quad_perm:[1,0,3,2] row_mask:0xf bank_mask:0xf
	v_add_f32_dpp v158, v158, v158 quad_perm:[1,0,3,2] row_mask:0xf bank_mask:0xf
	v_add_f32_dpp v159, v159, v159 quad_perm:[1,0,3,2] row_mask:0xf bank_mask:0xf
	v_add_f32_dpp v156, v156, v156 quad_perm:[2,3,0,1] row_mask:0xf bank_mask:0xf
	v_add_f32_dpp v157, v157, v157 quad_perm:[2,3,0,1] row_mask:0xf bank_mask:0xf
	v_add_f32_dpp v158, v158, v158 quad_perm:[2,3,0,1] row_mask:0xf bank_mask:0xf
	v_add_f32_dpp v159, v159, v159 quad_perm:[2,3,0,1] row_mask:0xf bank_mask:0xf
	v_add_f32_dpp v156, v156, v156 row_half_mirror row_mask:0xf bank_mask:0xf
	v_add_f32_dpp v157, v157, v157 row_half_mirror row_mask:0xf bank_mask:0xf
	v_add_f32_dpp v158, v158, v158 row_half_mirror row_mask:0xf bank_mask:0xf
	v_add_f32_dpp v159, v159, v159 row_half_mirror row_mask:0xf bank_mask:0xf
	v_add_f32_dpp v156, v156, v156 row_mirror row_mask:0xf bank_mask:0xf
	v_add_f32_dpp v157, v157, v157 row_mirror row_mask:0xf bank_mask:0xf
	v_add_f32_dpp v158, v158, v158 row_mirror row_mask:0xf bank_mask:0xf
	v_add_f32_dpp v159, v159, v159 row_mirror row_mask:0xf bank_mask:0xf
	v_mov_b32_e32 v160, v156
	v_mov_b32_e32 v161, v157
	v_mov_b32_e32 v162, v158
	v_mov_b32_e32 v163, v159
	v_permlane16_swap_b32_e32 v156, v160
	v_permlane16_swap_b32_e32 v157, v161
	v_permlane16_swap_b32_e32 v158, v162
	v_permlane16_swap_b32_e32 v159, v163
	v_add_f32_e32 v156, v156, v160
	v_add_f32_e32 v157, v157, v161
	v_add_f32_e32 v158, v158, v162
	v_add_f32_e32 v159, v159, v163
	v_mov_b32_e32 v160, v156
	v_mov_b32_e32 v161, v157
	v_mov_b32_e32 v162, v158
	v_mov_b32_e32 v163, v159
	v_permlane32_swap_b32_e32 v156, v160
	v_permlane32_swap_b32_e32 v157, v161
	v_permlane32_swap_b32_e32 v158, v162
	v_permlane32_swap_b32_e32 v159, v163
	v_add_f32_e32 v156, v156, v160
	v_add_f32_e32 v157, v157, v161
	v_add_f32_e32 v158, v158, v162
	v_add_f32_e32 v159, v159, v163
	v_fmac_f32_e32 v129, 0xbb800000, v156
	v_fmac_f32_e32 v131, 0xbb800000, v156
	v_fmac_f32_e32 v130, 0xbb800000, v156
	v_fmac_f32_e32 v128, 0xbb800000, v156
	v_fmac_f32_e32 v133, 0xbb800000, v157
	v_fmac_f32_e32 v135, 0xbb800000, v157
	v_fmac_f32_e32 v134, 0xbb800000, v157
	v_fmac_f32_e32 v132, 0xbb800000, v157
	v_fmac_f32_e32 v137, 0xbb800000, v158
	v_fmac_f32_e32 v139, 0xbb800000, v158
	v_fmac_f32_e32 v138, 0xbb800000, v158
	v_fmac_f32_e32 v136, 0xbb800000, v158
	v_fmac_f32_e32 v141, 0xbb800000, v159
	v_fmac_f32_e32 v143, 0xbb800000, v159
	v_fmac_f32_e32 v142, 0xbb800000, v159
	v_fmac_f32_e32 v140, 0xbb800000, v159
	v_mul_f32_e32 v156, v128, v128
	v_mul_f32_e32 v160, v129, v129
	v_mul_f32_e32 v164, v130, v130
	v_mul_f32_e32 v168, v131, v131
	v_mul_f32_e32 v157, v132, v132
	v_mul_f32_e32 v161, v133, v133
	v_mul_f32_e32 v165, v134, v134
	v_mul_f32_e32 v169, v135, v135
	v_mul_f32_e32 v158, v136, v136
	v_mul_f32_e32 v162, v137, v137
	v_mul_f32_e32 v166, v138, v138
	v_mul_f32_e32 v170, v139, v139
	v_mul_f32_e32 v159, v140, v140
	v_mul_f32_e32 v163, v141, v141
	v_mul_f32_e32 v167, v142, v142
	v_mul_f32_e32 v171, v143, v143
	v_add_f32_e32 v156, v160, v156
	v_add_f32_e32 v164, v164, v168
	v_add_f32_e32 v157, v161, v157
	v_add_f32_e32 v165, v165, v169
	v_add_f32_e32 v158, v162, v158
	v_add_f32_e32 v166, v166, v170
	v_add_f32_e32 v159, v163, v159
	v_add_f32_e32 v167, v167, v171
	v_add_f32_e32 v156, v156, v164
	v_add_f32_e32 v157, v157, v165
	v_add_f32_e32 v158, v158, v166
	v_add_f32_e32 v159, v159, v167
	v_add_f32_dpp v156, v156, v156 quad_perm:[1,0,3,2] row_mask:0xf bank_mask:0xf
	v_add_f32_dpp v157, v157, v157 quad_perm:[1,0,3,2] row_mask:0xf bank_mask:0xf
	v_add_f32_dpp v158, v158, v158 quad_perm:[1,0,3,2] row_mask:0xf bank_mask:0xf
	v_add_f32_dpp v159, v159, v159 quad_perm:[1,0,3,2] row_mask:0xf bank_mask:0xf
	v_add_f32_dpp v156, v156, v156 quad_perm:[2,3,0,1] row_mask:0xf bank_mask:0xf
	v_add_f32_dpp v157, v157, v157 quad_perm:[2,3,0,1] row_mask:0xf bank_mask:0xf
	v_add_f32_dpp v158, v158, v158 quad_perm:[2,3,0,1] row_mask:0xf bank_mask:0xf
	v_add_f32_dpp v159, v159, v159 quad_perm:[2,3,0,1] row_mask:0xf bank_mask:0xf
	v_add_f32_dpp v156, v156, v156 row_half_mirror row_mask:0xf bank_mask:0xf
	v_add_f32_dpp v157, v157, v157 row_half_mirror row_mask:0xf bank_mask:0xf
	v_add_f32_dpp v158, v158, v158 row_half_mirror row_mask:0xf bank_mask:0xf
	v_add_f32_dpp v159, v159, v159 row_half_mirror row_mask:0xf bank_mask:0xf
	v_add_f32_dpp v156, v156, v156 row_mirror row_mask:0xf bank_mask:0xf
	v_add_f32_dpp v157, v157, v157 row_mirror row_mask:0xf bank_mask:0xf
	v_add_f32_dpp v158, v158, v158 row_mirror row_mask:0xf bank_mask:0xf
	v_add_f32_dpp v159, v159, v159 row_mirror row_mask:0xf bank_mask:0xf
	v_mov_b32_e32 v160, v156
	v_mov_b32_e32 v161, v157
	v_mov_b32_e32 v162, v158
	v_mov_b32_e32 v163, v159
	v_permlane16_swap_b32_e32 v156, v160
	v_permlane16_swap_b32_e32 v157, v161
	v_permlane16_swap_b32_e32 v158, v162
	v_permlane16_swap_b32_e32 v159, v163
	v_add_f32_e32 v156, v156, v160
	v_add_f32_e32 v157, v157, v161
	v_add_f32_e32 v158, v158, v162
	v_add_f32_e32 v159, v159, v163
	v_mov_b32_e32 v160, v156
	v_mov_b32_e32 v161, v157
	v_mov_b32_e32 v162, v158
	v_mov_b32_e32 v163, v159
	v_permlane32_swap_b32_e32 v156, v160
	v_permlane32_swap_b32_e32 v157, v161
	v_permlane32_swap_b32_e32 v158, v162
	v_permlane32_swap_b32_e32 v159, v163
	v_add_f32_e32 v156, v156, v160
	v_add_f32_e32 v157, v157, v161
	v_add_f32_e32 v158, v158, v162
	v_add_f32_e32 v159, v159, v163
	v_fmamk_f32 v156, v156, 0x3b800000, v194
	v_fmamk_f32 v157, v157, 0x3b800000, v194
	v_fmamk_f32 v158, v158, 0x3b800000, v194
	v_fmamk_f32 v159, v159, 0x3b800000, v194
	v_cmp_gt_f32_e32 vcc, s13, v156
	v_mul_f32_e32 v164, 0x4f800000, v156
	s_nop 0
	v_cndmask_b32_e32 v156, v156, v164, vcc
	v_sqrt_f32_e32 v164, v156
	s_nop 0
	v_add_u32_e32 v165, -1, v164
	v_fma_f32 v166, -v165, v164, v156
	v_cmp_ge_f32_e64 s[36:37], 0, v166
	v_add_u32_e32 v166, 1, v164
	s_nop 0
	v_cndmask_b32_e64 v165, v164, v165, s[36:37]
	v_fma_f32 v164, -v166, v164, v156
	v_cmp_lt_f32_e64 s[36:37], 0, v164
	s_nop 1
	v_cndmask_b32_e64 v164, v165, v166, s[36:37]
	v_mul_f32_e32 v165, 0x37800000, v164
	v_cndmask_b32_e32 v164, v164, v165, vcc
	v_cmp_class_f32_e32 vcc, v156, v196
	s_nop 1
	v_cndmask_b32_e32 v156, v164, v156, vcc
	v_div_scale_f32 v164, s[36:37], v156, v156, 1.0
	v_rcp_f32_e32 v165, v164
	s_nop 0
	v_fma_f32 v166, -v164, v165, 1.0
	v_fmac_f32_e32 v165, v166, v165
	v_div_scale_f32 v166, vcc, 1.0, v156, 1.0
	v_mul_f32_e32 v167, v166, v165
	v_fma_f32 v168, -v164, v167, v166
	v_fmac_f32_e32 v167, v168, v165
	v_fma_f32 v164, -v164, v167, v166
	v_div_fmas_f32 v164, v164, v165, v167
	v_div_fixup_f32 v156, v164, v156, 1.0
	v_cmp_gt_f32_e32 vcc, s13, v157
	v_mul_f32_e32 v164, 0x4f800000, v157
	s_nop 0
	v_cndmask_b32_e32 v157, v157, v164, vcc
	v_sqrt_f32_e32 v164, v157
	s_nop 0
	v_add_u32_e32 v165, -1, v164
	v_fma_f32 v166, -v165, v164, v157
	v_cmp_ge_f32_e64 s[36:37], 0, v166
	v_add_u32_e32 v166, 1, v164
	s_nop 0
	v_cndmask_b32_e64 v165, v164, v165, s[36:37]
	v_fma_f32 v164, -v166, v164, v157
	v_cmp_lt_f32_e64 s[36:37], 0, v164
	s_nop 1
	v_cndmask_b32_e64 v164, v165, v166, s[36:37]
	v_mul_f32_e32 v165, 0x37800000, v164
	v_cndmask_b32_e32 v164, v164, v165, vcc
	v_cmp_class_f32_e32 vcc, v157, v196
	s_nop 1
	v_cndmask_b32_e32 v157, v164, v157, vcc
	v_div_scale_f32 v164, s[36:37], v157, v157, 1.0
	v_rcp_f32_e32 v165, v164
	s_nop 0
	v_fma_f32 v166, -v164, v165, 1.0
	v_fmac_f32_e32 v165, v166, v165
	v_div_scale_f32 v166, vcc, 1.0, v157, 1.0
	v_mul_f32_e32 v167, v166, v165
	v_fma_f32 v168, -v164, v167, v166
	v_fmac_f32_e32 v167, v168, v165
	v_fma_f32 v164, -v164, v167, v166
	v_div_fmas_f32 v164, v164, v165, v167
	v_div_fixup_f32 v157, v164, v157, 1.0
	v_cmp_gt_f32_e32 vcc, s13, v158
	v_mul_f32_e32 v164, 0x4f800000, v158
	s_nop 0
	v_cndmask_b32_e32 v158, v158, v164, vcc
	v_sqrt_f32_e32 v164, v158
	s_nop 0
	v_add_u32_e32 v165, -1, v164
	v_fma_f32 v166, -v165, v164, v158
	v_cmp_ge_f32_e64 s[36:37], 0, v166
	v_add_u32_e32 v166, 1, v164
	s_nop 0
	v_cndmask_b32_e64 v165, v164, v165, s[36:37]
	v_fma_f32 v164, -v166, v164, v158
	v_cmp_lt_f32_e64 s[36:37], 0, v164
	s_nop 1
	v_cndmask_b32_e64 v164, v165, v166, s[36:37]
	v_mul_f32_e32 v165, 0x37800000, v164
	v_cndmask_b32_e32 v164, v164, v165, vcc
	v_cmp_class_f32_e32 vcc, v158, v196
	s_nop 1
	v_cndmask_b32_e32 v158, v164, v158, vcc
	v_div_scale_f32 v164, s[36:37], v158, v158, 1.0
	v_rcp_f32_e32 v165, v164
	s_nop 0
	v_fma_f32 v166, -v164, v165, 1.0
	v_fmac_f32_e32 v165, v166, v165
	v_div_scale_f32 v166, vcc, 1.0, v158, 1.0
	v_mul_f32_e32 v167, v166, v165
	v_fma_f32 v168, -v164, v167, v166
	v_fmac_f32_e32 v167, v168, v165
	v_fma_f32 v164, -v164, v167, v166
	v_div_fmas_f32 v164, v164, v165, v167
	v_div_fixup_f32 v158, v164, v158, 1.0
	v_cmp_gt_f32_e32 vcc, s13, v159
	v_mul_f32_e32 v164, 0x4f800000, v159
	s_nop 0
	v_cndmask_b32_e32 v159, v159, v164, vcc
	v_sqrt_f32_e32 v164, v159
	s_nop 0
	v_add_u32_e32 v165, -1, v164
	v_fma_f32 v166, -v165, v164, v159
	v_cmp_ge_f32_e64 s[36:37], 0, v166
	v_add_u32_e32 v166, 1, v164
	s_nop 0
	v_cndmask_b32_e64 v165, v164, v165, s[36:37]
	v_fma_f32 v164, -v166, v164, v159
	v_cmp_lt_f32_e64 s[36:37], 0, v164
	s_nop 1
	v_cndmask_b32_e64 v164, v165, v166, s[36:37]
	v_mul_f32_e32 v165, 0x37800000, v164
	v_cndmask_b32_e32 v164, v164, v165, vcc
	v_cmp_class_f32_e32 vcc, v159, v196
	s_nop 1
	v_cndmask_b32_e32 v159, v164, v159, vcc
	v_div_scale_f32 v164, s[36:37], v159, v159, 1.0
	v_rcp_f32_e32 v165, v164
	s_nop 0
	v_fma_f32 v166, -v164, v165, 1.0
	v_fmac_f32_e32 v165, v166, v165
	v_div_scale_f32 v166, vcc, 1.0, v159, 1.0
	v_mul_f32_e32 v167, v166, v165
	v_fma_f32 v168, -v164, v167, v166
	v_fmac_f32_e32 v167, v168, v165
	v_fma_f32 v164, -v164, v167, v166
	v_div_fmas_f32 v164, v164, v165, v167
	v_div_fixup_f32 v159, v164, v159, 1.0
	v_mul_f32_e32 v128, v128, v156
	v_mul_f32_e32 v129, v129, v156
	v_mul_f32_e32 v130, v130, v156
	v_mul_f32_e32 v131, v131, v156
	v_mul_f32_e32 v132, v132, v157
	v_mul_f32_e32 v133, v133, v157
	v_mul_f32_e32 v134, v134, v157
	v_mul_f32_e32 v135, v135, v157
	v_mul_f32_e32 v136, v136, v158
	v_mul_f32_e32 v137, v137, v158
	v_mul_f32_e32 v138, v138, v158
	v_mul_f32_e32 v139, v139, v158
	v_mul_f32_e32 v140, v140, v159
	v_mul_f32_e32 v141, v141, v159
	v_mul_f32_e32 v142, v142, v159
	v_mul_f32_e32 v143, v143, v159
	v_mul_f32_e32 v128, v10, v128
	v_mul_f32_e32 v129, v11, v129
	v_mul_f32_e32 v130, v12, v130
	v_mul_f32_e32 v131, v13, v131
	v_mul_f32_e32 v132, v10, v132
	v_mul_f32_e32 v133, v11, v133
	v_mul_f32_e32 v134, v12, v134
	v_mul_f32_e32 v135, v13, v135
	v_mul_f32_e32 v136, v10, v136
	v_mul_f32_e32 v137, v11, v137
	v_mul_f32_e32 v138, v12, v138
	v_mul_f32_e32 v139, v13, v139
	v_mul_f32_e32 v140, v10, v140
	v_mul_f32_e32 v141, v11, v141
	v_mul_f32_e32 v142, v12, v142
	v_mul_f32_e32 v143, v13, v143
	v_cvt_pk_bf16_f32 v172, v128, v132
	v_cvt_pk_bf16_f32 v173, v136, v140
	v_cvt_pk_bf16_f32 v174, v129, v133
	v_cvt_pk_bf16_f32 v175, v137, v141
	v_cvt_pk_bf16_f32 v146, v130, v134
	v_cvt_pk_bf16_f32 v147, v138, v142
	v_cvt_pk_bf16_f32 v154, v131, v135
	v_cvt_pk_bf16_f32 v155, v139, v143
	ds_write_b64 v4, v[172:173] offset:24
	ds_write_b64 v4, v[174:175] offset:296
	ds_write_b64 v4, v[146:147] offset:568
	ds_write_b64 v4, v[154:155] offset:840
	s_waitcnt vmcnt(0)
	v_cvt_pk_bf16_f32 v64, v64, v65
	v_cvt_pk_bf16_f32 v65, v66, v67
	v_cvt_pk_bf16_f32 v66, v68, v69
	v_cvt_pk_bf16_f32 v67, v70, v71
	v_and_b32_e32 v64, v22, v64
	v_and_b32_e32 v65, v23, v65
	v_and_b32_e32 v66, v24, v66
	v_and_b32_e32 v67, v25, v67
	v_cvt_pk_bf16_f32 v72, v72, v73
	v_cvt_pk_bf16_f32 v73, v74, v75
	v_cvt_pk_bf16_f32 v74, v76, v77
	v_cvt_pk_bf16_f32 v75, v78, v79
	v_and_b32_e32 v72, v26, v72
	v_and_b32_e32 v73, v27, v73
	v_and_b32_e32 v74, v28, v74
	v_and_b32_e32 v75, v29, v75
	v_cvt_pk_bf16_f32 v80, v80, v81
	v_cvt_pk_bf16_f32 v81, v82, v83
	v_cvt_pk_bf16_f32 v82, v84, v85
	v_cvt_pk_bf16_f32 v83, v86, v87
	v_cvt_pk_bf16_f32 v88, v88, v89
	v_cvt_pk_bf16_f32 v89, v90, v91
	v_cvt_pk_bf16_f32 v90, v92, v93
	v_cvt_pk_bf16_f32 v91, v94, v95
	v_cvt_pk_bf16_f32 v96, v96, v97
	v_cvt_pk_bf16_f32 v97, v98, v99
	v_cvt_pk_bf16_f32 v98, v100, v101
	v_cvt_pk_bf16_f32 v99, v102, v103
	v_and_b32_e32 v96, s12, v96
	v_and_b32_e32 v97, s12, v97
	v_and_b32_e32 v98, s12, v98
	v_and_b32_e32 v99, s12, v99
	v_cvt_pk_bf16_f32 v104, v104, v105
	v_cvt_pk_bf16_f32 v105, v106, v107
	v_cvt_pk_bf16_f32 v106, v108, v109
	v_cvt_pk_bf16_f32 v107, v110, v111
	v_and_b32_e32 v104, s12, v104
	v_and_b32_e32 v105, s12, v105
	v_and_b32_e32 v106, s12, v106
	v_and_b32_e32 v107, s12, v107
	v_cvt_pk_bf16_f32 v112, v112, v113
	v_cvt_pk_bf16_f32 v113, v114, v115
	v_cvt_pk_bf16_f32 v114, v116, v117
	v_cvt_pk_bf16_f32 v115, v118, v119
	v_and_b32_e32 v112, v22, v112
	v_and_b32_e32 v113, v23, v113
	v_and_b32_e32 v114, v24, v114
	v_and_b32_e32 v115, v25, v115
	v_cvt_pk_bf16_f32 v120, v120, v121
	v_cvt_pk_bf16_f32 v121, v122, v123
	v_cvt_pk_bf16_f32 v122, v124, v125
	v_cvt_pk_bf16_f32 v123, v126, v127
	v_and_b32_e32 v120, v26, v120
	v_and_b32_e32 v121, v27, v121
	v_and_b32_e32 v122, v28, v122
	v_and_b32_e32 v123, v29, v123
	s_waitcnt lgkmcnt(0)
	s_barrier
	ds_read_b128 v[100:103], v5
	ds_read_b128 v[108:111], v5 offset:4352
	ds_read_b128 v[116:119], v5 offset:8704
	ds_read_b128 v[124:127], v5 offset:13056
	s_waitcnt lgkmcnt(0)
	v_mfma_f32_16x16x32_bf16 v[32:35], v[100:103], v[64:67], 0
	v_mfma_f32_16x16x32_bf16 v[36:39], v[108:111], v[64:67], 0
	v_mfma_f32_16x16x32_bf16 v[40:43], v[116:119], v[64:67], 0
	v_mfma_f32_16x16x32_bf16 v[44:47], v[124:127], v[64:67], 0
	v_mfma_f32_16x16x32_bf16 v[48:51], v[100:103], v[72:75], 0
	v_mfma_f32_16x16x32_bf16 v[52:55], v[108:111], v[72:75], 0
	v_mfma_f32_16x16x32_bf16 v[56:59], v[116:119], v[72:75], 0
	v_mfma_f32_16x16x32_bf16 v[60:63], v[124:127], v[72:75], 0
	v_mfma_f32_16x16x32_bf16 v[128:131], v[100:103], v[80:83], 0
	v_mfma_f32_16x16x32_bf16 v[132:135], v[108:111], v[80:83], 0
	v_mfma_f32_16x16x32_bf16 v[136:139], v[116:119], v[80:83], 0
	v_mfma_f32_16x16x32_bf16 v[140:143], v[124:127], v[80:83], 0
	v_mfma_f32_16x16x32_bf16 v[156:159], v[100:103], v[88:91], 0
	v_mfma_f32_16x16x32_bf16 v[160:163], v[108:111], v[88:91], 0
	v_mfma_f32_16x16x32_bf16 v[164:167], v[116:119], v[88:91], 0
	v_mfma_f32_16x16x32_bf16 v[168:171], v[124:127], v[88:91], 0
	ds_read_b128 v[68:71], v5 offset:64
	ds_read_b128 v[76:79], v5 offset:4416
	ds_read_b128 v[84:87], v5 offset:8768
	ds_read_b128 v[92:95], v5 offset:13120
	s_waitcnt lgkmcnt(0)
	v_mfma_f32_16x16x32_bf16 v[32:35], v[68:71], v[96:99], v[32:35]
	v_mfma_f32_16x16x32_bf16 v[36:39], v[76:79], v[96:99], v[36:39]
	v_mfma_f32_16x16x32_bf16 v[40:43], v[84:87], v[96:99], v[40:43]
	v_mfma_f32_16x16x32_bf16 v[44:47], v[92:95], v[96:99], v[44:47]
	v_mfma_f32_16x16x32_bf16 v[48:51], v[68:71], v[104:107], v[48:51]
	v_mfma_f32_16x16x32_bf16 v[52:55], v[76:79], v[104:107], v[52:55]
	v_mfma_f32_16x16x32_bf16 v[56:59], v[84:87], v[104:107], v[56:59]
	v_mfma_f32_16x16x32_bf16 v[60:63], v[92:95], v[104:107], v[60:63]
	v_mfma_f32_16x16x32_bf16 v[128:131], v[68:71], v[112:115], v[128:131]
	v_mfma_f32_16x16x32_bf16 v[132:135], v[76:79], v[112:115], v[132:135]
	v_mfma_f32_16x16x32_bf16 v[136:139], v[84:87], v[112:115], v[136:139]
	v_mfma_f32_16x16x32_bf16 v[140:143], v[92:95], v[112:115], v[140:143]
	v_mfma_f32_16x16x32_bf16 v[156:159], v[68:71], v[120:123], v[156:159]
	v_mfma_f32_16x16x32_bf16 v[160:163], v[76:79], v[120:123], v[160:163]
	v_mfma_f32_16x16x32_bf16 v[164:167], v[84:87], v[120:123], v[164:167]
	v_mfma_f32_16x16x32_bf16 v[168:171], v[92:95], v[120:123], v[168:171]
	s_cmp_eq_u32 s4, 0
	s_cbranch_scc1 .Lmixb_gate
	s_sub_u32 s10, s10, 0x8000
	s_subb_u32 s11, s11, 0
	global_load_dwordx4 v[64:67], v3, s[10:11] offset:256
	global_load_dwordx4 v[68:71], v3, s[10:11] offset:272
	s_add_u32 s10, s10, 0x2000
	s_addc_u32 s11, s11, 0
	global_load_dwordx4 v[72:75], v3, s[10:11] offset:256
	global_load_dwordx4 v[76:79], v3, s[10:11] offset:272
	s_add_u32 s10, s10, 0x2000
	s_addc_u32 s11, s11, 0
	global_load_dwordx4 v[80:83], v3, s[10:11] offset:256
	global_load_dwordx4 v[84:87], v3, s[10:11] offset:272
	global_load_dwordx4 v[96:99], v3, s[10:11] offset:384
	global_load_dwordx4 v[100:103], v3, s[10:11] offset:400
	s_add_u32 s10, s10, 0x2000
	s_addc_u32 s11, s11, 0
	global_load_dwordx4 v[88:91], v3, s[10:11] offset:256
	global_load_dwordx4 v[92:95], v3, s[10:11] offset:272
	global_load_dwordx4 v[104:107], v3, s[10:11] offset:384
	global_load_dwordx4 v[108:111], v3, s[10:11] offset:400
	s_waitcnt vmcnt(0)
	v_cvt_pk_bf16_f32 v64, v64, v65
	v_cvt_pk_bf16_f32 v65, v66, v67
	v_cvt_pk_bf16_f32 v66, v68, v69
	v_cvt_pk_bf16_f32 v67, v70, v71
	v_and_b32_e32 v64, v14, v64
	v_and_b32_e32 v65, v15, v65
	v_and_b32_e32 v66, v16, v66
	v_and_b32_e32 v67, v17, v67
	v_cvt_pk_bf16_f32 v72, v72, v73
	v_cvt_pk_bf16_f32 v73, v74, v75
	v_cvt_pk_bf16_f32 v74, v76, v77
	v_cvt_pk_bf16_f32 v75, v78, v79
	v_and_b32_e32 v72, v18, v72
	v_and_b32_e32 v73, v19, v73
	v_and_b32_e32 v74, v20, v74
	v_and_b32_e32 v75, v21, v75
	v_cvt_pk_bf16_f32 v80, v80, v81
	v_cvt_pk_bf16_f32 v81, v82, v83
	v_cvt_pk_bf16_f32 v82, v84, v85
	v_cvt_pk_bf16_f32 v83, v86, v87
	v_cvt_pk_bf16_f32 v88, v88, v89
	v_cvt_pk_bf16_f32 v89, v90, v91
	v_cvt_pk_bf16_f32 v90, v92, v93
	v_cvt_pk_bf16_f32 v91, v94, v95
	v_cvt_pk_bf16_f32 v96, v96, v97
	v_cvt_pk_bf16_f32 v97, v98, v99
	v_cvt_pk_bf16_f32 v98, v100, v101
	v_cvt_pk_bf16_f32 v99, v102, v103
	v_and_b32_e32 v96, v14, v96
	v_and_b32_e32 v97, v15, v97
	v_and_b32_e32 v98, v16, v98
	v_and_b32_e32 v99, v17, v99
	v_cvt_pk_bf16_f32 v104, v104, v105
	v_cvt_pk_bf16_f32 v105, v106, v107
	v_cvt_pk_bf16_f32 v106, v108, v109
	v_cvt_pk_bf16_f32 v107, v110, v111
	v_and_b32_e32 v104, v18, v104
	v_and_b32_e32 v105, v19, v105
	v_and_b32_e32 v106, v20, v106
	v_and_b32_e32 v107, v21, v107
	ds_read_b128 v[68:71], v5 offset:128
	ds_read_b128 v[76:79], v5 offset:4480
	ds_read_b128 v[84:87], v5 offset:8832
	ds_read_b128 v[92:95], v5 offset:13184
	ds_read_b128 v[100:103], v5 offset:192
	ds_read_b128 v[108:111], v5 offset:4544
	ds_read_b128 v[112:115], v5 offset:8896
	ds_read_b128 v[116:119], v5 offset:13248
	s_waitcnt lgkmcnt(4)
	v_mfma_f32_16x16x32_bf16 v[32:35], v[68:71], v[64:67], v[32:35]
	v_mfma_f32_16x16x32_bf16 v[36:39], v[76:79], v[64:67], v[36:39]
	v_mfma_f32_16x16x32_bf16 v[40:43], v[84:87], v[64:67], v[40:43]
	v_mfma_f32_16x16x32_bf16 v[44:47], v[92:95], v[64:67], v[44:47]
	v_mfma_f32_16x16x32_bf16 v[48:51], v[68:71], v[72:75], v[48:51]
	v_mfma_f32_16x16x32_bf16 v[52:55], v[76:79], v[72:75], v[52:55]
	v_mfma_f32_16x16x32_bf16 v[56:59], v[84:87], v[72:75], v[56:59]
	v_mfma_f32_16x16x32_bf16 v[60:63], v[92:95], v[72:75], v[60:63]
	v_mfma_f32_16x16x32_bf16 v[128:131], v[68:71], v[80:83], v[128:131]
	v_mfma_f32_16x16x32_bf16 v[132:135], v[76:79], v[80:83], v[132:135]
	v_mfma_f32_16x16x32_bf16 v[136:139], v[84:87], v[80:83], v[136:139]
	v_mfma_f32_16x16x32_bf16 v[140:143], v[92:95], v[80:83], v[140:143]
	v_mfma_f32_16x16x32_bf16 v[156:159], v[68:71], v[88:91], v[156:159]
	v_mfma_f32_16x16x32_bf16 v[160:163], v[76:79], v[88:91], v[160:163]
	v_mfma_f32_16x16x32_bf16 v[164:167], v[84:87], v[88:91], v[164:167]
	v_mfma_f32_16x16x32_bf16 v[168:171], v[92:95], v[88:91], v[168:171]
	s_waitcnt lgkmcnt(0)
	v_mfma_f32_16x16x32_bf16 v[128:131], v[100:103], v[96:99], v[128:131]
	v_mfma_f32_16x16x32_bf16 v[132:135], v[108:111], v[96:99], v[132:135]
	v_mfma_f32_16x16x32_bf16 v[136:139], v[112:115], v[96:99], v[136:139]
	v_mfma_f32_16x16x32_bf16 v[140:143], v[116:119], v[96:99], v[140:143]
	v_mfma_f32_16x16x32_bf16 v[156:159], v[100:103], v[104:107], v[156:159]
	v_mfma_f32_16x16x32_bf16 v[160:163], v[108:111], v[104:107], v[160:163]
	v_mfma_f32_16x16x32_bf16 v[164:167], v[112:115], v[104:107], v[164:167]
	v_mfma_f32_16x16x32_bf16 v[168:171], v[116:119], v[104:107], v[168:171]
.Lmixb_gate:
	global_load_dword v96, v7, s[14:15]
	global_load_dword v97, v7, s[14:15] offset:64
	global_load_dword v98, v7, s[14:15] offset:128
	global_load_dword v99, v7, s[14:15] offset:192
	v_mul_u32_u24_e32 v100, 0x210, v0
	v_lshl_add_u32 v100, v1, 3, v100
	s_mul_i32 s5, s4, 0x8400
	s_lshl_b32 s36, s3, 7
	s_add_i32 s5, s5, s36
	s_add_i32 s5, s5, 0x11000
	v_add_u32_e32 v100, s5, v100
	ds_read_b64 v[64:65], v100 offset:0
	ds_read_b64 v[66:67], v100 offset:32
	ds_read_b64 v[68:69], v100 offset:64
	ds_read_b64 v[70:71], v100 offset:96
	ds_read_b64 v[72:73], v100 offset:8448
	ds_read_b64 v[74:75], v100 offset:8480
	ds_read_b64 v[76:77], v100 offset:8512
	ds_read_b64 v[78:79], v100 offset:8544
	ds_read_b64 v[80:81], v100 offset:16896
	ds_read_b64 v[82:83], v100 offset:16928
	ds_read_b64 v[84:85], v100 offset:16960
	ds_read_b64 v[86:87], v100 offset:16992
	ds_read_b64 v[88:89], v100 offset:25344
	ds_read_b64 v[90:91], v100 offset:25376
	ds_read_b64 v[92:93], v100 offset:25408
	ds_read_b64 v[94:95], v100 offset:25440
	s_nop 7
	s_waitcnt vmcnt(0) lgkmcnt(0)
	v_add_f32_e32 v32, v96, v32
	v_add_f32_e32 v33, v96, v33
	v_add_f32_e32 v34, v96, v34
	v_add_f32_e32 v35, v96, v35
	v_lshlrev_b32_e32 v104, 16, v64
	v_and_b32_e32 v105, 0xffff0000, v64
	v_lshlrev_b32_e32 v106, 16, v65
	v_and_b32_e32 v107, 0xffff0000, v65
	v_mul_f32_e32 v32, v32, v104
	v_mul_f32_e32 v33, v33, v105
	v_mul_f32_e32 v34, v34, v106
	v_mul_f32_e32 v35, v35, v107
	v_cvt_pk_bf16_f32 v32, v32, v33
	v_cvt_pk_bf16_f32 v33, v34, v35
	ds_write_b64 v100, v[32:33] offset:0
	v_add_f32_e32 v36, v96, v36
	v_add_f32_e32 v37, v96, v37
	v_add_f32_e32 v38, v96, v38
	v_add_f32_e32 v39, v96, v39
	v_lshlrev_b32_e32 v108, 16, v66
	v_and_b32_e32 v109, 0xffff0000, v66
	v_lshlrev_b32_e32 v110, 16, v67
	v_and_b32_e32 v111, 0xffff0000, v67
	v_mul_f32_e32 v36, v36, v108
	v_mul_f32_e32 v37, v37, v109
	v_mul_f32_e32 v38, v38, v110
	v_mul_f32_e32 v39, v39, v111
	v_cvt_pk_bf16_f32 v36, v36, v37
	v_cvt_pk_bf16_f32 v37, v38, v39
	ds_write_b64 v100, v[36:37] offset:32
	v_add_f32_e32 v40, v96, v40
	v_add_f32_e32 v41, v96, v41
	v_add_f32_e32 v42, v96, v42
	v_add_f32_e32 v43, v96, v43
	v_lshlrev_b32_e32 v104, 16, v68
	v_and_b32_e32 v105, 0xffff0000, v68
	v_lshlrev_b32_e32 v106, 16, v69
	v_and_b32_e32 v107, 0xffff0000, v69
	v_mul_f32_e32 v40, v40, v104
	v_mul_f32_e32 v41, v41, v105
	v_mul_f32_e32 v42, v42, v106
	v_mul_f32_e32 v43, v43, v107
	v_cvt_pk_bf16_f32 v40, v40, v41
	v_cvt_pk_bf16_f32 v41, v42, v43
	ds_write_b64 v100, v[40:41] offset:64
	v_add_f32_e32 v44, v96, v44
	v_add_f32_e32 v45, v96, v45
	v_add_f32_e32 v46, v96, v46
	v_add_f32_e32 v47, v96, v47
	v_lshlrev_b32_e32 v108, 16, v70
	v_and_b32_e32 v109, 0xffff0000, v70
	v_lshlrev_b32_e32 v110, 16, v71
	v_and_b32_e32 v111, 0xffff0000, v71
	v_mul_f32_e32 v44, v44, v108
	v_mul_f32_e32 v45, v45, v109
	v_mul_f32_e32 v46, v46, v110
	v_mul_f32_e32 v47, v47, v111
	v_cvt_pk_bf16_f32 v44, v44, v45
	v_cvt_pk_bf16_f32 v45, v46, v47
	ds_write_b64 v100, v[44:45] offset:96
	v_add_f32_e32 v48, v97, v48
	v_add_f32_e32 v49, v97, v49
	v_add_f32_e32 v50, v97, v50
	v_add_f32_e32 v51, v97, v51
	v_lshlrev_b32_e32 v104, 16, v72
	v_and_b32_e32 v105, 0xffff0000, v72
	v_lshlrev_b32_e32 v106, 16, v73
	v_and_b32_e32 v107, 0xffff0000, v73
	v_mul_f32_e32 v48, v48, v104
	v_mul_f32_e32 v49, v49, v105
	v_mul_f32_e32 v50, v50, v106
	v_mul_f32_e32 v51, v51, v107
	v_cvt_pk_bf16_f32 v48, v48, v49
	v_cvt_pk_bf16_f32 v49, v50, v51
	ds_write_b64 v100, v[48:49] offset:8448
	v_add_f32_e32 v52, v97, v52
	v_add_f32_e32 v53, v97, v53
	v_add_f32_e32 v54, v97, v54
	v_add_f32_e32 v55, v97, v55
	v_lshlrev_b32_e32 v108, 16, v74
	v_and_b32_e32 v109, 0xffff0000, v74
	v_lshlrev_b32_e32 v110, 16, v75
	v_and_b32_e32 v111, 0xffff0000, v75
	v_mul_f32_e32 v52, v52, v108
	v_mul_f32_e32 v53, v53, v109
	v_mul_f32_e32 v54, v54, v110
	v_mul_f32_e32 v55, v55, v111
	v_cvt_pk_bf16_f32 v52, v52, v53
	v_cvt_pk_bf16_f32 v53, v54, v55
	ds_write_b64 v100, v[52:53] offset:8480
	v_add_f32_e32 v56, v97, v56
	v_add_f32_e32 v57, v97, v57
	v_add_f32_e32 v58, v97, v58
	v_add_f32_e32 v59, v97, v59
	v_lshlrev_b32_e32 v104, 16, v76
	v_and_b32_e32 v105, 0xffff0000, v76
	v_lshlrev_b32_e32 v106, 16, v77
	v_and_b32_e32 v107, 0xffff0000, v77
	v_mul_f32_e32 v56, v56, v104
	v_mul_f32_e32 v57, v57, v105
	v_mul_f32_e32 v58, v58, v106
	v_mul_f32_e32 v59, v59, v107
	v_cvt_pk_bf16_f32 v56, v56, v57
	v_cvt_pk_bf16_f32 v57, v58, v59
	ds_write_b64 v100, v[56:57] offset:8512
	v_add_f32_e32 v60, v97, v60
	v_add_f32_e32 v61, v97, v61
	v_add_f32_e32 v62, v97, v62
	v_add_f32_e32 v63, v97, v63
	v_lshlrev_b32_e32 v108, 16, v78
	v_and_b32_e32 v109, 0xffff0000, v78
	v_lshlrev_b32_e32 v110, 16, v79
	v_and_b32_e32 v111, 0xffff0000, v79
	v_mul_f32_e32 v60, v60, v108
	v_mul_f32_e32 v61, v61, v109
	v_mul_f32_e32 v62, v62, v110
	v_mul_f32_e32 v63, v63, v111
	v_cvt_pk_bf16_f32 v60, v60, v61
	v_cvt_pk_bf16_f32 v61, v62, v63
	ds_write_b64 v100, v[60:61] offset:8544
	v_add_f32_e32 v128, v98, v128
	v_add_f32_e32 v129, v98, v129
	v_add_f32_e32 v130, v98, v130
	v_add_f32_e32 v131, v98, v131
	v_lshlrev_b32_e32 v104, 16, v80
	v_and_b32_e32 v105, 0xffff0000, v80
	v_lshlrev_b32_e32 v106, 16, v81
	v_and_b32_e32 v107, 0xffff0000, v81
	v_mul_f32_e32 v128, v128, v104
	v_mul_f32_e32 v129, v129, v105
	v_mul_f32_e32 v130, v130, v106
	v_mul_f32_e32 v131, v131, v107
	v_cvt_pk_bf16_f32 v128, v128, v129
	v_cvt_pk_bf16_f32 v129, v130, v131
	ds_write_b64 v100, v[128:129] offset:16896
	v_add_f32_e32 v132, v98, v132
	v_add_f32_e32 v133, v98, v133
	v_add_f32_e32 v134, v98, v134
	v_add_f32_e32 v135, v98, v135
	v_lshlrev_b32_e32 v108, 16, v82
	v_and_b32_e32 v109, 0xffff0000, v82
	v_lshlrev_b32_e32 v110, 16, v83
	v_and_b32_e32 v111, 0xffff0000, v83
	v_mul_f32_e32 v132, v132, v108
	v_mul_f32_e32 v133, v133, v109
	v_mul_f32_e32 v134, v134, v110
	v_mul_f32_e32 v135, v135, v111
	v_cvt_pk_bf16_f32 v132, v132, v133
	v_cvt_pk_bf16_f32 v133, v134, v135
	ds_write_b64 v100, v[132:133] offset:16928
	v_add_f32_e32 v136, v98, v136
	v_add_f32_e32 v137, v98, v137
	v_add_f32_e32 v138, v98, v138
	v_add_f32_e32 v139, v98, v139
	v_lshlrev_b32_e32 v104, 16, v84
	v_and_b32_e32 v105, 0xffff0000, v84
	v_lshlrev_b32_e32 v106, 16, v85
	v_and_b32_e32 v107, 0xffff0000, v85
	v_mul_f32_e32 v136, v136, v104
	v_mul_f32_e32 v137, v137, v105
	v_mul_f32_e32 v138, v138, v106
	v_mul_f32_e32 v139, v139, v107
	v_cvt_pk_bf16_f32 v136, v136, v137
	v_cvt_pk_bf16_f32 v137, v138, v139
	ds_write_b64 v100, v[136:137] offset:16960
	v_add_f32_e32 v140, v98, v140
	v_add_f32_e32 v141, v98, v141
	v_add_f32_e32 v142, v98, v142
	v_add_f32_e32 v143, v98, v143
	v_lshlrev_b32_e32 v108, 16, v86
	v_and_b32_e32 v109, 0xffff0000, v86
	v_lshlrev_b32_e32 v110, 16, v87
	v_and_b32_e32 v111, 0xffff0000, v87
	v_mul_f32_e32 v140, v140, v108
	v_mul_f32_e32 v141, v141, v109
	v_mul_f32_e32 v142, v142, v110
	v_mul_f32_e32 v143, v143, v111
	v_cvt_pk_bf16_f32 v140, v140, v141
	v_cvt_pk_bf16_f32 v141, v142, v143
	ds_write_b64 v100, v[140:141] offset:16992
	v_add_f32_e32 v156, v99, v156
	v_add_f32_e32 v157, v99, v157
	v_add_f32_e32 v158, v99, v158
	v_add_f32_e32 v159, v99, v159
	v_lshlrev_b32_e32 v104, 16, v88
	v_and_b32_e32 v105, 0xffff0000, v88
	v_lshlrev_b32_e32 v106, 16, v89
	v_and_b32_e32 v107, 0xffff0000, v89
	v_mul_f32_e32 v156, v156, v104
	v_mul_f32_e32 v157, v157, v105
	v_mul_f32_e32 v158, v158, v106
	v_mul_f32_e32 v159, v159, v107
	v_cvt_pk_bf16_f32 v156, v156, v157
	v_cvt_pk_bf16_f32 v157, v158, v159
	ds_write_b64 v100, v[156:157] offset:25344
	v_add_f32_e32 v160, v99, v160
	v_add_f32_e32 v161, v99, v161
	v_add_f32_e32 v162, v99, v162
	v_add_f32_e32 v163, v99, v163
	v_lshlrev_b32_e32 v108, 16, v90
	v_and_b32_e32 v109, 0xffff0000, v90
	v_lshlrev_b32_e32 v110, 16, v91
	v_and_b32_e32 v111, 0xffff0000, v91
	v_mul_f32_e32 v160, v160, v108
	v_mul_f32_e32 v161, v161, v109
	v_mul_f32_e32 v162, v162, v110
	v_mul_f32_e32 v163, v163, v111
	v_cvt_pk_bf16_f32 v160, v160, v161
	v_cvt_pk_bf16_f32 v161, v162, v163
	ds_write_b64 v100, v[160:161] offset:25376
	v_add_f32_e32 v164, v99, v164
	v_add_f32_e32 v165, v99, v165
	v_add_f32_e32 v166, v99, v166
	v_add_f32_e32 v167, v99, v167
	v_lshlrev_b32_e32 v104, 16, v92
	v_and_b32_e32 v105, 0xffff0000, v92
	v_lshlrev_b32_e32 v106, 16, v93
	v_and_b32_e32 v107, 0xffff0000, v93
	v_mul_f32_e32 v164, v164, v104
	v_mul_f32_e32 v165, v165, v105
	v_mul_f32_e32 v166, v166, v106
	v_mul_f32_e32 v167, v167, v107
	v_cvt_pk_bf16_f32 v164, v164, v165
	v_cvt_pk_bf16_f32 v165, v166, v167
	ds_write_b64 v100, v[164:165] offset:25408
	v_add_f32_e32 v168, v99, v168
	v_add_f32_e32 v169, v99, v169
	v_add_f32_e32 v170, v99, v170
	v_add_f32_e32 v171, v99, v171
	v_lshlrev_b32_e32 v108, 16, v94
	v_and_b32_e32 v109, 0xffff0000, v94
	v_lshlrev_b32_e32 v110, 16, v95
	v_and_b32_e32 v111, 0xffff0000, v95
	v_mul_f32_e32 v168, v168, v108
	v_mul_f32_e32 v169, v169, v109
	v_mul_f32_e32 v170, v170, v110
	v_mul_f32_e32 v171, v171, v111
	v_cvt_pk_bf16_f32 v168, v168, v169
	v_cvt_pk_bf16_f32 v169, v170, v171
	ds_write_b64 v100, v[168:169] offset:25440
	s_waitcnt lgkmcnt(0)
	s_barrier
	v_lshrrev_b32_e32 v30, 5, v176
	v_and_b32_e32 v31, 31, v176
	v_mul_u32_u24_e32 v64, 0x1800, v30
	v_lshl_add_u32 v64, v31, 4, v64
	v_mul_u32_u24_e32 v65, 0x210, v30
	v_lshl_add_u32 v65, v31, 4, v65
	v_add_u32_e32 v65, 0x11000, v65
	ds_read_b128 v[68:71], v65
	ds_read_b128 v[72:75], v65 offset:8448
	ds_read_b128 v[76:79], v65 offset:16896
	ds_read_b128 v[80:83], v65 offset:25344
	ds_read_b128 v[84:87], v65 offset:33792
	ds_read_b128 v[88:91], v65 offset:42240
	ds_read_b128 v[92:95], v65 offset:50688
	ds_read_b128 v[96:99], v65 offset:59136
	s_mul_i32 s5, s0, 0x1800
	s_add_u32 s10, s66, s5
	s_addc_u32 s11, s67, 0
	s_add_u32 s10, s10, 0x1000
	s_addc_u32 s11, s11, 0
	s_waitcnt lgkmcnt(7)
	global_store_dwordx4 v64, v[68:71], s[10:11] offset:512
	s_add_u32 s10, s10, 0x18000
	s_addc_u32 s11, s11, 0
	s_waitcnt lgkmcnt(6)
	global_store_dwordx4 v64, v[72:75], s[10:11] offset:512
	s_add_u32 s10, s10, 0x18000
	s_addc_u32 s11, s11, 0
	s_waitcnt lgkmcnt(5)
	global_store_dwordx4 v64, v[76:79], s[10:11] offset:512
	s_add_u32 s10, s10, 0x18000
	s_addc_u32 s11, s11, 0
	s_waitcnt lgkmcnt(4)
	global_store_dwordx4 v64, v[80:83], s[10:11] offset:512
	s_add_u32 s10, s10, 0x18000
	s_addc_u32 s11, s11, 0
	s_waitcnt lgkmcnt(3)
	global_store_dwordx4 v64, v[84:87], s[10:11] offset:512
	s_add_u32 s10, s10, 0x18000
	s_addc_u32 s11, s11, 0
	s_waitcnt lgkmcnt(2)
	global_store_dwordx4 v64, v[88:91], s[10:11] offset:512
	s_add_u32 s10, s10, 0x18000
	s_addc_u32 s11, s11, 0
	s_waitcnt lgkmcnt(1)
	global_store_dwordx4 v64, v[92:95], s[10:11] offset:512
	s_add_u32 s10, s10, 0x18000
	s_addc_u32 s11, s11, 0
	s_waitcnt lgkmcnt(0)
	global_store_dwordx4 v64, v[96:99], s[10:11] offset:512
	v_readlane_b32 s8, v255, 40
	v_readlane_b32 s9, v255, 41
	v_readlane_b32 s10, v255, 42
	v_readlane_b32 s11, v255, 43
	v_readlane_b32 s12, v255, 44
	v_readlane_b32 s13, v255, 45
	v_readlane_b32 s14, v255, 46
	v_readlane_b32 s15, v255, 47
	s_mov_b64 s[4:5], 0
	s_mov_b64 s[2:3], -1
	s_barrier
	s_branch .LBB0_485

.LBB0_492:
	v_lshlrev_b32_e32 v4, 2, v176
	v_and_b32_e32 v144, 0x3fc, v4
	s_waitcnt lgkmcnt(0)
	v_lshl_add_u64 v[0:1], s[50:51], 0, v[144:145]
	v_add_co_u32_e32 v2, vcc, 0x1000, v0
	global_load_dword v16, v144, s[50:51]
	global_load_dword v18, v144, s[50:51] offset:1024
	global_load_dword v20, v144, s[50:51] offset:2048
	global_load_dword v22, v144, s[50:51] offset:3072
	v_addc_co_u32_e32 v3, vcc, 0, v1, vcc
	global_load_dword v24, v[2:3], off
	global_load_dword v26, v[2:3], off offset:1024
	global_load_dword v28, v[2:3], off offset:2048
	global_load_dword v30, v[2:3], off offset:3072
	v_add_co_u32_e32 v2, vcc, 0x2000, v0
	v_lshlrev_b32_e32 v8, 3, v176
	s_nop 0
	v_addc_co_u32_e32 v3, vcc, 0, v1, vcc
	global_load_dword v32, v[2:3], off
	global_load_dword v34, v[2:3], off offset:1024
	global_load_dword v36, v[2:3], off offset:2048
	global_load_dword v38, v[2:3], off offset:3072
	v_add_co_u32_e32 v2, vcc, 0x3000, v0
	s_lshl_b32 s0, s18, 6
	s_nop 0
	v_addc_co_u32_e32 v3, vcc, 0, v1, vcc
	global_load_dword v40, v[2:3], off
	global_load_dword v42, v[2:3], off offset:1024
	global_load_dword v44, v[2:3], off offset:2048
	global_load_dword v46, v[2:3], off offset:3072
	v_add_co_u32_e32 v2, vcc, 0x4000, v0
	v_and_b32_e32 v10, 0xf8, v8
	s_nop 0
	v_addc_co_u32_e32 v3, vcc, 0, v1, vcc
	global_load_dword v48, v[2:3], off
	global_load_dword v50, v[2:3], off offset:1024
	global_load_dword v52, v[2:3], off offset:2048
	global_load_dword v54, v[2:3], off offset:3072
	v_add_co_u32_e32 v2, vcc, 0x5000, v0
	s_sub_i32 s3, s0, 30
	s_nop 0
	v_addc_co_u32_e32 v3, vcc, 0, v1, vcc
	global_load_dword v56, v[2:3], off
	global_load_dword v58, v[2:3], off offset:1024
	global_load_dword v60, v[2:3], off offset:2048
	global_load_dword v62, v[2:3], off offset:3072
	v_add_co_u32_e32 v2, vcc, 0x6000, v0
	v_lshlrev_b32_e32 v8, 1, v10
	s_nop 0
	v_addc_co_u32_e32 v3, vcc, 0, v1, vcc
	v_mov_b32_e32 v9, v145
	v_ashrrev_i32_e32 v23, 5, v176
	v_add_co_u32_e32 v0, vcc, 0x7000, v0
	v_and_b32_e32 v17, 0xfc, v4
	v_lshl_add_u64 v[8:9], s[66:67], 0, v[8:9]
	v_lshl_add_u32 v21, v10, 2, 0
	v_add_u32_e32 v10, s3, v23
	v_addc_co_u32_e32 v1, vcc, 0, v1, vcc
	v_lshlrev_b32_e32 v19, 2, v17
	v_mad_i64_i32 v[14:15], s[4:5], v10, s54, v[8:9]
	global_load_dword v64, v[2:3], off
	global_load_dword v66, v[2:3], off offset:1024
	global_load_dword v68, v[2:3], off offset:2048
	global_load_dword v70, v[2:3], off offset:3072
	global_load_dword v72, v[0:1], off
	global_load_dword v74, v[0:1], off offset:1024
	global_load_dword v76, v[0:1], off offset:2048
	s_nop 0
	global_load_dwordx4 v[0:3], v19, s[68:69]
	global_load_dwordx4 v[4:7], v19, s[84:85]
	global_load_dwordx4 v[10:13], v[14:15], off offset:2560
	global_load_dwordx4 v[78:81], v[14:15], off offset:3072
	s_and_b32 s2, s0, 0xfc0
	s_sub_i32 s2, 30, s2
	v_cmp_gt_i32_e32 vcc, s2, v23
	s_waitcnt vmcnt(0)
	v_lshlrev_b32_e32 v82, 16, v11
	v_and_b32_e32 v31, 0xffff0000, v80
	v_lshlrev_b32_e32 v14, 16, v78
	v_and_b32_e32 v15, 0xffff0000, v78
	v_lshlrev_b32_e32 v29, 16, v80
	v_lshlrev_b32_e32 v33, 16, v81
	v_and_b32_e32 v35, 0xffff0000, v81
	v_lshlrev_b32_e32 v80, 16, v10
	v_and_b32_e32 v81, 0xffff0000, v10
	v_mul_f32_e32 v10, 0xbfb8aa3b, v31
	v_mul_f32_e32 v14, 0xbfb8aa3b, v14
	v_mul_f32_e32 v15, 0xbfb8aa3b, v15
	v_exp_f32_e32 v10, v10
	v_exp_f32_e32 v14, v14
	v_mul_f32_e32 v29, 0xbfb8aa3b, v29
	v_exp_f32_e32 v15, v15
	v_exp_f32_e32 v29, v29
	v_lshlrev_b32_e32 v25, 16, v79
	v_add_f32_e32 v10, 1.0, v10
	v_and_b32_e32 v27, 0xffff0000, v79
	v_add_f32_e32 v14, 1.0, v14
	v_add_f32_e32 v15, 1.0, v15
	v_rcp_f32_e32 v79, v10
	v_mul_f32_e32 v10, 0xbfb8aa3b, v25
	v_rcp_f32_e32 v14, v14
	v_add_f32_e32 v29, 1.0, v29
	v_rcp_f32_e32 v15, v15
	v_exp_f32_e32 v10, v10
	v_rcp_f32_e32 v78, v29
	v_and_b32_e32 v83, 0xffff0000, v11
	v_pk_mul_f32 v[14:15], v[14:15], v[80:81]
	v_lshlrev_b32_e32 v80, 16, v12
	v_and_b32_e32 v81, 0xffff0000, v12
	v_add_f32_e32 v10, 1.0, v10
	v_pk_mul_f32 v[78:79], v[78:79], v[80:81]
	v_rcp_f32_e32 v80, v10
	v_mul_f32_e32 v10, 0xbfb8aa3b, v33
	v_mul_f32_e32 v12, 0xbfb8aa3b, v27
	v_mul_f32_e32 v11, 0xbfb8aa3b, v35
	v_exp_f32_e32 v10, v10
	v_exp_f32_e32 v12, v12
	v_exp_f32_e32 v11, v11
	v_add_f32_e32 v10, 1.0, v10
	v_add_f32_e32 v12, 1.0, v12
	v_add_f32_e32 v11, 1.0, v11
	v_rcp_f32_e32 v10, v10
	v_rcp_f32_e32 v81, v12
	v_rcp_f32_e32 v11, v11
	v_lshlrev_b32_e32 v12, 16, v13
	v_and_b32_e32 v13, 0xffff0000, v13
	v_pk_mul_f32 v[80:81], v[80:81], v[82:83]
	v_pk_mul_f32 v[10:11], v[10:11], v[12:13]
	v_cndmask_b32_e64 v81, v81, 0, vcc
	v_cndmask_b32_e64 v13, v11, 0, vcc
	v_cndmask_b32_e64 v12, v10, 0, vcc
	v_cndmask_b32_e64 v11, v79, 0, vcc
	v_cndmask_b32_e64 v10, v78, 0, vcc
	v_cndmask_b32_e64 v80, v80, 0, vcc
	v_cndmask_b32_e64 v79, v15, 0, vcc
	v_cndmask_b32_e64 v78, v14, 0, vcc
	v_lshl_add_u32 v14, v23, 10, v21
	ds_write_b128 v14, v[78:81]
	ds_write_b128 v14, v[10:13] offset:16
	v_add_u32_e32 v10, 0x200, v176
	v_ashrrev_i32_e32 v23, 5, v10
	v_add_u32_e32 v10, s3, v23
	v_mad_i64_i32 v[14:15], s[4:5], v10, s54, v[8:9]
	global_load_dwordx4 v[10:13], v[14:15], off offset:2560
	global_load_dwordx4 v[78:81], v[14:15], off offset:3072
	v_cmp_gt_i32_e32 vcc, s2, v23
	s_waitcnt vmcnt(1)
	v_lshlrev_b32_e32 v82, 16, v11
	s_waitcnt vmcnt(0)
	v_and_b32_e32 v31, 0xffff0000, v80
	v_lshlrev_b32_e32 v14, 16, v78
	v_and_b32_e32 v15, 0xffff0000, v78
	v_lshlrev_b32_e32 v29, 16, v80
	v_lshlrev_b32_e32 v33, 16, v81
	v_and_b32_e32 v35, 0xffff0000, v81
	v_lshlrev_b32_e32 v80, 16, v10
	v_and_b32_e32 v81, 0xffff0000, v10
	v_mul_f32_e32 v10, 0xbfb8aa3b, v31
	v_mul_f32_e32 v14, 0xbfb8aa3b, v14
	v_mul_f32_e32 v15, 0xbfb8aa3b, v15
	v_exp_f32_e32 v10, v10
	v_exp_f32_e32 v14, v14
	v_mul_f32_e32 v29, 0xbfb8aa3b, v29
	v_exp_f32_e32 v15, v15
	v_exp_f32_e32 v29, v29
	v_lshlrev_b32_e32 v25, 16, v79
	v_add_f32_e32 v10, 1.0, v10
	v_and_b32_e32 v27, 0xffff0000, v79
	v_add_f32_e32 v14, 1.0, v14
	v_add_f32_e32 v15, 1.0, v15
	v_rcp_f32_e32 v79, v10
	v_mul_f32_e32 v10, 0xbfb8aa3b, v25
	v_rcp_f32_e32 v14, v14
	v_add_f32_e32 v29, 1.0, v29
	v_rcp_f32_e32 v15, v15
	v_exp_f32_e32 v10, v10
	v_rcp_f32_e32 v78, v29
	v_and_b32_e32 v83, 0xffff0000, v11
	v_pk_mul_f32 v[14:15], v[14:15], v[80:81]
	v_lshlrev_b32_e32 v80, 16, v12
	v_and_b32_e32 v81, 0xffff0000, v12
	v_add_f32_e32 v10, 1.0, v10
	v_pk_mul_f32 v[78:79], v[78:79], v[80:81]
	v_rcp_f32_e32 v80, v10
	v_mul_f32_e32 v10, 0xbfb8aa3b, v33
	v_mul_f32_e32 v12, 0xbfb8aa3b, v27
	v_mul_f32_e32 v11, 0xbfb8aa3b, v35
	v_exp_f32_e32 v10, v10
	v_exp_f32_e32 v12, v12
	v_exp_f32_e32 v11, v11
	v_add_f32_e32 v10, 1.0, v10
	v_add_f32_e32 v12, 1.0, v12
	v_add_f32_e32 v11, 1.0, v11
	v_rcp_f32_e32 v10, v10
	v_rcp_f32_e32 v81, v12
	v_rcp_f32_e32 v11, v11
	v_lshlrev_b32_e32 v12, 16, v13
	v_and_b32_e32 v13, 0xffff0000, v13
	v_pk_mul_f32 v[80:81], v[80:81], v[82:83]
	v_pk_mul_f32 v[10:11], v[10:11], v[12:13]
	v_cndmask_b32_e64 v81, v81, 0, vcc
	v_cndmask_b32_e64 v13, v11, 0, vcc
	v_cndmask_b32_e64 v12, v10, 0, vcc
	v_cndmask_b32_e64 v11, v79, 0, vcc
	v_cndmask_b32_e64 v10, v78, 0, vcc
	v_cndmask_b32_e64 v80, v80, 0, vcc
	v_cndmask_b32_e64 v79, v15, 0, vcc
	v_cndmask_b32_e64 v78, v14, 0, vcc
	v_lshl_add_u32 v14, v23, 10, v21
	ds_write_b128 v14, v[78:81]
	ds_write_b128 v14, v[10:13] offset:16
	v_add_u32_e32 v10, 0x400, v176
	v_ashrrev_i32_e32 v23, 5, v10
	v_add_u32_e32 v10, s3, v23
	v_mad_i64_i32 v[14:15], s[4:5], v10, s54, v[8:9]
	global_load_dwordx4 v[10:13], v[14:15], off offset:2560
	global_load_dwordx4 v[78:81], v[14:15], off offset:3072
	v_cmp_gt_i32_e32 vcc, s2, v23
	s_waitcnt vmcnt(1)
	v_lshlrev_b32_e32 v82, 16, v11
	s_waitcnt vmcnt(0)
	v_and_b32_e32 v31, 0xffff0000, v80
	v_lshlrev_b32_e32 v14, 16, v78
	v_and_b32_e32 v15, 0xffff0000, v78
	v_lshlrev_b32_e32 v29, 16, v80
	v_lshlrev_b32_e32 v33, 16, v81
	v_and_b32_e32 v35, 0xffff0000, v81
	v_lshlrev_b32_e32 v80, 16, v10
	v_and_b32_e32 v81, 0xffff0000, v10
	v_mul_f32_e32 v10, 0xbfb8aa3b, v31
	v_mul_f32_e32 v14, 0xbfb8aa3b, v14
	v_mul_f32_e32 v15, 0xbfb8aa3b, v15
	v_exp_f32_e32 v10, v10
	v_exp_f32_e32 v14, v14
	v_mul_f32_e32 v29, 0xbfb8aa3b, v29
	v_exp_f32_e32 v15, v15
	v_exp_f32_e32 v29, v29
	v_lshlrev_b32_e32 v25, 16, v79
	v_add_f32_e32 v10, 1.0, v10
	v_and_b32_e32 v27, 0xffff0000, v79
	v_add_f32_e32 v14, 1.0, v14
	v_add_f32_e32 v15, 1.0, v15
	v_rcp_f32_e32 v79, v10
	v_mul_f32_e32 v10, 0xbfb8aa3b, v25
	v_rcp_f32_e32 v14, v14
	v_add_f32_e32 v29, 1.0, v29
	v_rcp_f32_e32 v15, v15
	v_exp_f32_e32 v10, v10
	v_rcp_f32_e32 v78, v29
	v_and_b32_e32 v83, 0xffff0000, v11
	v_pk_mul_f32 v[14:15], v[14:15], v[80:81]
	v_lshlrev_b32_e32 v80, 16, v12
	v_and_b32_e32 v81, 0xffff0000, v12
	v_add_f32_e32 v10, 1.0, v10
	v_pk_mul_f32 v[78:79], v[78:79], v[80:81]
	v_rcp_f32_e32 v80, v10
	v_mul_f32_e32 v10, 0xbfb8aa3b, v33
	v_mul_f32_e32 v12, 0xbfb8aa3b, v27
	v_mul_f32_e32 v11, 0xbfb8aa3b, v35
	v_exp_f32_e32 v10, v10
	v_exp_f32_e32 v12, v12
	v_exp_f32_e32 v11, v11
	v_add_f32_e32 v10, 1.0, v10
	v_add_f32_e32 v12, 1.0, v12
	v_add_f32_e32 v11, 1.0, v11
	v_rcp_f32_e32 v10, v10
	v_rcp_f32_e32 v81, v12
	v_rcp_f32_e32 v11, v11
	v_lshlrev_b32_e32 v12, 16, v13
	v_and_b32_e32 v13, 0xffff0000, v13
	v_pk_mul_f32 v[80:81], v[80:81], v[82:83]
	v_pk_mul_f32 v[10:11], v[10:11], v[12:13]
	v_cndmask_b32_e64 v81, v81, 0, vcc
	v_cndmask_b32_e64 v13, v11, 0, vcc
	v_cndmask_b32_e64 v12, v10, 0, vcc
	v_cndmask_b32_e64 v11, v79, 0, vcc
	v_cndmask_b32_e64 v10, v78, 0, vcc
	v_cndmask_b32_e64 v80, v80, 0, vcc
	v_cndmask_b32_e64 v79, v15, 0, vcc
	v_cndmask_b32_e64 v78, v14, 0, vcc
	v_lshl_add_u32 v14, v23, 10, v21
	ds_write_b128 v14, v[78:81]
	ds_write_b128 v14, v[10:13] offset:16
	v_add_u32_e32 v10, 0x600, v176
	v_ashrrev_i32_e32 v23, 5, v10
	v_add_u32_e32 v10, s3, v23
	v_mad_i64_i32 v[14:15], s[4:5], v10, s54, v[8:9]
	global_load_dwordx4 v[10:13], v[14:15], off offset:2560
	global_load_dwordx4 v[78:81], v[14:15], off offset:3072
	v_cmp_gt_i32_e32 vcc, s2, v23
	s_waitcnt vmcnt(1)
	v_lshlrev_b32_e32 v82, 16, v11
	s_waitcnt vmcnt(0)
	v_and_b32_e32 v31, 0xffff0000, v80
	v_lshlrev_b32_e32 v14, 16, v78
	v_and_b32_e32 v15, 0xffff0000, v78
	v_lshlrev_b32_e32 v29, 16, v80
	v_lshlrev_b32_e32 v33, 16, v81
	v_and_b32_e32 v35, 0xffff0000, v81
	v_lshlrev_b32_e32 v80, 16, v10
	v_and_b32_e32 v81, 0xffff0000, v10
	v_mul_f32_e32 v10, 0xbfb8aa3b, v31
	v_mul_f32_e32 v14, 0xbfb8aa3b, v14
	v_mul_f32_e32 v15, 0xbfb8aa3b, v15
	v_exp_f32_e32 v10, v10
	v_exp_f32_e32 v14, v14
	v_mul_f32_e32 v29, 0xbfb8aa3b, v29
	v_exp_f32_e32 v15, v15
	v_exp_f32_e32 v29, v29
	v_lshlrev_b32_e32 v25, 16, v79
	v_add_f32_e32 v10, 1.0, v10
	v_and_b32_e32 v27, 0xffff0000, v79
	v_add_f32_e32 v14, 1.0, v14
	v_add_f32_e32 v15, 1.0, v15
	v_rcp_f32_e32 v79, v10
	v_mul_f32_e32 v10, 0xbfb8aa3b, v25
	v_rcp_f32_e32 v14, v14
	v_add_f32_e32 v29, 1.0, v29
	v_rcp_f32_e32 v15, v15
	v_exp_f32_e32 v10, v10
	v_rcp_f32_e32 v78, v29
	v_and_b32_e32 v83, 0xffff0000, v11
	v_pk_mul_f32 v[14:15], v[14:15], v[80:81]
	v_lshlrev_b32_e32 v80, 16, v12
	v_and_b32_e32 v81, 0xffff0000, v12
	v_add_f32_e32 v10, 1.0, v10
	v_pk_mul_f32 v[78:79], v[78:79], v[80:81]
	v_rcp_f32_e32 v80, v10
	v_mul_f32_e32 v10, 0xbfb8aa3b, v33
	v_mul_f32_e32 v12, 0xbfb8aa3b, v27
	v_mul_f32_e32 v11, 0xbfb8aa3b, v35
	v_exp_f32_e32 v10, v10
	v_exp_f32_e32 v12, v12
	v_exp_f32_e32 v11, v11
	v_add_f32_e32 v10, 1.0, v10
	v_add_f32_e32 v12, 1.0, v12
	v_add_f32_e32 v11, 1.0, v11
	v_rcp_f32_e32 v10, v10
	v_rcp_f32_e32 v81, v12
	v_rcp_f32_e32 v11, v11
	v_lshlrev_b32_e32 v12, 16, v13
	v_and_b32_e32 v13, 0xffff0000, v13
	v_pk_mul_f32 v[80:81], v[80:81], v[82:83]
	v_pk_mul_f32 v[10:11], v[10:11], v[12:13]
	v_cndmask_b32_e64 v81, v81, 0, vcc
	v_cndmask_b32_e64 v13, v11, 0, vcc
	v_cndmask_b32_e64 v12, v10, 0, vcc
	v_cndmask_b32_e64 v11, v79, 0, vcc
	v_cndmask_b32_e64 v10, v78, 0, vcc
	v_cndmask_b32_e64 v80, v80, 0, vcc
	v_cndmask_b32_e64 v79, v15, 0, vcc
	v_cndmask_b32_e64 v78, v14, 0, vcc
	v_lshl_add_u32 v14, v23, 10, v21
	ds_write_b128 v14, v[78:81]
	ds_write_b128 v14, v[10:13] offset:16
	v_add_u32_e32 v10, 0x800, v176
	v_ashrrev_i32_e32 v23, 5, v10
	v_add_u32_e32 v10, s3, v23
	v_mad_i64_i32 v[14:15], s[4:5], v10, s54, v[8:9]
	global_load_dwordx4 v[10:13], v[14:15], off offset:2560
	global_load_dwordx4 v[78:81], v[14:15], off offset:3072
	v_cmp_gt_i32_e32 vcc, s2, v23
	s_waitcnt vmcnt(1)
	v_lshlrev_b32_e32 v82, 16, v11
	s_waitcnt vmcnt(0)
	v_and_b32_e32 v31, 0xffff0000, v80
	v_lshlrev_b32_e32 v14, 16, v78
	v_and_b32_e32 v15, 0xffff0000, v78
	v_lshlrev_b32_e32 v29, 16, v80
	v_lshlrev_b32_e32 v33, 16, v81
	v_and_b32_e32 v35, 0xffff0000, v81
	v_lshlrev_b32_e32 v80, 16, v10
	v_and_b32_e32 v81, 0xffff0000, v10
	v_mul_f32_e32 v10, 0xbfb8aa3b, v31
	v_mul_f32_e32 v14, 0xbfb8aa3b, v14
	v_mul_f32_e32 v15, 0xbfb8aa3b, v15
	v_exp_f32_e32 v10, v10
	v_exp_f32_e32 v14, v14
	v_mul_f32_e32 v29, 0xbfb8aa3b, v29
	v_exp_f32_e32 v15, v15
	v_exp_f32_e32 v29, v29
	v_lshlrev_b32_e32 v25, 16, v79
	v_add_f32_e32 v10, 1.0, v10
	v_and_b32_e32 v27, 0xffff0000, v79
	v_add_f32_e32 v14, 1.0, v14
	v_add_f32_e32 v15, 1.0, v15
	v_rcp_f32_e32 v79, v10
	v_mul_f32_e32 v10, 0xbfb8aa3b, v25
	v_rcp_f32_e32 v14, v14
	v_add_f32_e32 v29, 1.0, v29
	v_rcp_f32_e32 v15, v15
	v_exp_f32_e32 v10, v10
	v_rcp_f32_e32 v78, v29
	v_and_b32_e32 v83, 0xffff0000, v11
	v_pk_mul_f32 v[14:15], v[14:15], v[80:81]
	v_lshlrev_b32_e32 v80, 16, v12
	v_and_b32_e32 v81, 0xffff0000, v12
	v_add_f32_e32 v10, 1.0, v10
	v_pk_mul_f32 v[78:79], v[78:79], v[80:81]
	v_rcp_f32_e32 v80, v10
	v_mul_f32_e32 v10, 0xbfb8aa3b, v33
	v_mul_f32_e32 v12, 0xbfb8aa3b, v27
	v_mul_f32_e32 v11, 0xbfb8aa3b, v35
	v_exp_f32_e32 v10, v10
	v_exp_f32_e32 v12, v12
	v_exp_f32_e32 v11, v11
	v_add_f32_e32 v10, 1.0, v10
	v_add_f32_e32 v12, 1.0, v12
	v_add_f32_e32 v11, 1.0, v11
	v_rcp_f32_e32 v10, v10
	v_rcp_f32_e32 v81, v12
	v_rcp_f32_e32 v11, v11
	v_lshlrev_b32_e32 v12, 16, v13
	v_and_b32_e32 v13, 0xffff0000, v13
	v_pk_mul_f32 v[80:81], v[80:81], v[82:83]
	v_pk_mul_f32 v[10:11], v[10:11], v[12:13]
	v_cndmask_b32_e64 v81, v81, 0, vcc
	v_cndmask_b32_e64 v13, v11, 0, vcc
	v_cndmask_b32_e64 v12, v10, 0, vcc
	v_cndmask_b32_e64 v11, v79, 0, vcc
	v_cndmask_b32_e64 v10, v78, 0, vcc
	v_cndmask_b32_e64 v80, v80, 0, vcc
	v_cndmask_b32_e64 v79, v15, 0, vcc
	v_cndmask_b32_e64 v78, v14, 0, vcc
	v_lshl_add_u32 v14, v23, 10, v21
	ds_write_b128 v14, v[78:81]
	ds_write_b128 v14, v[10:13] offset:16
	v_add_u32_e32 v10, 0xa00, v176
	v_ashrrev_i32_e32 v23, 5, v10
	v_add_u32_e32 v10, s3, v23
	v_mad_i64_i32 v[12:13], s[4:5], v10, s54, v[8:9]
	global_load_dwordx4 v[8:11], v[12:13], off offset:2560
	s_nop 0
	global_load_dwordx4 v[12:15], v[12:13], off offset:3072
	v_cmp_gt_i32_e32 vcc, s2, v23
	v_lshl_add_u32 v21, v23, 10, v21
	s_mov_b32 s4, 0xf800000
	s_waitcnt vmcnt(1)
	v_lshlrev_b32_e32 v78, 16, v8
	s_waitcnt vmcnt(0)
	v_lshlrev_b32_e32 v29, 16, v13
	v_and_b32_e32 v31, 0xffff0000, v13
	v_lshlrev_b32_e32 v13, 16, v14
	v_mul_f32_e32 v13, 0xbfb8aa3b, v13
	v_exp_f32_e32 v13, v13
	v_and_b32_e32 v33, 0xffff0000, v14
	v_lshlrev_b32_e32 v25, 16, v12
	v_and_b32_e32 v27, 0xffff0000, v12
	v_add_f32_e32 v13, 1.0, v13
	v_and_b32_e32 v79, 0xffff0000, v8
	v_mul_f32_e32 v8, 0xbfb8aa3b, v33
	v_mul_f32_e32 v12, 0xbfb8aa3b, v25
	v_rcp_f32_e32 v14, v13
	v_mul_f32_e32 v13, 0xbfb8aa3b, v27
	v_exp_f32_e32 v8, v8
	v_exp_f32_e32 v12, v12
	v_exp_f32_e32 v13, v13
	v_lshlrev_b32_e32 v35, 16, v15
	v_add_f32_e32 v8, 1.0, v8
	v_and_b32_e32 v37, 0xffff0000, v15
	v_add_f32_e32 v12, 1.0, v12
	v_add_f32_e32 v13, 1.0, v13
	v_rcp_f32_e32 v15, v8
	v_mul_f32_e32 v8, 0xbfb8aa3b, v29
	v_rcp_f32_e32 v12, v12
	v_rcp_f32_e32 v13, v13
	v_exp_f32_e32 v8, v8
	v_lshlrev_b32_e32 v80, 16, v9
	v_and_b32_e32 v81, 0xffff0000, v9
	v_pk_mul_f32 v[12:13], v[12:13], v[78:79]
	v_lshlrev_b32_e32 v78, 16, v10
	v_and_b32_e32 v79, 0xffff0000, v10
	v_add_f32_e32 v8, 1.0, v8
	v_pk_mul_f32 v[14:15], v[14:15], v[78:79]
	v_rcp_f32_e32 v78, v8
	v_mul_f32_e32 v8, 0xbfb8aa3b, v35
	v_mul_f32_e32 v10, 0xbfb8aa3b, v31
	v_mul_f32_e32 v9, 0xbfb8aa3b, v37
	v_exp_f32_e32 v8, v8
	v_exp_f32_e32 v10, v10
	v_exp_f32_e32 v9, v9
	v_cndmask_b32_e64 v13, v13, 0, vcc
	v_add_f32_e32 v8, 1.0, v8
	v_add_f32_e32 v10, 1.0, v10
	v_add_f32_e32 v9, 1.0, v9
	v_rcp_f32_e32 v8, v8
	v_rcp_f32_e32 v79, v10
	v_rcp_f32_e32 v9, v9
	v_lshlrev_b32_e32 v10, 16, v11
	v_and_b32_e32 v11, 0xffff0000, v11
	v_pk_mul_f32 v[78:79], v[78:79], v[80:81]
	v_pk_mul_f32 v[8:9], v[8:9], v[10:11]
	v_cndmask_b32_e64 v12, v12, 0, vcc
	v_cndmask_b32_e64 v11, v9, 0, vcc
	v_cndmask_b32_e64 v10, v8, 0, vcc
	v_cndmask_b32_e64 v9, v15, 0, vcc
	v_cndmask_b32_e64 v8, v14, 0, vcc
	v_cndmask_b32_e64 v15, v79, 0, vcc
	v_cndmask_b32_e64 v14, v78, 0, vcc
	ds_write_b128 v21, v[12:15]
	ds_write_b128 v21, v[8:11] offset:16
	v_lshlrev_b32_e32 v8, 6, v176
	v_and_b32_e32 v8, 0xffffc000, v8
	v_add3_u32 v21, 0, v8, v144
	s_waitcnt lgkmcnt(0)
	s_barrier
	ds_read2st64_b32 v[8:9], v21 offset1:4
	ds_read2st64_b32 v[136:137], v21 offset0:128 offset1:132
	v_add_u32_e32 v23, 0x8000, v21
	v_lshlrev_b32_e32 v144, 1, v17
	s_waitcnt lgkmcnt(1)
	v_mov_b32_e32 v138, v8
	v_mov_b32_e32 v124, v9
	ds_read2st64_b32 v[8:9], v21 offset0:8 offset1:12
	ds_read2st64_b32 v[142:143], v21 offset0:136 offset1:140
	s_waitcnt lgkmcnt(2)
	v_mov_b32_e32 v139, v136
	v_mov_b32_e32 v125, v137
	v_pk_fma_f32 v[138:139], v[16:17], v[138:139], 0 op_sel_hi:[0,1,0]
	s_waitcnt lgkmcnt(1)
	v_mov_b32_e32 v126, v8
	v_mov_b32_e32 v116, v9
	ds_read2st64_b32 v[8:9], v21 offset0:16 offset1:20
	ds_read2st64_b32 v[158:159], v21 offset0:144 offset1:148
	s_waitcnt lgkmcnt(2)
	v_mov_b32_e32 v127, v142
	v_pk_fma_f32 v[138:139], v[18:19], v[124:125], v[138:139] op_sel_hi:[0,1,1]
	v_pk_fma_f32 v[124:125], v[16:17], v[124:125], 0 op_sel_hi:[0,1,0]
	s_waitcnt lgkmcnt(1)
	v_mov_b32_e32 v118, v8
	v_mov_b32_e32 v108, v9
	ds_read2st64_b32 v[8:9], v21 offset0:24 offset1:28
	ds_read2st64_b32 v[162:163], v21 offset0:152 offset1:156
	v_mov_b32_e32 v117, v143
	v_pk_fma_f32 v[138:139], v[20:21], v[126:127], v[138:139] op_sel_hi:[0,1,1]
	v_pk_fma_f32 v[124:125], v[18:19], v[126:127], v[124:125] op_sel_hi:[0,1,1]
	s_waitcnt lgkmcnt(1)
	v_mov_b32_e32 v110, v8
	v_mov_b32_e32 v100, v9
	ds_read2st64_b32 v[8:9], v21 offset0:32 offset1:36
	ds_read2st64_b32 v[166:167], v21 offset0:160 offset1:164
	v_pk_fma_f32 v[126:127], v[16:17], v[126:127], 0 op_sel_hi:[0,1,0]
	v_mov_b32_e32 v119, v158
	v_pk_fma_f32 v[138:139], v[22:23], v[116:117], v[138:139] op_sel_hi:[0,1,1]
	s_waitcnt lgkmcnt(1)
	v_mov_b32_e32 v102, v8
	v_mov_b32_e32 v92, v9
	ds_read2st64_b32 v[8:9], v21 offset0:40 offset1:44
	ds_read2st64_b32 v[170:171], v21 offset0:168 offset1:172
	v_pk_fma_f32 v[124:125], v[20:21], v[116:117], v[124:125] op_sel_hi:[0,1,1]
	v_pk_fma_f32 v[126:127], v[18:19], v[116:117], v[126:127] op_sel_hi:[0,1,1]
	v_pk_fma_f32 v[116:117], v[16:17], v[116:117], 0 op_sel_hi:[0,1,0]
	s_waitcnt lgkmcnt(1)
	v_mov_b32_e32 v94, v8
	v_mov_b32_e32 v84, v9
	ds_read2st64_b32 v[8:9], v21 offset0:48 offset1:52
	ds_read2st64_b32 v[174:175], v21 offset0:176 offset1:180
	v_mov_b32_e32 v109, v159
	v_pk_fma_f32 v[138:139], v[24:25], v[118:119], v[138:139] op_sel_hi:[0,1,1]
	v_pk_fma_f32 v[124:125], v[22:23], v[118:119], v[124:125] op_sel_hi:[0,1,1]
	s_waitcnt lgkmcnt(1)
	v_mov_b32_e32 v86, v8
	v_mov_b32_e32 v14, v9
	ds_read2st64_b32 v[10:11], v21 offset0:56 offset1:60
	ds_read2st64_b32 v[8:9], v21 offset0:184 offset1:188
	v_pk_fma_f32 v[126:127], v[20:21], v[118:119], v[126:127] op_sel_hi:[0,1,1]
	v_pk_fma_f32 v[116:117], v[18:19], v[118:119], v[116:117] op_sel_hi:[0,1,1]
	v_pk_fma_f32 v[118:119], v[16:17], v[118:119], 0 op_sel_hi:[0,1,0]
	s_waitcnt lgkmcnt(1)
	v_mov_b32_e32 v78, v10
	s_waitcnt lgkmcnt(0)
	v_mov_b32_e32 v79, v8
	v_mov_b32_e32 v8, v11
	ds_read2st64_b32 v[80:81], v21 offset0:64 offset1:68
	ds_read2st64_b32 v[10:11], v21 offset0:192 offset1:196
	v_mov_b32_e32 v111, v162
	v_pk_fma_f32 v[138:139], v[26:27], v[108:109], v[138:139] op_sel_hi:[0,1,1]
	v_pk_fma_f32 v[124:125], v[24:25], v[108:109], v[124:125] op_sel_hi:[0,1,1]
	s_waitcnt lgkmcnt(1)
	v_mov_b32_e32 v12, v80
	s_waitcnt lgkmcnt(0)
	v_mov_b32_e32 v13, v10
	v_mov_b32_e32 v10, v81
	ds_read2st64_b32 v[88:89], v21 offset0:72 offset1:76
	ds_read2st64_b32 v[80:81], v21 offset0:200 offset1:204
	v_pk_fma_f32 v[126:127], v[22:23], v[108:109], v[126:127] op_sel_hi:[0,1,1]
	v_pk_fma_f32 v[116:117], v[20:21], v[108:109], v[116:117] op_sel_hi:[0,1,1]
	v_pk_fma_f32 v[118:119], v[18:19], v[108:109], v[118:119] op_sel_hi:[0,1,1]
	s_waitcnt lgkmcnt(1)
	v_mov_b32_e32 v82, v88
	s_waitcnt lgkmcnt(0)
	v_mov_b32_e32 v83, v80
	v_mov_b32_e32 v80, v89
	ds_read2st64_b32 v[96:97], v21 offset0:80 offset1:84
	ds_read2st64_b32 v[88:89], v21 offset0:208 offset1:212
	v_pk_fma_f32 v[108:109], v[16:17], v[108:109], 0 op_sel_hi:[0,1,0]
	v_mov_b32_e32 v101, v163
	v_pk_fma_f32 v[138:139], v[28:29], v[110:111], v[138:139] op_sel_hi:[0,1,1]
	s_waitcnt lgkmcnt(1)
	v_mov_b32_e32 v90, v96
	s_waitcnt lgkmcnt(0)
	v_mov_b32_e32 v91, v88
	v_mov_b32_e32 v88, v97
	ds_read2st64_b32 v[104:105], v21 offset0:88 offset1:92
	ds_read2st64_b32 v[96:97], v21 offset0:216 offset1:220
	v_pk_fma_f32 v[124:125], v[26:27], v[110:111], v[124:125] op_sel_hi:[0,1,1]
	v_pk_fma_f32 v[126:127], v[24:25], v[110:111], v[126:127] op_sel_hi:[0,1,1]
	v_pk_fma_f32 v[116:117], v[22:23], v[110:111], v[116:117] op_sel_hi:[0,1,1]
	s_waitcnt lgkmcnt(1)
	v_mov_b32_e32 v98, v104
	s_waitcnt lgkmcnt(0)
	v_mov_b32_e32 v99, v96
	v_mov_b32_e32 v96, v105
	ds_read2st64_b32 v[112:113], v21 offset0:96 offset1:100
	ds_read2st64_b32 v[104:105], v21 offset0:224 offset1:228
	v_pk_fma_f32 v[118:119], v[20:21], v[110:111], v[118:119] op_sel_hi:[0,1,1]
	v_pk_fma_f32 v[108:109], v[18:19], v[110:111], v[108:109] op_sel_hi:[0,1,1]
	v_pk_fma_f32 v[110:111], v[16:17], v[110:111], 0 op_sel_hi:[0,1,0]
	s_waitcnt lgkmcnt(1)
	v_mov_b32_e32 v106, v112
	s_waitcnt lgkmcnt(0)
	v_mov_b32_e32 v107, v104
	v_mov_b32_e32 v104, v113
	ds_read2st64_b32 v[120:121], v21 offset0:104 offset1:108
	ds_read2st64_b32 v[112:113], v21 offset0:232 offset1:236
	v_mov_b32_e32 v103, v166
	v_pk_fma_f32 v[138:139], v[30:31], v[100:101], v[138:139] op_sel_hi:[0,1,1]
	v_pk_fma_f32 v[124:125], v[28:29], v[100:101], v[124:125] op_sel_hi:[0,1,1]
	s_waitcnt lgkmcnt(1)
	v_mov_b32_e32 v114, v120
	s_waitcnt lgkmcnt(0)
	v_mov_b32_e32 v115, v112
	v_mov_b32_e32 v112, v121
	ds_read2st64_b32 v[128:129], v21 offset0:112 offset1:116
	ds_read2st64_b32 v[120:121], v21 offset0:240 offset1:244
	v_pk_fma_f32 v[126:127], v[26:27], v[100:101], v[126:127] op_sel_hi:[0,1,1]
	v_pk_fma_f32 v[116:117], v[24:25], v[100:101], v[116:117] op_sel_hi:[0,1,1]
	v_pk_fma_f32 v[118:119], v[22:23], v[100:101], v[118:119] op_sel_hi:[0,1,1]
	s_waitcnt lgkmcnt(1)
	v_mov_b32_e32 v122, v128
	s_waitcnt lgkmcnt(0)
	v_mov_b32_e32 v123, v120
	v_mov_b32_e32 v120, v129
	ds_read2st64_b32 v[132:133], v21 offset0:120 offset1:124
	ds_read2st64_b32 v[128:129], v21 offset0:248 offset1:252
	v_pk_fma_f32 v[108:109], v[20:21], v[100:101], v[108:109] op_sel_hi:[0,1,1]
	v_pk_fma_f32 v[110:111], v[18:19], v[100:101], v[110:111] op_sel_hi:[0,1,1]
	v_pk_fma_f32 v[100:101], v[16:17], v[100:101], 0 op_sel_hi:[0,1,0]
	v_mov_b32_e32 v93, v167
	s_waitcnt lgkmcnt(1)
	v_mov_b32_e32 v130, v132
	s_waitcnt lgkmcnt(0)
	v_mov_b32_e32 v131, v128
	v_mov_b32_e32 v128, v133
	ds_read2st64_b32 v[132:133], v23 offset0:128 offset1:132
	v_pk_fma_f32 v[138:139], v[32:33], v[102:103], v[138:139] op_sel_hi:[0,1,1]
	v_pk_fma_f32 v[124:125], v[30:31], v[102:103], v[124:125] op_sel_hi:[0,1,1]
	v_pk_fma_f32 v[126:127], v[28:29], v[102:103], v[126:127] op_sel_hi:[0,1,1]
	v_pk_fma_f32 v[116:117], v[26:27], v[102:103], v[116:117] op_sel_hi:[0,1,1]
	v_pk_fma_f32 v[118:119], v[24:25], v[102:103], v[118:119] op_sel_hi:[0,1,1]
	v_pk_fma_f32 v[108:109], v[22:23], v[102:103], v[108:109] op_sel_hi:[0,1,1]
	v_pk_fma_f32 v[110:111], v[20:21], v[102:103], v[110:111] op_sel_hi:[0,1,1]
	v_pk_fma_f32 v[100:101], v[18:19], v[102:103], v[100:101] op_sel_hi:[0,1,1]
	v_pk_fma_f32 v[102:103], v[16:17], v[102:103], 0 op_sel_hi:[0,1,0]
	v_mov_b32_e32 v95, v170
	v_pk_fma_f32 v[138:139], v[34:35], v[92:93], v[138:139] op_sel_hi:[0,1,1]
	v_pk_fma_f32 v[124:125], v[32:33], v[92:93], v[124:125] op_sel_hi:[0,1,1]
	v_pk_fma_f32 v[126:127], v[30:31], v[92:93], v[126:127] op_sel_hi:[0,1,1]
	v_pk_fma_f32 v[116:117], v[28:29], v[92:93], v[116:117] op_sel_hi:[0,1,1]
	v_pk_fma_f32 v[118:119], v[26:27], v[92:93], v[118:119] op_sel_hi:[0,1,1]
	v_pk_fma_f32 v[108:109], v[24:25], v[92:93], v[108:109] op_sel_hi:[0,1,1]
	v_pk_fma_f32 v[110:111], v[22:23], v[92:93], v[110:111] op_sel_hi:[0,1,1]
	v_pk_fma_f32 v[100:101], v[20:21], v[92:93], v[100:101] op_sel_hi:[0,1,1]
	v_pk_fma_f32 v[102:103], v[18:19], v[92:93], v[102:103] op_sel_hi:[0,1,1]
	v_pk_fma_f32 v[92:93], v[16:17], v[92:93], 0 op_sel_hi:[0,1,0]
	v_mov_b32_e32 v85, v171
	v_pk_fma_f32 v[138:139], v[36:37], v[94:95], v[138:139] op_sel_hi:[0,1,1]
	v_pk_fma_f32 v[124:125], v[34:35], v[94:95], v[124:125] op_sel_hi:[0,1,1]
	v_pk_fma_f32 v[126:127], v[32:33], v[94:95], v[126:127] op_sel_hi:[0,1,1]
	v_pk_fma_f32 v[116:117], v[30:31], v[94:95], v[116:117] op_sel_hi:[0,1,1]
	v_pk_fma_f32 v[118:119], v[28:29], v[94:95], v[118:119] op_sel_hi:[0,1,1]
	v_pk_fma_f32 v[108:109], v[26:27], v[94:95], v[108:109] op_sel_hi:[0,1,1]
	v_pk_fma_f32 v[110:111], v[24:25], v[94:95], v[110:111] op_sel_hi:[0,1,1]
	v_pk_fma_f32 v[100:101], v[22:23], v[94:95], v[100:101] op_sel_hi:[0,1,1]
	v_pk_fma_f32 v[102:103], v[20:21], v[94:95], v[102:103] op_sel_hi:[0,1,1]
	v_pk_fma_f32 v[92:93], v[18:19], v[94:95], v[92:93] op_sel_hi:[0,1,1]
	v_pk_fma_f32 v[94:95], v[16:17], v[94:95], 0 op_sel_hi:[0,1,0]
	v_mov_b32_e32 v87, v174
	v_pk_fma_f32 v[138:139], v[38:39], v[84:85], v[138:139] op_sel_hi:[0,1,1]
	v_pk_fma_f32 v[124:125], v[36:37], v[84:85], v[124:125] op_sel_hi:[0,1,1]
	v_pk_fma_f32 v[126:127], v[34:35], v[84:85], v[126:127] op_sel_hi:[0,1,1]
	v_pk_fma_f32 v[116:117], v[32:33], v[84:85], v[116:117] op_sel_hi:[0,1,1]
	v_pk_fma_f32 v[118:119], v[30:31], v[84:85], v[118:119] op_sel_hi:[0,1,1]
	v_pk_fma_f32 v[108:109], v[28:29], v[84:85], v[108:109] op_sel_hi:[0,1,1]
	v_pk_fma_f32 v[110:111], v[26:27], v[84:85], v[110:111] op_sel_hi:[0,1,1]
	v_pk_fma_f32 v[100:101], v[24:25], v[84:85], v[100:101] op_sel_hi:[0,1,1]
	v_pk_fma_f32 v[102:103], v[22:23], v[84:85], v[102:103] op_sel_hi:[0,1,1]
	v_pk_fma_f32 v[92:93], v[20:21], v[84:85], v[92:93] op_sel_hi:[0,1,1]
	v_pk_fma_f32 v[94:95], v[18:19], v[84:85], v[94:95] op_sel_hi:[0,1,1]
	v_pk_fma_f32 v[84:85], v[16:17], v[84:85], 0 op_sel_hi:[0,1,0]
	v_mov_b32_e32 v15, v175
	v_pk_fma_f32 v[138:139], v[40:41], v[86:87], v[138:139] op_sel_hi:[0,1,1]
	v_pk_fma_f32 v[124:125], v[38:39], v[86:87], v[124:125] op_sel_hi:[0,1,1]
	v_pk_fma_f32 v[126:127], v[36:37], v[86:87], v[126:127] op_sel_hi:[0,1,1]
	v_pk_fma_f32 v[116:117], v[34:35], v[86:87], v[116:117] op_sel_hi:[0,1,1]
	v_pk_fma_f32 v[118:119], v[32:33], v[86:87], v[118:119] op_sel_hi:[0,1,1]
	v_pk_fma_f32 v[108:109], v[30:31], v[86:87], v[108:109] op_sel_hi:[0,1,1]
	v_pk_fma_f32 v[110:111], v[28:29], v[86:87], v[110:111] op_sel_hi:[0,1,1]
	v_pk_fma_f32 v[100:101], v[26:27], v[86:87], v[100:101] op_sel_hi:[0,1,1]
	v_pk_fma_f32 v[102:103], v[24:25], v[86:87], v[102:103] op_sel_hi:[0,1,1]
	v_pk_fma_f32 v[92:93], v[22:23], v[86:87], v[92:93] op_sel_hi:[0,1,1]
	v_pk_fma_f32 v[94:95], v[20:21], v[86:87], v[94:95] op_sel_hi:[0,1,1]
	v_pk_fma_f32 v[84:85], v[18:19], v[86:87], v[84:85] op_sel_hi:[0,1,1]
	v_pk_fma_f32 v[86:87], v[16:17], v[86:87], 0 op_sel_hi:[0,1,0]
	v_mov_b32_e32 v134, v136
	s_waitcnt lgkmcnt(0)
	v_mov_b32_e32 v135, v132
	v_mov_b32_e32 v132, v137
	ds_read2st64_b32 v[136:137], v23 offset0:136 offset1:140
	v_pk_fma_f32 v[138:139], v[42:43], v[14:15], v[138:139] op_sel_hi:[0,1,1]
	v_pk_fma_f32 v[124:125], v[40:41], v[14:15], v[124:125] op_sel_hi:[0,1,1]
	v_pk_fma_f32 v[126:127], v[38:39], v[14:15], v[126:127] op_sel_hi:[0,1,1]
	v_pk_fma_f32 v[116:117], v[36:37], v[14:15], v[116:117] op_sel_hi:[0,1,1]
	v_pk_fma_f32 v[118:119], v[34:35], v[14:15], v[118:119] op_sel_hi:[0,1,1]
	v_pk_fma_f32 v[108:109], v[32:33], v[14:15], v[108:109] op_sel_hi:[0,1,1]
	v_pk_fma_f32 v[110:111], v[30:31], v[14:15], v[110:111] op_sel_hi:[0,1,1]
	v_pk_fma_f32 v[100:101], v[28:29], v[14:15], v[100:101] op_sel_hi:[0,1,1]
	v_pk_fma_f32 v[102:103], v[26:27], v[14:15], v[102:103] op_sel_hi:[0,1,1]
	v_pk_fma_f32 v[92:93], v[24:25], v[14:15], v[92:93] op_sel_hi:[0,1,1]
	v_pk_fma_f32 v[94:95], v[22:23], v[14:15], v[94:95] op_sel_hi:[0,1,1]
	v_pk_fma_f32 v[84:85], v[20:21], v[14:15], v[84:85] op_sel_hi:[0,1,1]
	v_pk_fma_f32 v[86:87], v[18:19], v[14:15], v[86:87] op_sel_hi:[0,1,1]
	v_pk_fma_f32 v[14:15], v[16:17], v[14:15], 0 op_sel_hi:[0,1,0]
	v_pk_fma_f32 v[138:139], v[44:45], v[78:79], v[138:139] op_sel_hi:[0,1,1]
	v_pk_fma_f32 v[124:125], v[42:43], v[78:79], v[124:125] op_sel_hi:[0,1,1]
	v_pk_fma_f32 v[126:127], v[40:41], v[78:79], v[126:127] op_sel_hi:[0,1,1]
	v_pk_fma_f32 v[116:117], v[38:39], v[78:79], v[116:117] op_sel_hi:[0,1,1]
	v_pk_fma_f32 v[118:119], v[36:37], v[78:79], v[118:119] op_sel_hi:[0,1,1]
	v_pk_fma_f32 v[108:109], v[34:35], v[78:79], v[108:109] op_sel_hi:[0,1,1]
	v_pk_fma_f32 v[110:111], v[32:33], v[78:79], v[110:111] op_sel_hi:[0,1,1]
	v_pk_fma_f32 v[100:101], v[30:31], v[78:79], v[100:101] op_sel_hi:[0,1,1]
	v_pk_fma_f32 v[102:103], v[28:29], v[78:79], v[102:103] op_sel_hi:[0,1,1]
	v_pk_fma_f32 v[92:93], v[26:27], v[78:79], v[92:93] op_sel_hi:[0,1,1]
	v_pk_fma_f32 v[94:95], v[24:25], v[78:79], v[94:95] op_sel_hi:[0,1,1]
	v_pk_fma_f32 v[84:85], v[22:23], v[78:79], v[84:85] op_sel_hi:[0,1,1]
	v_pk_fma_f32 v[86:87], v[20:21], v[78:79], v[86:87] op_sel_hi:[0,1,1]
	v_pk_fma_f32 v[14:15], v[18:19], v[78:79], v[14:15] op_sel_hi:[0,1,1]
	v_pk_fma_f32 v[78:79], v[16:17], v[78:79], 0 op_sel_hi:[0,1,0]
	v_pk_fma_f32 v[138:139], v[46:47], v[8:9], v[138:139] op_sel_hi:[0,1,1]
	v_pk_fma_f32 v[124:125], v[44:45], v[8:9], v[124:125] op_sel_hi:[0,1,1]
	v_pk_fma_f32 v[126:127], v[42:43], v[8:9], v[126:127] op_sel_hi:[0,1,1]
	v_pk_fma_f32 v[116:117], v[40:41], v[8:9], v[116:117] op_sel_hi:[0,1,1]
	v_pk_fma_f32 v[118:119], v[38:39], v[8:9], v[118:119] op_sel_hi:[0,1,1]
	v_pk_fma_f32 v[108:109], v[36:37], v[8:9], v[108:109] op_sel_hi:[0,1,1]
	v_pk_fma_f32 v[110:111], v[34:35], v[8:9], v[110:111] op_sel_hi:[0,1,1]
	v_pk_fma_f32 v[100:101], v[32:33], v[8:9], v[100:101] op_sel_hi:[0,1,1]
	v_pk_fma_f32 v[102:103], v[30:31], v[8:9], v[102:103] op_sel_hi:[0,1,1]
	v_pk_fma_f32 v[92:93], v[28:29], v[8:9], v[92:93] op_sel_hi:[0,1,1]
	v_pk_fma_f32 v[94:95], v[26:27], v[8:9], v[94:95] op_sel_hi:[0,1,1]
	v_pk_fma_f32 v[84:85], v[24:25], v[8:9], v[84:85] op_sel_hi:[0,1,1]
	v_pk_fma_f32 v[86:87], v[22:23], v[8:9], v[86:87] op_sel_hi:[0,1,1]
	v_pk_fma_f32 v[14:15], v[20:21], v[8:9], v[14:15] op_sel_hi:[0,1,1]
	v_pk_fma_f32 v[78:79], v[18:19], v[8:9], v[78:79] op_sel_hi:[0,1,1]
	v_pk_fma_f32 v[8:9], v[16:17], v[8:9], 0 op_sel_hi:[0,1,0]
	v_pk_fma_f32 v[8:9], v[18:19], v[12:13], v[8:9] op_sel_hi:[0,1,1]
	v_pk_fma_f32 v[8:9], v[20:21], v[10:11], v[8:9] op_sel_hi:[0,1,1]
	v_mov_b32_e32 v140, v142
	s_waitcnt lgkmcnt(0)
	v_mov_b32_e32 v141, v136
	v_mov_b32_e32 v136, v143
	ds_read2st64_b32 v[142:143], v23 offset0:144 offset1:148
	v_pk_fma_f32 v[78:79], v[20:21], v[12:13], v[78:79] op_sel_hi:[0,1,1]
	v_pk_fma_f32 v[8:9], v[22:23], v[82:83], v[8:9] op_sel_hi:[0,1,1]
	v_pk_fma_f32 v[14:15], v[22:23], v[12:13], v[14:15] op_sel_hi:[0,1,1]
	v_pk_fma_f32 v[78:79], v[22:23], v[10:11], v[78:79] op_sel_hi:[0,1,1]
	v_pk_fma_f32 v[8:9], v[24:25], v[80:81], v[8:9] op_sel_hi:[0,1,1]
	v_pk_fma_f32 v[86:87], v[24:25], v[12:13], v[86:87] op_sel_hi:[0,1,1]
	v_pk_fma_f32 v[14:15], v[24:25], v[10:11], v[14:15] op_sel_hi:[0,1,1]
	v_pk_fma_f32 v[78:79], v[24:25], v[82:83], v[78:79] op_sel_hi:[0,1,1]
	v_pk_fma_f32 v[8:9], v[26:27], v[90:91], v[8:9] op_sel_hi:[0,1,1]
	v_pk_fma_f32 v[84:85], v[26:27], v[12:13], v[84:85] op_sel_hi:[0,1,1]
	v_pk_fma_f32 v[86:87], v[26:27], v[10:11], v[86:87] op_sel_hi:[0,1,1]
	v_pk_fma_f32 v[14:15], v[26:27], v[82:83], v[14:15] op_sel_hi:[0,1,1]
	v_pk_fma_f32 v[78:79], v[26:27], v[80:81], v[78:79] op_sel_hi:[0,1,1]
	v_pk_fma_f32 v[8:9], v[28:29], v[88:89], v[8:9] op_sel_hi:[0,1,1]
	v_pk_fma_f32 v[94:95], v[28:29], v[12:13], v[94:95] op_sel_hi:[0,1,1]
	v_pk_fma_f32 v[84:85], v[28:29], v[10:11], v[84:85] op_sel_hi:[0,1,1]
	v_pk_fma_f32 v[86:87], v[28:29], v[82:83], v[86:87] op_sel_hi:[0,1,1]
	v_pk_fma_f32 v[14:15], v[28:29], v[80:81], v[14:15] op_sel_hi:[0,1,1]
	v_pk_fma_f32 v[78:79], v[28:29], v[90:91], v[78:79] op_sel_hi:[0,1,1]
	v_pk_fma_f32 v[8:9], v[30:31], v[98:99], v[8:9] op_sel_hi:[0,1,1]
	v_mov_b32_e32 v156, v158
	s_waitcnt lgkmcnt(0)
	v_mov_b32_e32 v157, v142
	v_mov_b32_e32 v142, v159
	ds_read2st64_b32 v[158:159], v23 offset0:152 offset1:156
	v_pk_fma_f32 v[92:93], v[30:31], v[12:13], v[92:93] op_sel_hi:[0,1,1]
	v_pk_fma_f32 v[94:95], v[30:31], v[10:11], v[94:95] op_sel_hi:[0,1,1]
	v_pk_fma_f32 v[84:85], v[30:31], v[82:83], v[84:85] op_sel_hi:[0,1,1]
	v_pk_fma_f32 v[86:87], v[30:31], v[80:81], v[86:87] op_sel_hi:[0,1,1]
	v_pk_fma_f32 v[14:15], v[30:31], v[90:91], v[14:15] op_sel_hi:[0,1,1]
	v_pk_fma_f32 v[78:79], v[30:31], v[88:89], v[78:79] op_sel_hi:[0,1,1]
	v_pk_fma_f32 v[8:9], v[32:33], v[96:97], v[8:9] op_sel_hi:[0,1,1]
	v_pk_fma_f32 v[102:103], v[32:33], v[12:13], v[102:103] op_sel_hi:[0,1,1]
	v_pk_fma_f32 v[92:93], v[32:33], v[10:11], v[92:93] op_sel_hi:[0,1,1]
	v_pk_fma_f32 v[94:95], v[32:33], v[82:83], v[94:95] op_sel_hi:[0,1,1]
	v_pk_fma_f32 v[84:85], v[32:33], v[80:81], v[84:85] op_sel_hi:[0,1,1]
	v_pk_fma_f32 v[86:87], v[32:33], v[90:91], v[86:87] op_sel_hi:[0,1,1]
	v_pk_fma_f32 v[14:15], v[32:33], v[88:89], v[14:15] op_sel_hi:[0,1,1]
	v_pk_fma_f32 v[78:79], v[32:33], v[98:99], v[78:79] op_sel_hi:[0,1,1]
	v_pk_fma_f32 v[8:9], v[34:35], v[106:107], v[8:9] op_sel_hi:[0,1,1]
	v_pk_fma_f32 v[100:101], v[34:35], v[12:13], v[100:101] op_sel_hi:[0,1,1]
	v_pk_fma_f32 v[102:103], v[34:35], v[10:11], v[102:103] op_sel_hi:[0,1,1]
	v_pk_fma_f32 v[92:93], v[34:35], v[82:83], v[92:93] op_sel_hi:[0,1,1]
	v_pk_fma_f32 v[94:95], v[34:35], v[80:81], v[94:95] op_sel_hi:[0,1,1]
	v_pk_fma_f32 v[84:85], v[34:35], v[90:91], v[84:85] op_sel_hi:[0,1,1]
	v_pk_fma_f32 v[86:87], v[34:35], v[88:89], v[86:87] op_sel_hi:[0,1,1]
	v_pk_fma_f32 v[14:15], v[34:35], v[98:99], v[14:15] op_sel_hi:[0,1,1]
	v_pk_fma_f32 v[78:79], v[34:35], v[96:97], v[78:79] op_sel_hi:[0,1,1]
	v_pk_fma_f32 v[8:9], v[36:37], v[104:105], v[8:9] op_sel_hi:[0,1,1]
	v_pk_fma_f32 v[110:111], v[36:37], v[12:13], v[110:111] op_sel_hi:[0,1,1]
	v_pk_fma_f32 v[100:101], v[36:37], v[10:11], v[100:101] op_sel_hi:[0,1,1]
	v_pk_fma_f32 v[102:103], v[36:37], v[82:83], v[102:103] op_sel_hi:[0,1,1]
	v_pk_fma_f32 v[92:93], v[36:37], v[80:81], v[92:93] op_sel_hi:[0,1,1]
	v_pk_fma_f32 v[94:95], v[36:37], v[90:91], v[94:95] op_sel_hi:[0,1,1]
	v_pk_fma_f32 v[84:85], v[36:37], v[88:89], v[84:85] op_sel_hi:[0,1,1]
	v_pk_fma_f32 v[86:87], v[36:37], v[98:99], v[86:87] op_sel_hi:[0,1,1]
	v_pk_fma_f32 v[14:15], v[36:37], v[96:97], v[14:15] op_sel_hi:[0,1,1]
	v_pk_fma_f32 v[78:79], v[36:37], v[106:107], v[78:79] op_sel_hi:[0,1,1]
	v_pk_fma_f32 v[8:9], v[38:39], v[114:115], v[8:9] op_sel_hi:[0,1,1]
	v_pk_fma_f32 v[108:109], v[38:39], v[12:13], v[108:109] op_sel_hi:[0,1,1]
	v_pk_fma_f32 v[110:111], v[38:39], v[10:11], v[110:111] op_sel_hi:[0,1,1]
	v_pk_fma_f32 v[100:101], v[38:39], v[82:83], v[100:101] op_sel_hi:[0,1,1]
	v_pk_fma_f32 v[102:103], v[38:39], v[80:81], v[102:103] op_sel_hi:[0,1,1]
	v_pk_fma_f32 v[92:93], v[38:39], v[90:91], v[92:93] op_sel_hi:[0,1,1]
	v_pk_fma_f32 v[94:95], v[38:39], v[88:89], v[94:95] op_sel_hi:[0,1,1]
	v_pk_fma_f32 v[84:85], v[38:39], v[98:99], v[84:85] op_sel_hi:[0,1,1]
	v_pk_fma_f32 v[86:87], v[38:39], v[96:97], v[86:87] op_sel_hi:[0,1,1]
	v_pk_fma_f32 v[14:15], v[38:39], v[106:107], v[14:15] op_sel_hi:[0,1,1]
	v_pk_fma_f32 v[78:79], v[38:39], v[104:105], v[78:79] op_sel_hi:[0,1,1]
	v_pk_fma_f32 v[8:9], v[40:41], v[112:113], v[8:9] op_sel_hi:[0,1,1]
	v_mov_b32_e32 v160, v162
	s_waitcnt lgkmcnt(0)
	v_mov_b32_e32 v161, v158
	v_mov_b32_e32 v158, v163
	ds_read2st64_b32 v[162:163], v23 offset0:160 offset1:164
	v_pk_fma_f32 v[118:119], v[40:41], v[12:13], v[118:119] op_sel_hi:[0,1,1]
	v_pk_fma_f32 v[108:109], v[40:41], v[10:11], v[108:109] op_sel_hi:[0,1,1]
	v_pk_fma_f32 v[110:111], v[40:41], v[82:83], v[110:111] op_sel_hi:[0,1,1]
	v_pk_fma_f32 v[100:101], v[40:41], v[80:81], v[100:101] op_sel_hi:[0,1,1]
	v_pk_fma_f32 v[102:103], v[40:41], v[90:91], v[102:103] op_sel_hi:[0,1,1]
	v_pk_fma_f32 v[92:93], v[40:41], v[88:89], v[92:93] op_sel_hi:[0,1,1]
	v_pk_fma_f32 v[94:95], v[40:41], v[98:99], v[94:95] op_sel_hi:[0,1,1]
	v_pk_fma_f32 v[84:85], v[40:41], v[96:97], v[84:85] op_sel_hi:[0,1,1]
	v_pk_fma_f32 v[86:87], v[40:41], v[106:107], v[86:87] op_sel_hi:[0,1,1]
	v_pk_fma_f32 v[14:15], v[40:41], v[104:105], v[14:15] op_sel_hi:[0,1,1]
	v_pk_fma_f32 v[78:79], v[40:41], v[114:115], v[78:79] op_sel_hi:[0,1,1]
	v_pk_fma_f32 v[8:9], v[42:43], v[122:123], v[8:9] op_sel_hi:[0,1,1]
	v_pk_fma_f32 v[116:117], v[42:43], v[12:13], v[116:117] op_sel_hi:[0,1,1]
	v_pk_fma_f32 v[118:119], v[42:43], v[10:11], v[118:119] op_sel_hi:[0,1,1]
	v_pk_fma_f32 v[108:109], v[42:43], v[82:83], v[108:109] op_sel_hi:[0,1,1]
	v_pk_fma_f32 v[110:111], v[42:43], v[80:81], v[110:111] op_sel_hi:[0,1,1]
	v_pk_fma_f32 v[100:101], v[42:43], v[90:91], v[100:101] op_sel_hi:[0,1,1]
	v_pk_fma_f32 v[102:103], v[42:43], v[88:89], v[102:103] op_sel_hi:[0,1,1]
	v_pk_fma_f32 v[92:93], v[42:43], v[98:99], v[92:93] op_sel_hi:[0,1,1]
	v_pk_fma_f32 v[94:95], v[42:43], v[96:97], v[94:95] op_sel_hi:[0,1,1]
	v_pk_fma_f32 v[84:85], v[42:43], v[106:107], v[84:85] op_sel_hi:[0,1,1]
	v_pk_fma_f32 v[86:87], v[42:43], v[104:105], v[86:87] op_sel_hi:[0,1,1]
	v_pk_fma_f32 v[14:15], v[42:43], v[114:115], v[14:15] op_sel_hi:[0,1,1]
	v_pk_fma_f32 v[78:79], v[42:43], v[112:113], v[78:79] op_sel_hi:[0,1,1]
	v_pk_fma_f32 v[8:9], v[44:45], v[120:121], v[8:9] op_sel_hi:[0,1,1]
	v_pk_fma_f32 v[124:125], v[46:47], v[12:13], v[124:125] op_sel_hi:[0,1,1]
	v_pk_fma_f32 v[126:127], v[44:45], v[12:13], v[126:127] op_sel_hi:[0,1,1]
	v_pk_fma_f32 v[116:117], v[44:45], v[10:11], v[116:117] op_sel_hi:[0,1,1]
	v_pk_fma_f32 v[118:119], v[44:45], v[82:83], v[118:119] op_sel_hi:[0,1,1]
	v_pk_fma_f32 v[108:109], v[44:45], v[80:81], v[108:109] op_sel_hi:[0,1,1]
	v_pk_fma_f32 v[110:111], v[44:45], v[90:91], v[110:111] op_sel_hi:[0,1,1]
	v_pk_fma_f32 v[100:101], v[44:45], v[88:89], v[100:101] op_sel_hi:[0,1,1]
	v_pk_fma_f32 v[102:103], v[44:45], v[98:99], v[102:103] op_sel_hi:[0,1,1]
	v_pk_fma_f32 v[92:93], v[44:45], v[96:97], v[92:93] op_sel_hi:[0,1,1]
	v_pk_fma_f32 v[94:95], v[44:45], v[106:107], v[94:95] op_sel_hi:[0,1,1]
	v_pk_fma_f32 v[84:85], v[44:45], v[104:105], v[84:85] op_sel_hi:[0,1,1]
	v_pk_fma_f32 v[86:87], v[44:45], v[114:115], v[86:87] op_sel_hi:[0,1,1]
	v_pk_fma_f32 v[14:15], v[44:45], v[112:113], v[14:15] op_sel_hi:[0,1,1]
	v_pk_fma_f32 v[78:79], v[44:45], v[122:123], v[78:79] op_sel_hi:[0,1,1]
	v_pk_fma_f32 v[8:9], v[46:47], v[130:131], v[8:9] op_sel_hi:[0,1,1]
	v_pk_fma_f32 v[138:139], v[48:49], v[12:13], v[138:139] op_sel_hi:[0,1,1]
	v_pk_fma_f32 v[124:125], v[48:49], v[10:11], v[124:125] op_sel_hi:[0,1,1]
	v_pk_fma_f32 v[126:127], v[46:47], v[10:11], v[126:127] op_sel_hi:[0,1,1]
	v_pk_fma_f32 v[116:117], v[46:47], v[82:83], v[116:117] op_sel_hi:[0,1,1]
	v_pk_fma_f32 v[118:119], v[46:47], v[80:81], v[118:119] op_sel_hi:[0,1,1]
	v_pk_fma_f32 v[108:109], v[46:47], v[90:91], v[108:109] op_sel_hi:[0,1,1]
	v_pk_fma_f32 v[110:111], v[46:47], v[88:89], v[110:111] op_sel_hi:[0,1,1]
	v_pk_fma_f32 v[100:101], v[46:47], v[98:99], v[100:101] op_sel_hi:[0,1,1]
	v_pk_fma_f32 v[102:103], v[46:47], v[96:97], v[102:103] op_sel_hi:[0,1,1]
	v_pk_fma_f32 v[92:93], v[46:47], v[106:107], v[92:93] op_sel_hi:[0,1,1]
	v_pk_fma_f32 v[94:95], v[46:47], v[104:105], v[94:95] op_sel_hi:[0,1,1]
	v_pk_fma_f32 v[84:85], v[46:47], v[114:115], v[84:85] op_sel_hi:[0,1,1]
	v_pk_fma_f32 v[86:87], v[46:47], v[112:113], v[86:87] op_sel_hi:[0,1,1]
	v_pk_fma_f32 v[14:15], v[46:47], v[122:123], v[14:15] op_sel_hi:[0,1,1]
	v_pk_fma_f32 v[78:79], v[46:47], v[120:121], v[78:79] op_sel_hi:[0,1,1]
	v_pk_fma_f32 v[8:9], v[48:49], v[128:129], v[8:9] op_sel_hi:[0,1,1]
	v_pk_fma_f32 v[138:139], v[50:51], v[10:11], v[138:139] op_sel_hi:[0,1,1]
	v_pk_fma_f32 v[124:125], v[50:51], v[82:83], v[124:125] op_sel_hi:[0,1,1]
	v_pk_fma_f32 v[126:127], v[48:49], v[82:83], v[126:127] op_sel_hi:[0,1,1]
	v_pk_fma_f32 v[116:117], v[48:49], v[80:81], v[116:117] op_sel_hi:[0,1,1]
	v_pk_fma_f32 v[118:119], v[48:49], v[90:91], v[118:119] op_sel_hi:[0,1,1]
	v_pk_fma_f32 v[108:109], v[48:49], v[88:89], v[108:109] op_sel_hi:[0,1,1]
	v_pk_fma_f32 v[110:111], v[48:49], v[98:99], v[110:111] op_sel_hi:[0,1,1]
	v_pk_fma_f32 v[100:101], v[48:49], v[96:97], v[100:101] op_sel_hi:[0,1,1]
	v_pk_fma_f32 v[102:103], v[48:49], v[106:107], v[102:103] op_sel_hi:[0,1,1]
	v_pk_fma_f32 v[92:93], v[48:49], v[104:105], v[92:93] op_sel_hi:[0,1,1]
	v_pk_fma_f32 v[94:95], v[48:49], v[114:115], v[94:95] op_sel_hi:[0,1,1]
	v_pk_fma_f32 v[84:85], v[48:49], v[112:113], v[84:85] op_sel_hi:[0,1,1]
	v_pk_fma_f32 v[86:87], v[48:49], v[122:123], v[86:87] op_sel_hi:[0,1,1]
	v_pk_fma_f32 v[14:15], v[48:49], v[120:121], v[14:15] op_sel_hi:[0,1,1]
	v_pk_fma_f32 v[78:79], v[48:49], v[130:131], v[78:79] op_sel_hi:[0,1,1]
	v_pk_fma_f32 v[8:9], v[50:51], v[134:135], v[8:9] op_sel_hi:[0,1,1]
	v_mov_b32_e32 v164, v166
	s_waitcnt lgkmcnt(0)
	v_mov_b32_e32 v165, v162
	v_mov_b32_e32 v162, v167
	ds_read2st64_b32 v[166:167], v23 offset0:168 offset1:172
	v_pk_fma_f32 v[138:139], v[52:53], v[82:83], v[138:139] op_sel_hi:[0,1,1]
	v_pk_fma_f32 v[124:125], v[52:53], v[80:81], v[124:125] op_sel_hi:[0,1,1]
	v_pk_fma_f32 v[126:127], v[50:51], v[80:81], v[126:127] op_sel_hi:[0,1,1]
	v_pk_fma_f32 v[116:117], v[50:51], v[90:91], v[116:117] op_sel_hi:[0,1,1]
	v_pk_fma_f32 v[118:119], v[50:51], v[88:89], v[118:119] op_sel_hi:[0,1,1]
	v_pk_fma_f32 v[108:109], v[50:51], v[98:99], v[108:109] op_sel_hi:[0,1,1]
	v_pk_fma_f32 v[110:111], v[50:51], v[96:97], v[110:111] op_sel_hi:[0,1,1]
	v_pk_fma_f32 v[100:101], v[50:51], v[106:107], v[100:101] op_sel_hi:[0,1,1]
	v_pk_fma_f32 v[102:103], v[50:51], v[104:105], v[102:103] op_sel_hi:[0,1,1]
	v_pk_fma_f32 v[92:93], v[50:51], v[114:115], v[92:93] op_sel_hi:[0,1,1]
	v_pk_fma_f32 v[94:95], v[50:51], v[112:113], v[94:95] op_sel_hi:[0,1,1]
	v_pk_fma_f32 v[84:85], v[50:51], v[122:123], v[84:85] op_sel_hi:[0,1,1]
	v_pk_fma_f32 v[86:87], v[50:51], v[120:121], v[86:87] op_sel_hi:[0,1,1]
	v_pk_fma_f32 v[14:15], v[50:51], v[130:131], v[14:15] op_sel_hi:[0,1,1]
	v_pk_fma_f32 v[78:79], v[50:51], v[128:129], v[78:79] op_sel_hi:[0,1,1]
	v_pk_fma_f32 v[8:9], v[52:53], v[132:133], v[8:9] op_sel_hi:[0,1,1]
	v_pk_fma_f32 v[138:139], v[54:55], v[80:81], v[138:139] op_sel_hi:[0,1,1]
	v_pk_fma_f32 v[124:125], v[54:55], v[90:91], v[124:125] op_sel_hi:[0,1,1]
	v_pk_fma_f32 v[126:127], v[52:53], v[90:91], v[126:127] op_sel_hi:[0,1,1]
	v_pk_fma_f32 v[116:117], v[52:53], v[88:89], v[116:117] op_sel_hi:[0,1,1]
	v_pk_fma_f32 v[118:119], v[52:53], v[98:99], v[118:119] op_sel_hi:[0,1,1]
	v_pk_fma_f32 v[108:109], v[52:53], v[96:97], v[108:109] op_sel_hi:[0,1,1]
	v_pk_fma_f32 v[110:111], v[52:53], v[106:107], v[110:111] op_sel_hi:[0,1,1]
	v_pk_fma_f32 v[100:101], v[52:53], v[104:105], v[100:101] op_sel_hi:[0,1,1]
	v_pk_fma_f32 v[102:103], v[52:53], v[114:115], v[102:103] op_sel_hi:[0,1,1]
	v_pk_fma_f32 v[92:93], v[52:53], v[112:113], v[92:93] op_sel_hi:[0,1,1]
	v_pk_fma_f32 v[94:95], v[52:53], v[122:123], v[94:95] op_sel_hi:[0,1,1]
	v_pk_fma_f32 v[84:85], v[52:53], v[120:121], v[84:85] op_sel_hi:[0,1,1]
	v_pk_fma_f32 v[86:87], v[52:53], v[130:131], v[86:87] op_sel_hi:[0,1,1]
	v_pk_fma_f32 v[14:15], v[52:53], v[128:129], v[14:15] op_sel_hi:[0,1,1]
	v_pk_fma_f32 v[78:79], v[52:53], v[134:135], v[78:79] op_sel_hi:[0,1,1]
	v_pk_fma_f32 v[8:9], v[54:55], v[140:141], v[8:9] op_sel_hi:[0,1,1]
	v_pk_fma_f32 v[138:139], v[56:57], v[90:91], v[138:139] op_sel_hi:[0,1,1]
	v_pk_fma_f32 v[124:125], v[56:57], v[88:89], v[124:125] op_sel_hi:[0,1,1]
	v_pk_fma_f32 v[126:127], v[54:55], v[88:89], v[126:127] op_sel_hi:[0,1,1]
	v_pk_fma_f32 v[116:117], v[54:55], v[98:99], v[116:117] op_sel_hi:[0,1,1]
	v_pk_fma_f32 v[118:119], v[54:55], v[96:97], v[118:119] op_sel_hi:[0,1,1]
	v_pk_fma_f32 v[108:109], v[54:55], v[106:107], v[108:109] op_sel_hi:[0,1,1]
	v_pk_fma_f32 v[110:111], v[54:55], v[104:105], v[110:111] op_sel_hi:[0,1,1]
	v_pk_fma_f32 v[100:101], v[54:55], v[114:115], v[100:101] op_sel_hi:[0,1,1]
	v_pk_fma_f32 v[102:103], v[54:55], v[112:113], v[102:103] op_sel_hi:[0,1,1]
	v_pk_fma_f32 v[92:93], v[54:55], v[122:123], v[92:93] op_sel_hi:[0,1,1]
	v_pk_fma_f32 v[94:95], v[54:55], v[120:121], v[94:95] op_sel_hi:[0,1,1]
	v_pk_fma_f32 v[84:85], v[54:55], v[130:131], v[84:85] op_sel_hi:[0,1,1]
	v_pk_fma_f32 v[86:87], v[54:55], v[128:129], v[86:87] op_sel_hi:[0,1,1]
	v_pk_fma_f32 v[14:15], v[54:55], v[134:135], v[14:15] op_sel_hi:[0,1,1]
	v_pk_fma_f32 v[78:79], v[54:55], v[132:133], v[78:79] op_sel_hi:[0,1,1]
	v_pk_fma_f32 v[8:9], v[56:57], v[136:137], v[8:9] op_sel_hi:[0,1,1]
	v_pk_fma_f32 v[138:139], v[58:59], v[88:89], v[138:139] op_sel_hi:[0,1,1]
	v_pk_fma_f32 v[124:125], v[58:59], v[98:99], v[124:125] op_sel_hi:[0,1,1]
	v_pk_fma_f32 v[126:127], v[56:57], v[98:99], v[126:127] op_sel_hi:[0,1,1]
	v_pk_fma_f32 v[116:117], v[56:57], v[96:97], v[116:117] op_sel_hi:[0,1,1]
	v_pk_fma_f32 v[118:119], v[56:57], v[106:107], v[118:119] op_sel_hi:[0,1,1]
	v_pk_fma_f32 v[108:109], v[56:57], v[104:105], v[108:109] op_sel_hi:[0,1,1]
	v_pk_fma_f32 v[110:111], v[56:57], v[114:115], v[110:111] op_sel_hi:[0,1,1]
	v_pk_fma_f32 v[100:101], v[56:57], v[112:113], v[100:101] op_sel_hi:[0,1,1]
	v_pk_fma_f32 v[102:103], v[56:57], v[122:123], v[102:103] op_sel_hi:[0,1,1]
	v_pk_fma_f32 v[92:93], v[56:57], v[120:121], v[92:93] op_sel_hi:[0,1,1]
	v_pk_fma_f32 v[94:95], v[56:57], v[130:131], v[94:95] op_sel_hi:[0,1,1]
	v_pk_fma_f32 v[84:85], v[56:57], v[128:129], v[84:85] op_sel_hi:[0,1,1]
	v_pk_fma_f32 v[86:87], v[56:57], v[134:135], v[86:87] op_sel_hi:[0,1,1]
	v_pk_fma_f32 v[14:15], v[56:57], v[132:133], v[14:15] op_sel_hi:[0,1,1]
	v_pk_fma_f32 v[78:79], v[56:57], v[140:141], v[78:79] op_sel_hi:[0,1,1]
	v_pk_fma_f32 v[8:9], v[58:59], v[156:157], v[8:9] op_sel_hi:[0,1,1]
	v_pk_fma_f32 v[138:139], v[60:61], v[98:99], v[138:139] op_sel_hi:[0,1,1]
	v_pk_fma_f32 v[124:125], v[60:61], v[96:97], v[124:125] op_sel_hi:[0,1,1]
	v_pk_fma_f32 v[126:127], v[58:59], v[96:97], v[126:127] op_sel_hi:[0,1,1]
	v_pk_fma_f32 v[116:117], v[58:59], v[106:107], v[116:117] op_sel_hi:[0,1,1]
	v_pk_fma_f32 v[118:119], v[58:59], v[104:105], v[118:119] op_sel_hi:[0,1,1]
	v_pk_fma_f32 v[108:109], v[58:59], v[114:115], v[108:109] op_sel_hi:[0,1,1]
	v_pk_fma_f32 v[110:111], v[58:59], v[112:113], v[110:111] op_sel_hi:[0,1,1]
	v_pk_fma_f32 v[100:101], v[58:59], v[122:123], v[100:101] op_sel_hi:[0,1,1]
	v_pk_fma_f32 v[102:103], v[58:59], v[120:121], v[102:103] op_sel_hi:[0,1,1]
	v_pk_fma_f32 v[92:93], v[58:59], v[130:131], v[92:93] op_sel_hi:[0,1,1]
	v_pk_fma_f32 v[94:95], v[58:59], v[128:129], v[94:95] op_sel_hi:[0,1,1]
	v_pk_fma_f32 v[84:85], v[58:59], v[134:135], v[84:85] op_sel_hi:[0,1,1]
	v_pk_fma_f32 v[86:87], v[58:59], v[132:133], v[86:87] op_sel_hi:[0,1,1]
	v_pk_fma_f32 v[14:15], v[58:59], v[140:141], v[14:15] op_sel_hi:[0,1,1]
	v_pk_fma_f32 v[78:79], v[58:59], v[136:137], v[78:79] op_sel_hi:[0,1,1]
	v_pk_fma_f32 v[8:9], v[60:61], v[142:143], v[8:9] op_sel_hi:[0,1,1]
	v_mov_b32_e32 v168, v170
	s_waitcnt lgkmcnt(0)
	v_mov_b32_e32 v169, v166
	v_mov_b32_e32 v166, v171
	ds_read2st64_b32 v[170:171], v23 offset0:176 offset1:180
	v_pk_fma_f32 v[138:139], v[62:63], v[96:97], v[138:139] op_sel_hi:[0,1,1]
	v_pk_fma_f32 v[124:125], v[62:63], v[106:107], v[124:125] op_sel_hi:[0,1,1]
	v_pk_fma_f32 v[126:127], v[60:61], v[106:107], v[126:127] op_sel_hi:[0,1,1]
	v_pk_fma_f32 v[116:117], v[60:61], v[104:105], v[116:117] op_sel_hi:[0,1,1]
	v_pk_fma_f32 v[118:119], v[60:61], v[114:115], v[118:119] op_sel_hi:[0,1,1]
	v_pk_fma_f32 v[108:109], v[60:61], v[112:113], v[108:109] op_sel_hi:[0,1,1]
	v_pk_fma_f32 v[110:111], v[60:61], v[122:123], v[110:111] op_sel_hi:[0,1,1]
	v_pk_fma_f32 v[100:101], v[60:61], v[120:121], v[100:101] op_sel_hi:[0,1,1]
	v_pk_fma_f32 v[102:103], v[60:61], v[130:131], v[102:103] op_sel_hi:[0,1,1]
	v_pk_fma_f32 v[92:93], v[60:61], v[128:129], v[92:93] op_sel_hi:[0,1,1]
	v_pk_fma_f32 v[94:95], v[60:61], v[134:135], v[94:95] op_sel_hi:[0,1,1]
	v_pk_fma_f32 v[84:85], v[60:61], v[132:133], v[84:85] op_sel_hi:[0,1,1]
	v_pk_fma_f32 v[86:87], v[60:61], v[140:141], v[86:87] op_sel_hi:[0,1,1]
	v_pk_fma_f32 v[14:15], v[60:61], v[136:137], v[14:15] op_sel_hi:[0,1,1]
	v_pk_fma_f32 v[78:79], v[60:61], v[156:157], v[78:79] op_sel_hi:[0,1,1]
	v_pk_fma_f32 v[8:9], v[62:63], v[160:161], v[8:9] op_sel_hi:[0,1,1]
	v_pk_fma_f32 v[138:139], v[64:65], v[106:107], v[138:139] op_sel_hi:[0,1,1]
	v_pk_fma_f32 v[124:125], v[64:65], v[104:105], v[124:125] op_sel_hi:[0,1,1]
	v_pk_fma_f32 v[126:127], v[62:63], v[104:105], v[126:127] op_sel_hi:[0,1,1]
	v_pk_fma_f32 v[116:117], v[62:63], v[114:115], v[116:117] op_sel_hi:[0,1,1]
	v_pk_fma_f32 v[118:119], v[62:63], v[112:113], v[118:119] op_sel_hi:[0,1,1]
	v_pk_fma_f32 v[108:109], v[62:63], v[122:123], v[108:109] op_sel_hi:[0,1,1]
	v_pk_fma_f32 v[110:111], v[62:63], v[120:121], v[110:111] op_sel_hi:[0,1,1]
	v_pk_fma_f32 v[100:101], v[62:63], v[130:131], v[100:101] op_sel_hi:[0,1,1]
	v_pk_fma_f32 v[102:103], v[62:63], v[128:129], v[102:103] op_sel_hi:[0,1,1]
	v_pk_fma_f32 v[92:93], v[62:63], v[134:135], v[92:93] op_sel_hi:[0,1,1]
	v_pk_fma_f32 v[94:95], v[62:63], v[132:133], v[94:95] op_sel_hi:[0,1,1]
	v_pk_fma_f32 v[84:85], v[62:63], v[140:141], v[84:85] op_sel_hi:[0,1,1]
	v_pk_fma_f32 v[86:87], v[62:63], v[136:137], v[86:87] op_sel_hi:[0,1,1]
	v_pk_fma_f32 v[14:15], v[62:63], v[156:157], v[14:15] op_sel_hi:[0,1,1]
	v_pk_fma_f32 v[78:79], v[62:63], v[142:143], v[78:79] op_sel_hi:[0,1,1]
	v_pk_fma_f32 v[8:9], v[64:65], v[158:159], v[8:9] op_sel_hi:[0,1,1]
	v_pk_fma_f32 v[138:139], v[66:67], v[104:105], v[138:139] op_sel_hi:[0,1,1]
	v_pk_fma_f32 v[124:125], v[66:67], v[114:115], v[124:125] op_sel_hi:[0,1,1]
	v_pk_fma_f32 v[126:127], v[64:65], v[114:115], v[126:127] op_sel_hi:[0,1,1]
	v_pk_fma_f32 v[116:117], v[64:65], v[112:113], v[116:117] op_sel_hi:[0,1,1]
	v_pk_fma_f32 v[118:119], v[64:65], v[122:123], v[118:119] op_sel_hi:[0,1,1]
	v_pk_fma_f32 v[108:109], v[64:65], v[120:121], v[108:109] op_sel_hi:[0,1,1]
	v_pk_fma_f32 v[110:111], v[64:65], v[130:131], v[110:111] op_sel_hi:[0,1,1]
	v_pk_fma_f32 v[100:101], v[64:65], v[128:129], v[100:101] op_sel_hi:[0,1,1]
	v_pk_fma_f32 v[102:103], v[64:65], v[134:135], v[102:103] op_sel_hi:[0,1,1]
	v_pk_fma_f32 v[92:93], v[64:65], v[132:133], v[92:93] op_sel_hi:[0,1,1]
	v_pk_fma_f32 v[94:95], v[64:65], v[140:141], v[94:95] op_sel_hi:[0,1,1]
	v_pk_fma_f32 v[84:85], v[64:65], v[136:137], v[84:85] op_sel_hi:[0,1,1]
	v_pk_fma_f32 v[86:87], v[64:65], v[156:157], v[86:87] op_sel_hi:[0,1,1]
	v_pk_fma_f32 v[14:15], v[64:65], v[142:143], v[14:15] op_sel_hi:[0,1,1]
	v_pk_fma_f32 v[78:79], v[64:65], v[160:161], v[78:79] op_sel_hi:[0,1,1]
	v_pk_fma_f32 v[8:9], v[66:67], v[164:165], v[8:9] op_sel_hi:[0,1,1]
	v_pk_fma_f32 v[138:139], v[68:69], v[114:115], v[138:139] op_sel_hi:[0,1,1]
	v_pk_fma_f32 v[124:125], v[68:69], v[112:113], v[124:125] op_sel_hi:[0,1,1]
	v_pk_fma_f32 v[126:127], v[66:67], v[112:113], v[126:127] op_sel_hi:[0,1,1]
	v_pk_fma_f32 v[116:117], v[66:67], v[122:123], v[116:117] op_sel_hi:[0,1,1]
	v_pk_fma_f32 v[118:119], v[66:67], v[120:121], v[118:119] op_sel_hi:[0,1,1]
	v_pk_fma_f32 v[108:109], v[66:67], v[130:131], v[108:109] op_sel_hi:[0,1,1]
	v_pk_fma_f32 v[110:111], v[66:67], v[128:129], v[110:111] op_sel_hi:[0,1,1]
	v_pk_fma_f32 v[100:101], v[66:67], v[134:135], v[100:101] op_sel_hi:[0,1,1]
	v_pk_fma_f32 v[102:103], v[66:67], v[132:133], v[102:103] op_sel_hi:[0,1,1]
	v_pk_fma_f32 v[92:93], v[66:67], v[140:141], v[92:93] op_sel_hi:[0,1,1]
	v_pk_fma_f32 v[94:95], v[66:67], v[136:137], v[94:95] op_sel_hi:[0,1,1]
	v_pk_fma_f32 v[84:85], v[66:67], v[156:157], v[84:85] op_sel_hi:[0,1,1]
	v_pk_fma_f32 v[86:87], v[66:67], v[142:143], v[86:87] op_sel_hi:[0,1,1]
	v_pk_fma_f32 v[14:15], v[66:67], v[160:161], v[14:15] op_sel_hi:[0,1,1]
	v_pk_fma_f32 v[78:79], v[66:67], v[158:159], v[78:79] op_sel_hi:[0,1,1]
	v_pk_fma_f32 v[8:9], v[68:69], v[162:163], v[8:9] op_sel_hi:[0,1,1]
	v_pk_fma_f32 v[138:139], v[70:71], v[112:113], v[138:139] op_sel_hi:[0,1,1]
	v_pk_fma_f32 v[124:125], v[70:71], v[122:123], v[124:125] op_sel_hi:[0,1,1]
	v_pk_fma_f32 v[126:127], v[68:69], v[122:123], v[126:127] op_sel_hi:[0,1,1]
	v_pk_fma_f32 v[116:117], v[68:69], v[120:121], v[116:117] op_sel_hi:[0,1,1]
	v_pk_fma_f32 v[118:119], v[68:69], v[130:131], v[118:119] op_sel_hi:[0,1,1]
	v_pk_fma_f32 v[108:109], v[68:69], v[128:129], v[108:109] op_sel_hi:[0,1,1]
	v_pk_fma_f32 v[110:111], v[68:69], v[134:135], v[110:111] op_sel_hi:[0,1,1]
	v_pk_fma_f32 v[100:101], v[68:69], v[132:133], v[100:101] op_sel_hi:[0,1,1]
	v_pk_fma_f32 v[102:103], v[68:69], v[140:141], v[102:103] op_sel_hi:[0,1,1]
	v_pk_fma_f32 v[92:93], v[68:69], v[136:137], v[92:93] op_sel_hi:[0,1,1]
	v_pk_fma_f32 v[94:95], v[68:69], v[156:157], v[94:95] op_sel_hi:[0,1,1]
	v_pk_fma_f32 v[84:85], v[68:69], v[142:143], v[84:85] op_sel_hi:[0,1,1]
	v_pk_fma_f32 v[86:87], v[68:69], v[160:161], v[86:87] op_sel_hi:[0,1,1]
	v_pk_fma_f32 v[14:15], v[68:69], v[158:159], v[14:15] op_sel_hi:[0,1,1]
	v_pk_fma_f32 v[78:79], v[68:69], v[164:165], v[78:79] op_sel_hi:[0,1,1]
	v_pk_fma_f32 v[8:9], v[70:71], v[168:169], v[8:9] op_sel_hi:[0,1,1]
	v_mov_b32_e32 v172, v174
	s_waitcnt lgkmcnt(0)
	v_mov_b32_e32 v173, v170
	v_pk_fma_f32 v[138:139], v[72:73], v[122:123], v[138:139] op_sel_hi:[0,1,1]
	v_pk_fma_f32 v[124:125], v[72:73], v[120:121], v[124:125] op_sel_hi:[0,1,1]
	v_pk_fma_f32 v[126:127], v[70:71], v[120:121], v[126:127] op_sel_hi:[0,1,1]
	v_pk_fma_f32 v[116:117], v[70:71], v[130:131], v[116:117] op_sel_hi:[0,1,1]
	v_pk_fma_f32 v[118:119], v[70:71], v[128:129], v[118:119] op_sel_hi:[0,1,1]
	v_pk_fma_f32 v[108:109], v[70:71], v[134:135], v[108:109] op_sel_hi:[0,1,1]
	v_pk_fma_f32 v[110:111], v[70:71], v[132:133], v[110:111] op_sel_hi:[0,1,1]
	v_pk_fma_f32 v[100:101], v[70:71], v[140:141], v[100:101] op_sel_hi:[0,1,1]
	v_pk_fma_f32 v[102:103], v[70:71], v[136:137], v[102:103] op_sel_hi:[0,1,1]
	v_pk_fma_f32 v[92:93], v[70:71], v[156:157], v[92:93] op_sel_hi:[0,1,1]
	v_pk_fma_f32 v[94:95], v[70:71], v[142:143], v[94:95] op_sel_hi:[0,1,1]
	v_pk_fma_f32 v[84:85], v[70:71], v[160:161], v[84:85] op_sel_hi:[0,1,1]
	v_pk_fma_f32 v[86:87], v[70:71], v[158:159], v[86:87] op_sel_hi:[0,1,1]
	v_pk_fma_f32 v[14:15], v[70:71], v[164:165], v[14:15] op_sel_hi:[0,1,1]
	v_pk_fma_f32 v[78:79], v[70:71], v[162:163], v[78:79] op_sel_hi:[0,1,1]
	v_pk_fma_f32 v[8:9], v[72:73], v[166:167], v[8:9] op_sel_hi:[0,1,1]
	v_mov_b32_e32 v170, v175
	v_pk_fma_f32 v[138:139], v[74:75], v[120:121], v[138:139] op_sel_hi:[0,1,1]
	v_pk_fma_f32 v[124:125], v[74:75], v[130:131], v[124:125] op_sel_hi:[0,1,1]
	v_pk_fma_f32 v[126:127], v[72:73], v[130:131], v[126:127] op_sel_hi:[0,1,1]
	v_pk_fma_f32 v[116:117], v[72:73], v[128:129], v[116:117] op_sel_hi:[0,1,1]
	v_pk_fma_f32 v[118:119], v[72:73], v[134:135], v[118:119] op_sel_hi:[0,1,1]
	v_pk_fma_f32 v[108:109], v[72:73], v[132:133], v[108:109] op_sel_hi:[0,1,1]
	v_pk_fma_f32 v[110:111], v[72:73], v[140:141], v[110:111] op_sel_hi:[0,1,1]
	v_pk_fma_f32 v[100:101], v[72:73], v[136:137], v[100:101] op_sel_hi:[0,1,1]
	v_pk_fma_f32 v[102:103], v[72:73], v[156:157], v[102:103] op_sel_hi:[0,1,1]
	v_pk_fma_f32 v[92:93], v[72:73], v[142:143], v[92:93] op_sel_hi:[0,1,1]
	v_pk_fma_f32 v[94:95], v[72:73], v[160:161], v[94:95] op_sel_hi:[0,1,1]
	v_pk_fma_f32 v[84:85], v[72:73], v[158:159], v[84:85] op_sel_hi:[0,1,1]
	v_pk_fma_f32 v[86:87], v[72:73], v[164:165], v[86:87] op_sel_hi:[0,1,1]
	v_pk_fma_f32 v[14:15], v[72:73], v[162:163], v[14:15] op_sel_hi:[0,1,1]
	v_pk_fma_f32 v[78:79], v[72:73], v[168:169], v[78:79] op_sel_hi:[0,1,1]
	v_pk_fma_f32 v[8:9], v[74:75], v[172:173], v[8:9] op_sel_hi:[0,1,1]
	v_pk_fma_f32 v[138:139], v[76:77], v[130:131], v[138:139] op_sel_hi:[0,1,1]
	v_pk_fma_f32 v[124:125], v[76:77], v[128:129], v[124:125] op_sel_hi:[0,1,1]
	v_pk_fma_f32 v[126:127], v[74:75], v[128:129], v[126:127] op_sel_hi:[0,1,1]
	v_pk_fma_f32 v[116:117], v[74:75], v[134:135], v[116:117] op_sel_hi:[0,1,1]
	v_pk_fma_f32 v[118:119], v[74:75], v[132:133], v[118:119] op_sel_hi:[0,1,1]
	v_pk_fma_f32 v[108:109], v[74:75], v[140:141], v[108:109] op_sel_hi:[0,1,1]
	v_pk_fma_f32 v[110:111], v[74:75], v[136:137], v[110:111] op_sel_hi:[0,1,1]
	v_pk_fma_f32 v[100:101], v[74:75], v[156:157], v[100:101] op_sel_hi:[0,1,1]
	v_pk_fma_f32 v[102:103], v[74:75], v[142:143], v[102:103] op_sel_hi:[0,1,1]
	v_pk_fma_f32 v[92:93], v[74:75], v[160:161], v[92:93] op_sel_hi:[0,1,1]
	v_pk_fma_f32 v[94:95], v[74:75], v[158:159], v[94:95] op_sel_hi:[0,1,1]
	v_pk_fma_f32 v[84:85], v[74:75], v[164:165], v[84:85] op_sel_hi:[0,1,1]
	v_pk_fma_f32 v[86:87], v[74:75], v[162:163], v[86:87] op_sel_hi:[0,1,1]
	v_pk_fma_f32 v[14:15], v[74:75], v[168:169], v[14:15] op_sel_hi:[0,1,1]
	v_pk_fma_f32 v[78:79], v[74:75], v[166:167], v[78:79] op_sel_hi:[0,1,1]
	v_pk_fma_f32 v[8:9], v[76:77], v[170:171], v[8:9] op_sel_hi:[0,1,1]
	v_pk_fma_f32 v[126:127], v[76:77], v[134:135], v[126:127] op_sel_hi:[0,1,1]
	v_pk_fma_f32 v[116:117], v[76:77], v[132:133], v[116:117] op_sel_hi:[0,1,1]
	v_pk_fma_f32 v[118:119], v[76:77], v[140:141], v[118:119] op_sel_hi:[0,1,1]
	v_pk_fma_f32 v[108:109], v[76:77], v[136:137], v[108:109] op_sel_hi:[0,1,1]
	v_pk_fma_f32 v[110:111], v[76:77], v[156:157], v[110:111] op_sel_hi:[0,1,1]
	v_pk_fma_f32 v[100:101], v[76:77], v[142:143], v[100:101] op_sel_hi:[0,1,1]
	v_pk_fma_f32 v[102:103], v[76:77], v[160:161], v[102:103] op_sel_hi:[0,1,1]
	v_pk_fma_f32 v[92:93], v[76:77], v[158:159], v[92:93] op_sel_hi:[0,1,1]
	v_pk_fma_f32 v[94:95], v[76:77], v[164:165], v[94:95] op_sel_hi:[0,1,1]
	v_pk_fma_f32 v[84:85], v[76:77], v[162:163], v[84:85] op_sel_hi:[0,1,1]
	v_pk_fma_f32 v[86:87], v[76:77], v[168:169], v[86:87] op_sel_hi:[0,1,1]
	v_pk_fma_f32 v[14:15], v[76:77], v[166:167], v[14:15] op_sel_hi:[0,1,1]
	v_pk_fma_f32 v[78:79], v[76:77], v[172:173], v[78:79] op_sel_hi:[0,1,1]
	s_barrier
	ds_write2st64_b32 v21, v138, v124 offset1:4
	ds_write2st64_b32 v21, v139, v125 offset0:128 offset1:132
	ds_write2st64_b32 v21, v126, v116 offset0:8 offset1:12
	ds_write2st64_b32 v21, v127, v117 offset0:136 offset1:140
	ds_write2st64_b32 v21, v118, v108 offset0:16 offset1:20
	ds_write2st64_b32 v21, v119, v109 offset0:144 offset1:148
	ds_write2st64_b32 v21, v110, v100 offset0:24 offset1:28
	ds_write2st64_b32 v21, v111, v101 offset0:152 offset1:156
	ds_write2st64_b32 v21, v102, v92 offset0:32 offset1:36
	ds_write2st64_b32 v21, v103, v93 offset0:160 offset1:164
	ds_write2st64_b32 v21, v94, v84 offset0:40 offset1:44
	ds_write2st64_b32 v21, v95, v85 offset0:168 offset1:172
	ds_write2st64_b32 v21, v86, v14 offset0:48 offset1:52
	ds_write2st64_b32 v21, v87, v15 offset0:176 offset1:180
	ds_write2st64_b32 v21, v78, v8 offset0:56 offset1:60
	ds_write2st64_b32 v21, v79, v9 offset0:184 offset1:188
	v_and_b32_e32 v8, 64, v197
	v_add_u32_e32 v8, 64, v8
	v_xor_b32_e32 v9, 1, v197
	v_cmp_lt_i32_e32 vcc, v9, v8
	v_add_u32_e32 v22, 0, v19
	v_ashrrev_i32_e32 v21, 3, v176
	v_cndmask_b32_e32 v9, v197, v9, vcc
	v_lshlrev_b32_e32 v20, 2, v9
	v_xor_b32_e32 v9, 2, v197
	v_cmp_lt_i32_e32 vcc, v9, v8
	v_and_b32_e32 v23, -8, v21
	s_waitcnt lgkmcnt(0)
	v_cndmask_b32_e32 v9, v197, v9, vcc
	v_lshlrev_b32_e32 v19, 2, v9
	v_xor_b32_e32 v9, 4, v197
	v_cmp_lt_i32_e32 vcc, v9, v8
	s_barrier
	s_lshl_b32 s0, s18, 6
	s_mov_b32 s4, 0xf800000
	s_add_u32 s2, s66, 0x1000
	s_addc_u32 s3, s67, 0
	v_lshrrev_b32_e32 v8, 6, v176
	v_lshlrev_b32_e32 v9, 4, v197
	v_lshl_add_u32 v9, v8, 13, v9
	v_lshlrev_b32_e32 v10, 3, v197
	v_lshlrev_b32_e32 v8, 3, v8
	v_add_u32_e32 v8, s0, v8
	v_mul_u32_u24_e32 v8, 0x1800, v8
	v_add_u32_e32 v10, v8, v10
	s_mov_b32 s5, 4
.Lmixc_ln_loop:
	ds_read_b128 v[32:35], v9
	ds_read_b128 v[36:39], v9 offset:1024
	s_waitcnt lgkmcnt(0)
	v_add_f32_e32 v12, v33, v32
	v_add_f32_e32 v16, v34, v35
	v_add_f32_e32 v13, v37, v36
	v_add_f32_e32 v17, v38, v39
	v_add_f32_e32 v12, v12, v16
	v_add_f32_e32 v13, v13, v17
	s_nop 1
	v_add_f32_dpp v12, v12, v12 quad_perm:[1,0,3,2] row_mask:0xf bank_mask:0xf
	v_add_f32_dpp v13, v13, v13 quad_perm:[1,0,3,2] row_mask:0xf bank_mask:0xf
	s_nop 1
	v_add_f32_dpp v12, v12, v12 quad_perm:[2,3,0,1] row_mask:0xf bank_mask:0xf
	v_add_f32_dpp v13, v13, v13 quad_perm:[2,3,0,1] row_mask:0xf bank_mask:0xf
	s_nop 1
	v_add_f32_dpp v12, v12, v12 row_half_mirror row_mask:0xf bank_mask:0xf
	v_add_f32_dpp v13, v13, v13 row_half_mirror row_mask:0xf bank_mask:0xf
	s_nop 1
	v_add_f32_dpp v12, v12, v12 row_mirror row_mask:0xf bank_mask:0xf
	v_add_f32_dpp v13, v13, v13 row_mirror row_mask:0xf bank_mask:0xf
	s_nop 1
	v_mov_b32_e32 v16, v12
	v_mov_b32_e32 v17, v13
	s_nop 1
	v_permlane16_swap_b32_e32 v12, v16
	v_permlane16_swap_b32_e32 v13, v17
	v_add_f32_e32 v12, v12, v16
	v_add_f32_e32 v13, v13, v17
	s_nop 1
	v_mov_b32_e32 v16, v12
	v_mov_b32_e32 v17, v13
	s_nop 1
	v_permlane32_swap_b32_e32 v12, v16
	v_permlane32_swap_b32_e32 v13, v17
	v_add_f32_e32 v12, v12, v16
	v_add_f32_e32 v13, v13, v17
	s_nop 1
	v_fmac_f32_e32 v32, 0xbb800000, v12
	v_fmac_f32_e32 v33, 0xbb800000, v12
	v_fmac_f32_e32 v34, 0xbb800000, v12
	v_fmac_f32_e32 v35, 0xbb800000, v12
	v_fmac_f32_e32 v36, 0xbb800000, v13
	v_fmac_f32_e32 v37, 0xbb800000, v13
	v_fmac_f32_e32 v38, 0xbb800000, v13
	v_fmac_f32_e32 v39, 0xbb800000, v13
	v_mul_f32_e32 v12, v32, v32
	v_mul_f32_e32 v16, v33, v33
	v_mul_f32_e32 v20, v34, v34
	v_mul_f32_e32 v24, v35, v35
	v_mul_f32_e32 v13, v36, v36
	v_mul_f32_e32 v17, v37, v37
	v_mul_f32_e32 v21, v38, v38
	v_mul_f32_e32 v25, v39, v39
	v_add_f32_e32 v12, v16, v12
	v_add_f32_e32 v20, v20, v24
	v_add_f32_e32 v13, v17, v13
	v_add_f32_e32 v21, v21, v25
	v_add_f32_e32 v12, v12, v20
	v_add_f32_e32 v13, v13, v21
	s_nop 1
	v_add_f32_dpp v12, v12, v12 quad_perm:[1,0,3,2] row_mask:0xf bank_mask:0xf
	v_add_f32_dpp v13, v13, v13 quad_perm:[1,0,3,2] row_mask:0xf bank_mask:0xf
	s_nop 1
	v_add_f32_dpp v12, v12, v12 quad_perm:[2,3,0,1] row_mask:0xf bank_mask:0xf
	v_add_f32_dpp v13, v13, v13 quad_perm:[2,3,0,1] row_mask:0xf bank_mask:0xf
	s_nop 1
	v_add_f32_dpp v12, v12, v12 row_half_mirror row_mask:0xf bank_mask:0xf
	v_add_f32_dpp v13, v13, v13 row_half_mirror row_mask:0xf bank_mask:0xf
	s_nop 1
	v_add_f32_dpp v12, v12, v12 row_mirror row_mask:0xf bank_mask:0xf
	v_add_f32_dpp v13, v13, v13 row_mirror row_mask:0xf bank_mask:0xf
	s_nop 1
	v_mov_b32_e32 v16, v12
	v_mov_b32_e32 v17, v13
	s_nop 1
	v_permlane16_swap_b32_e32 v12, v16
	v_permlane16_swap_b32_e32 v13, v17
	v_add_f32_e32 v12, v12, v16
	v_add_f32_e32 v13, v13, v17
	s_nop 1
	v_mov_b32_e32 v16, v12
	v_mov_b32_e32 v17, v13
	s_nop 1
	v_permlane32_swap_b32_e32 v12, v16
	v_permlane32_swap_b32_e32 v13, v17
	v_add_f32_e32 v12, v12, v16
	v_add_f32_e32 v13, v13, v17
	s_nop 1
	v_fmamk_f32 v12, v12, 0x3b800000, v194
	v_fmamk_f32 v13, v13, 0x3b800000, v194
	v_cmp_gt_f32_e32 vcc, s4, v12
	v_mul_f32_e32 v20, 0x4f800000, v12
	s_nop 0
	v_cndmask_b32_e32 v12, v12, v20, vcc
	v_sqrt_f32_e32 v20, v12
	s_nop 0
	v_add_u32_e32 v21, -1, v20
	v_fma_f32 v22, -v21, v20, v12
	v_cmp_ge_f32_e64 s[36:37], 0, v22
	v_add_u32_e32 v22, 1, v20
	s_nop 0
	v_cndmask_b32_e64 v21, v20, v21, s[36:37]
	v_fma_f32 v20, -v22, v20, v12
	v_cmp_lt_f32_e64 s[36:37], 0, v20
	s_nop 1
	v_cndmask_b32_e64 v20, v21, v22, s[36:37]
	v_mul_f32_e32 v21, 0x37800000, v20
	v_cndmask_b32_e32 v20, v20, v21, vcc
	v_cmp_class_f32_e32 vcc, v12, v196
	s_nop 1
	v_cndmask_b32_e32 v12, v20, v12, vcc
	v_div_scale_f32 v20, s[36:37], v12, v12, 1.0
	v_rcp_f32_e32 v21, v20
	s_nop 0
	v_fma_f32 v22, -v20, v21, 1.0
	v_fmac_f32_e32 v21, v22, v21
	v_div_scale_f32 v22, vcc, 1.0, v12, 1.0
	v_mul_f32_e32 v23, v22, v21
	v_fma_f32 v24, -v20, v23, v22
	v_fmac_f32_e32 v23, v24, v21
	v_fma_f32 v20, -v20, v23, v22
	v_div_fmas_f32 v20, v20, v21, v23
	v_div_fixup_f32 v12, v20, v12, 1.0
	v_cmp_gt_f32_e32 vcc, s4, v13
	v_mul_f32_e32 v20, 0x4f800000, v13
	s_nop 0
	v_cndmask_b32_e32 v13, v13, v20, vcc
	v_sqrt_f32_e32 v20, v13
	s_nop 0
	v_add_u32_e32 v21, -1, v20
	v_fma_f32 v22, -v21, v20, v13
	v_cmp_ge_f32_e64 s[36:37], 0, v22
	v_add_u32_e32 v22, 1, v20
	s_nop 0
	v_cndmask_b32_e64 v21, v20, v21, s[36:37]
	v_fma_f32 v20, -v22, v20, v13
	v_cmp_lt_f32_e64 s[36:37], 0, v20
	s_nop 1
	v_cndmask_b32_e64 v20, v21, v22, s[36:37]
	v_mul_f32_e32 v21, 0x37800000, v20
	v_cndmask_b32_e32 v20, v20, v21, vcc
	v_cmp_class_f32_e32 vcc, v13, v196
	s_nop 1
	v_cndmask_b32_e32 v13, v20, v13, vcc
	v_div_scale_f32 v20, s[36:37], v13, v13, 1.0
	v_rcp_f32_e32 v21, v20
	s_nop 0
	v_fma_f32 v22, -v20, v21, 1.0
	v_fmac_f32_e32 v21, v22, v21
	v_div_scale_f32 v22, vcc, 1.0, v13, 1.0
	v_mul_f32_e32 v23, v22, v21
	v_fma_f32 v24, -v20, v23, v22
	v_fmac_f32_e32 v23, v24, v21
	v_fma_f32 v20, -v20, v23, v22
	v_div_fmas_f32 v20, v20, v21, v23
	v_div_fixup_f32 v13, v20, v13, 1.0
	v_mul_f32_e32 v32, v32, v12
	v_mul_f32_e32 v33, v33, v12
	v_mul_f32_e32 v34, v34, v12
	v_mul_f32_e32 v35, v35, v12
	v_mul_f32_e32 v36, v36, v13
	v_mul_f32_e32 v37, v37, v13
	v_mul_f32_e32 v38, v38, v13
	v_mul_f32_e32 v39, v39, v13
	v_fma_f32 v32, v0, v32, v4
	v_fma_f32 v33, v1, v33, v5
	v_fma_f32 v34, v2, v34, v6
	v_fma_f32 v35, v3, v35, v7
	v_fma_f32 v36, v0, v36, v4
	v_fma_f32 v37, v1, v37, v5
	v_fma_f32 v38, v2, v38, v6
	v_fma_f32 v39, v3, v39, v7
	v_mul_f32_e32 v64, 0xbfb8aa3b, v32
	v_mul_f32_e32 v65, 0xbfb8aa3b, v33
	v_mul_f32_e32 v66, 0xbfb8aa3b, v34
	v_mul_f32_e32 v67, 0xbfb8aa3b, v35
	v_mul_f32_e32 v68, 0xbfb8aa3b, v36
	v_mul_f32_e32 v69, 0xbfb8aa3b, v37
	v_mul_f32_e32 v70, 0xbfb8aa3b, v38
	v_mul_f32_e32 v71, 0xbfb8aa3b, v39
	v_exp_f32_e32 v64, v64
	v_exp_f32_e32 v65, v65
	v_exp_f32_e32 v66, v66
	v_exp_f32_e32 v67, v67
	v_exp_f32_e32 v68, v68
	v_exp_f32_e32 v69, v69
	v_exp_f32_e32 v70, v70
	v_exp_f32_e32 v71, v71
	v_add_f32_e32 v64, 1.0, v64
	v_add_f32_e32 v65, 1.0, v65
	v_add_f32_e32 v66, 1.0, v66
	v_add_f32_e32 v67, 1.0, v67
	v_add_f32_e32 v68, 1.0, v68
	v_add_f32_e32 v69, 1.0, v69
	v_add_f32_e32 v70, 1.0, v70
	v_add_f32_e32 v71, 1.0, v71
	v_rcp_f32_e32 v64, v64
	v_rcp_f32_e32 v65, v65
	v_rcp_f32_e32 v66, v66
	v_rcp_f32_e32 v67, v67
	v_rcp_f32_e32 v68, v68
	v_rcp_f32_e32 v69, v69
	v_rcp_f32_e32 v70, v70
	v_rcp_f32_e32 v71, v71
	v_mul_f32_e32 v32, v32, v64
	v_mul_f32_e32 v33, v33, v65
	v_mul_f32_e32 v34, v34, v66
	v_mul_f32_e32 v35, v35, v67
	v_mul_f32_e32 v36, v36, v68
	v_mul_f32_e32 v37, v37, v69
	v_mul_f32_e32 v38, v38, v70
	v_mul_f32_e32 v39, v39, v71
	v_cvt_pk_bf16_f32 v32, v32, v33
	v_cvt_pk_bf16_f32 v33, v34, v35
	v_cvt_pk_bf16_f32 v36, v36, v37
	v_cvt_pk_bf16_f32 v37, v38, v39
	global_store_dwordx2 v10, v[32:33], s[2:3] offset:1024
	s_add_u32 s2, s2, 0x1800
	s_addc_u32 s3, s3, 0
	global_store_dwordx2 v10, v[36:37], s[2:3] offset:1024
	s_add_u32 s2, s2, 0x1800
	s_addc_u32 s3, s3, 0
	v_add_u32_e32 v9, 2048, v9
	s_sub_u32 s5, s5, 1
	s_cmp_lg_u32 s5, 0
	s_cbranch_scc1 .Lmixc_ln_loop
	s_mov_b64 s[2:3], -1
	s_barrier
